# write-through scope (sc0 sc1) on the 128 dwordx4 global stores so the grid-seam L2 write-back has less dirty data to flush
# baseline (speedup 1.0000x reference)
; __host__ __device__ __forceinline__ int blk_off(int r, int c) { const int rr = r & 127; return (r >> 7) * 8192 + (((rr >> 4) * 2 + (c >> 5)) * 512) + (rr & 15) * 32 + (c & 31); }
; __device__ __forceinline__ unsigned cvt_pk_bf16(float lo, float hi) { unsigned r; asm volatile("v_cvt_pk_bf16_f32 %0, %1, %2" : "=v"(r) : "v"(lo), "v"(hi)); return r; }
; __device__ __forceinline__ int win_row(int n) {
;     if (n >= 4096) { const int isci = n >= 5120 ? 1 : 0, ch = n - (isci ? 5120 : 4096); return (16 + (ch >> 7)) * 256 + isci * 128 + (ch & 127); }
;     const int c = n & 255; return (n & ~255) + ((c >> 5) & 1) * 128 + (c >> 6) * 32 + (c & 31); }
; __device__ __forceinline__ void titem_load(const TItem& d, f32x4 (&v)[16], float (&gg)[16], int lane) {
; #pragma unroll
;     for (int i = 0; i < 16; ++i) { const int kk = 32 * (i >> 3) + 8 * (lane >> 4) + (i & 7); v[i] = *(const f32x4*)(d.src + (size_t)kk * d.N + (lane & 15) * 4); gg[i] = d.g ? d.g[kk] : 1.f; }
; }
; __device__ __forceinline__ void titem_process(const TItem& d, const f32x4 (&v)[16], const float (&gg)[16], int lane) {
;     const int n0 = d.perm >> 1;
; #pragma unroll
;     for (int j = 0; j < 4; ++j) { const int n = n0 + 4 * (lane & 15) + j, nr = (d.perm & 1) ? win_row(n) : n;
;         const int w32 = nr & 31, nrs = (nr & 255 & ~31) + 16 * ((w32 >> 2) & 1) + 4 * (w32 >> 3) + (w32 & 3);
;         bf16* rowp = d.dst + (size_t)(nr >> 8) * (d.K >> 6) * (256 * 64);
; #pragma unroll
;         for (int h = 0; h < 2; ++h) { v4u o;
;             o.x = pg8::cvt_pk_bf16(v[8 * h + 0][j] * gg[8 * h + 0], v[8 * h + 1][j] * gg[8 * h + 1]); o.y = pg8::cvt_pk_bf16(v[8 * h + 2][j] * gg[8 * h + 2], v[8 * h + 3][j] * gg[8 * h + 3]);
;             o.z = pg8::cvt_pk_bf16(v[8 * h + 4][j] * gg[8 * h + 4], v[8 * h + 5][j] * gg[8 * h + 5]); o.w = pg8::cvt_pk_bf16(v[8 * h + 6][j] * gg[8 * h + 6], v[8 * h + 7][j] * gg[8 * h + 7]);
;             *(v4u*)(rowp + pg8::blk_off(nrs, 8 * (lane >> 4) + 32 * h)) = o; } }
; }
.LBB0_101:
	v_and_b32_e32 v188, 0x60, v130
	v_lshlrev_b32_e32 v189, 2, v130
	s_ashr_i32 s4, s3, 6
	v_and_or_b32 v194, v189, 16, v188
	v_lshrrev_b32_e32 v188, 1, v130
	v_and_b32_e32 v189, 3, v130
	v_ashrrev_i32_e32 v191, 8, v130
	s_ashr_i32 s5, s4, 31
	v_and_or_b32 v190, v188, 12, v189
	v_ashrrev_i32_e32 v188, 31, v191
	s_lshl_b64 s[36:37], s[4:5], 15
	v_lshlrev_b32_e32 v130, 6, v130
	v_mul_lo_u32 v195, s36, v188
	s_lshr_b64 s[4:5], s[4:5], 17
	v_mov_b64_e32 v[188:189], s[0:1]
	v_and_b32_e32 v130, 0x2000, v130
	v_mul_i32_i24_e32 v196, s4, v191
	v_mad_u64_u32 v[192:193], s[4:5], s36, v191, v[188:189]
	v_lshl_or_b32 v130, v190, 5, v130
	s_waitcnt vmcnt(15)
	v_mul_f32_e32 v188, v162, v2
	s_waitcnt vmcnt(14)
	v_mul_f32_e32 v189, v161, v6
	v_lshlrev_b32_e32 v194, 6, v194
	v_cvt_pk_bf16_f32 v188, v188, v189
	s_waitcnt vmcnt(13)
	v_mul_f32_e32 v189, v164, v10
	s_waitcnt vmcnt(12)
	v_mul_f32_e32 v190, v163, v14
	v_or3_b32 v130, v130, v194, v179
	v_add3_u32 v193, v196, v193, v195
	v_cvt_pk_bf16_f32 v189, v189, v190
	s_waitcnt vmcnt(11)
	v_mul_f32_e32 v190, v166, v18
	s_waitcnt vmcnt(10)
	v_mul_f32_e32 v191, v165, v22
	v_lshlrev_b32_e32 v130, 1, v130
	v_cvt_pk_bf16_f32 v190, v190, v191
	s_waitcnt vmcnt(9)
	v_mul_f32_e32 v191, v168, v26
	v_lshl_add_u64 v[192:193], v[192:193], 0, v[130:131]
	s_waitcnt vmcnt(8)
	v_mul_f32_e32 v195, v167, v30
	v_cvt_pk_bf16_f32 v191, v191, v195
	global_store_dwordx4 v[192:193], v[188:191], off sc0 sc1
	s_waitcnt vmcnt(8)
	v_mul_f32_e32 v130, v171, v34
	s_andn2_b64 vcc, exec, s[38:39]
	s_waitcnt vmcnt(7)
	v_mul_f32_e32 v188, v170, v38
	v_cvt_pk_bf16_f32 v188, v130, v188
	s_waitcnt vmcnt(6)
	v_mul_f32_e32 v130, v173, v42
	s_waitcnt vmcnt(5)
	v_mul_f32_e32 v189, v172, v46
	v_cvt_pk_bf16_f32 v189, v130, v189
	s_waitcnt vmcnt(4)
	v_mul_f32_e32 v130, v175, v50
	s_waitcnt vmcnt(3)
	v_mul_f32_e32 v190, v174, v54
	v_cvt_pk_bf16_f32 v190, v130, v190
	s_waitcnt vmcnt(2)
	v_mul_f32_e32 v130, v178, v58
	s_waitcnt vmcnt(1)
	v_mul_f32_e32 v191, v176, v62
	v_cvt_pk_bf16_f32 v191, v130, v191
	v_cndmask_b32_e64 v130, 0, 1, s[38:39]
	v_cmp_ne_u32_e64 s[4:5], 1, v130
	v_add_u32_e32 v130, 1, v187
	global_store_dwordx4 v[192:193], v[188:191], off offset:1024 sc0 sc1
	s_cbranch_vccnz .LBB0_107
	v_cmp_gt_i32_e32 vcc, s52, v187
	s_and_saveexec_b64 s[38:39], vcc
	s_xor_b64 s[38:39], exec, s[38:39]
	v_lshlrev_b32_e32 v188, 2, v130
	v_lshrrev_b32_e32 v189, 1, v130
	v_and_b32_e32 v188, 0x80, v188
	v_and_b32_e32 v189, 0x60, v189
	v_and_b32_e32 v130, 0xffffff1f, v130
	v_or3_b32 v130, v188, v130, v189
	s_andn2_saveexec_b64 s[38:39], s[38:39]
	v_cmp_lt_u32_e32 vcc, s54, v130
	s_nop 1
	v_cndmask_b32_e32 v188, v180, v181, vcc
	v_add_lshl_u32 v188, v188, v130, 1
	v_and_b32_e32 v188, 0xffffff00, v188
	v_cndmask_b32_e32 v189, 0, v182, vcc
	v_and_b32_e32 v130, 0x7f, v130
	v_or3_b32 v130, v188, v189, v130
	v_add_u32_e32 v130, 0x1000, v130
	s_or_b64 exec, exec, s[38:39]
.LBB0_107:
	s_nop 0
	v_and_b32_e32 v188, 0x60, v130
	v_lshlrev_b32_e32 v189, 2, v130
	v_and_or_b32 v194, v189, 16, v188
	v_lshrrev_b32_e32 v188, 1, v130
	v_and_b32_e32 v189, 3, v130
	v_ashrrev_i32_e32 v191, 8, v130
	v_and_or_b32 v190, v188, 12, v189
	v_ashrrev_i32_e32 v188, 31, v191
	v_lshlrev_b32_e32 v130, 6, v130
	v_mul_lo_u32 v195, s36, v188
	v_mov_b64_e32 v[188:189], s[0:1]
	v_and_b32_e32 v130, 0x2000, v130
	v_mad_u64_u32 v[192:193], s[38:39], s36, v191, v[188:189]
	v_lshl_or_b32 v130, v190, 5, v130
	v_mul_f32_e32 v188, v162, v3
	v_mul_f32_e32 v189, v161, v7
	v_lshlrev_b32_e32 v194, 6, v194
	v_mul_i32_i24_e32 v196, s37, v191
	v_cvt_pk_bf16_f32 v188, v188, v189
	v_mul_f32_e32 v189, v164, v11
	v_mul_f32_e32 v190, v163, v15
	v_or3_b32 v130, v130, v194, v179
	v_add3_u32 v193, v196, v193, v195
	v_cvt_pk_bf16_f32 v189, v189, v190
	v_mul_f32_e32 v190, v166, v19
	v_mul_f32_e32 v191, v165, v23
	v_lshlrev_b32_e32 v130, 1, v130
	v_cvt_pk_bf16_f32 v190, v190, v191
	v_mul_f32_e32 v191, v168, v27
	v_lshl_add_u64 v[192:193], v[192:193], 0, v[130:131]
	v_mul_f32_e32 v195, v167, v31
	v_cvt_pk_bf16_f32 v191, v191, v195
	global_store_dwordx4 v[192:193], v[188:191], off sc0 sc1
	v_mul_f32_e32 v130, v171, v35
	s_and_b64 vcc, exec, s[4:5]
	v_mul_f32_e32 v188, v170, v39
	v_cvt_pk_bf16_f32 v188, v130, v188
	v_mul_f32_e32 v130, v173, v43
	v_mul_f32_e32 v189, v172, v47
	v_cvt_pk_bf16_f32 v189, v130, v189
	v_mul_f32_e32 v130, v175, v51
	v_mul_f32_e32 v190, v174, v55
	v_cvt_pk_bf16_f32 v190, v130, v190
	v_mul_f32_e32 v130, v178, v59
	v_mul_f32_e32 v191, v176, v63
	v_cvt_pk_bf16_f32 v191, v130, v191
	v_add_u32_e32 v130, 2, v187
	global_store_dwordx4 v[192:193], v[188:191], off offset:1024 sc0 sc1
	s_cbranch_vccnz .LBB0_113
	v_cmp_gt_i32_e32 vcc, s55, v187
	s_and_saveexec_b64 s[38:39], vcc
	s_xor_b64 s[38:39], exec, s[38:39]
	v_lshlrev_b32_e32 v188, 2, v130
	v_lshrrev_b32_e32 v189, 1, v130
	v_and_b32_e32 v188, 0x80, v188
	v_and_b32_e32 v189, 0x60, v189
	v_and_b32_e32 v130, 0xffffff1f, v130
	v_or3_b32 v130, v188, v130, v189
	s_andn2_saveexec_b64 s[38:39], s[38:39]
	v_cmp_lt_u32_e32 vcc, s54, v130
	s_nop 1
	v_cndmask_b32_e32 v188, v180, v181, vcc
	v_add_lshl_u32 v188, v188, v130, 1
	v_and_b32_e32 v188, 0xffffff00, v188
	v_cndmask_b32_e32 v189, 0, v182, vcc
	v_and_b32_e32 v130, 0x7f, v130
	v_or3_b32 v130, v188, v189, v130
	v_add_u32_e32 v130, 0x1000, v130
	s_or_b64 exec, exec, s[38:39]
; __host__ __device__ __forceinline__ int blk_off(int r, int c) { const int rr = r & 127; return (r >> 7) * 8192 + (((rr >> 4) * 2 + (c >> 5)) * 512) + (rr & 15) * 32 + (c & 31); }
; __device__ __forceinline__ unsigned cvt_pk_bf16(float lo, float hi) { unsigned r; asm volatile("v_cvt_pk_bf16_f32 %0, %1, %2" : "=v"(r) : "v"(lo), "v"(hi)); return r; }
; __device__ __forceinline__ void titem_process(const TItem& d, const f32x4 (&v)[16], const float (&gg)[16], int lane) {
;     const int n0 = d.perm >> 1;
; #pragma unroll
;     for (int j = 0; j < 4; ++j) { const int n = n0 + 4 * (lane & 15) + j, nr = (d.perm & 1) ? win_row(n) : n;
;         const int w32 = nr & 31, nrs = (nr & 255 & ~31) + 16 * ((w32 >> 2) & 1) + 4 * (w32 >> 3) + (w32 & 3);
;         bf16* rowp = d.dst + (size_t)(nr >> 8) * (d.K >> 6) * (256 * 64);
; #pragma unroll
;         for (int h = 0; h < 2; ++h) { v4u o;
;             o.x = pg8::cvt_pk_bf16(v[8 * h + 0][j] * gg[8 * h + 0], v[8 * h + 1][j] * gg[8 * h + 1]); o.y = pg8::cvt_pk_bf16(v[8 * h + 2][j] * gg[8 * h + 2], v[8 * h + 3][j] * gg[8 * h + 3]);
;             o.z = pg8::cvt_pk_bf16(v[8 * h + 4][j] * gg[8 * h + 4], v[8 * h + 5][j] * gg[8 * h + 5]); o.w = pg8::cvt_pk_bf16(v[8 * h + 6][j] * gg[8 * h + 6], v[8 * h + 7][j] * gg[8 * h + 7]);
;             *(v4u*)(rowp + pg8::blk_off(nrs, 8 * (lane >> 4) + 32 * h)) = o; } }
; }
; __global__ void __launch_bounds__(NWAVES * 64, 2) hybrid_fwd(Args args) {
;     ...
;             while (it < DEPTH * I_L) {
;                 const int itn = it + NGW; f32x4 vb[16]; float gb[16]; TItem d1;
;                 if (itn < DEPTH * I_L) { d1 = decode(itn); titem_load(d1, vb, gb, lane); }
;                 titem_process(d0, va, ga, lane);
;                 if (itn < DEPTH * I_L) {
; #pragma unroll
;                     for (int i = 0; i < 16; ++i) { va[i] = vb[i]; ga[i] = gb[i]; }
;                     d0 = d1; }
;                 it = itn;
;             }
.LBB0_113:
	s_nop 0
	v_and_b32_e32 v188, 0x60, v130
	v_lshlrev_b32_e32 v189, 2, v130
	v_and_or_b32 v194, v189, 16, v188
	v_lshrrev_b32_e32 v188, 1, v130
	v_and_b32_e32 v189, 3, v130
	v_ashrrev_i32_e32 v191, 8, v130
	v_and_or_b32 v190, v188, 12, v189
	v_ashrrev_i32_e32 v188, 31, v191
	v_lshlrev_b32_e32 v130, 6, v130
	v_mul_lo_u32 v195, s36, v188
	v_mov_b64_e32 v[188:189], s[0:1]
	v_and_b32_e32 v130, 0x2000, v130
	v_mad_u64_u32 v[192:193], s[38:39], s36, v191, v[188:189]
	v_lshl_or_b32 v130, v190, 5, v130
	v_mul_f32_e32 v188, v162, v4
	v_mul_f32_e32 v189, v161, v8
	v_lshlrev_b32_e32 v194, 6, v194
	v_mul_i32_i24_e32 v196, s37, v191
	v_cvt_pk_bf16_f32 v188, v188, v189
	v_mul_f32_e32 v189, v164, v12
	v_mul_f32_e32 v190, v163, v16
	v_or3_b32 v130, v130, v194, v179
	v_add3_u32 v193, v196, v193, v195
	v_cvt_pk_bf16_f32 v189, v189, v190
	v_mul_f32_e32 v190, v166, v20
	v_mul_f32_e32 v191, v165, v24
	v_lshlrev_b32_e32 v130, 1, v130
	v_cvt_pk_bf16_f32 v190, v190, v191
	v_mul_f32_e32 v191, v168, v28
	v_lshl_add_u64 v[192:193], v[192:193], 0, v[130:131]
	v_mul_f32_e32 v195, v167, v32
	v_cvt_pk_bf16_f32 v191, v191, v195
	global_store_dwordx4 v[192:193], v[188:191], off sc0 sc1
	v_mul_f32_e32 v130, v171, v36
	s_and_b64 vcc, exec, s[4:5]
	v_mul_f32_e32 v188, v170, v40
	v_cvt_pk_bf16_f32 v188, v130, v188
	v_mul_f32_e32 v130, v173, v44
	v_mul_f32_e32 v189, v172, v48
	v_cvt_pk_bf16_f32 v189, v130, v189
	v_mul_f32_e32 v130, v175, v52
	v_mul_f32_e32 v190, v174, v56
	v_cvt_pk_bf16_f32 v190, v130, v190
	v_mul_f32_e32 v130, v178, v60
	v_mul_f32_e32 v191, v176, v64
	v_cvt_pk_bf16_f32 v191, v130, v191
	v_add_u32_e32 v130, 3, v187
	global_store_dwordx4 v[192:193], v[188:191], off offset:1024 sc0 sc1
	s_cbranch_vccnz .LBB0_119
	v_cmp_gt_i32_e32 vcc, s56, v187
	s_and_saveexec_b64 s[4:5], vcc
	s_xor_b64 s[4:5], exec, s[4:5]
	v_lshlrev_b32_e32 v187, 2, v130
	v_lshrrev_b32_e32 v188, 1, v130
	v_and_b32_e32 v187, 0x80, v187
	v_and_b32_e32 v188, 0x60, v188
	v_and_b32_e32 v130, 0xffffff1f, v130
	v_or3_b32 v130, v187, v130, v188
	s_andn2_saveexec_b64 s[4:5], s[4:5]
	v_cmp_lt_u32_e32 vcc, s54, v130
	s_nop 1
	v_cndmask_b32_e32 v187, v180, v181, vcc
	v_add_lshl_u32 v187, v187, v130, 1
	v_and_b32_e32 v187, 0xffffff00, v187
	v_cndmask_b32_e32 v188, 0, v182, vcc
	v_and_b32_e32 v130, 0x7f, v130
	v_or3_b32 v130, v187, v188, v130
	v_add_u32_e32 v130, 0x1000, v130
	s_or_b64 exec, exec, s[4:5]
.LBB0_119:
	v_and_b32_e32 v187, 0x60, v130
	v_lshlrev_b32_e32 v188, 2, v130
	v_and_or_b32 v187, v188, 16, v187
	v_lshrrev_b32_e32 v188, 1, v130
	v_and_b32_e32 v189, 3, v130
	v_ashrrev_i32_e32 v191, 8, v130
	v_and_or_b32 v190, v188, 12, v189
	v_ashrrev_i32_e32 v188, 31, v191
	v_lshlrev_b32_e32 v130, 6, v130
	v_mul_lo_u32 v194, s36, v188
	v_mov_b64_e32 v[188:189], s[0:1]
	v_and_b32_e32 v130, 0x2000, v130
	v_mad_u64_u32 v[192:193], s[4:5], s36, v191, v[188:189]
	v_lshl_or_b32 v130, v190, 5, v130
	v_mul_f32_e32 v188, v162, v5
	v_mul_f32_e32 v189, v161, v9
	v_lshlrev_b32_e32 v187, 6, v187
	v_mul_i32_i24_e32 v195, s37, v191
	v_cvt_pk_bf16_f32 v188, v188, v189
	v_mul_f32_e32 v189, v164, v13
	v_mul_f32_e32 v190, v163, v17
	v_or3_b32 v130, v130, v187, v179
	v_add3_u32 v193, v195, v193, v194
	v_cvt_pk_bf16_f32 v189, v189, v190
	v_mul_f32_e32 v190, v166, v21
	v_mul_f32_e32 v191, v165, v25
	v_lshlrev_b32_e32 v130, 1, v130
	v_cvt_pk_bf16_f32 v190, v190, v191
	v_mul_f32_e32 v191, v168, v29
	v_lshl_add_u64 v[192:193], v[192:193], 0, v[130:131]
	v_mul_f32_e32 v130, v171, v37
	v_mul_f32_e32 v187, v170, v41
	v_mul_f32_e32 v194, v167, v33
	v_cvt_pk_bf16_f32 v191, v191, v194
	global_store_dwordx4 v[192:193], v[188:191], off sc0 sc1
	s_andn2_b64 vcc, exec, s[30:31]
	s_nop 0
	v_cvt_pk_bf16_f32 v188, v130, v187
	v_mul_f32_e32 v130, v173, v45
	v_mul_f32_e32 v187, v172, v49
	v_cvt_pk_bf16_f32 v189, v130, v187
	v_mul_f32_e32 v130, v175, v53
	v_mul_f32_e32 v187, v174, v57
	v_cvt_pk_bf16_f32 v190, v130, v187
	v_mul_f32_e32 v130, v178, v61
	v_mul_f32_e32 v187, v176, v65
	v_cvt_pk_bf16_f32 v191, v130, v187
	global_store_dwordx4 v[192:193], v[188:191], off offset:1024 sc0 sc1
	s_cbranch_vccnz .LBB0_57
	v_mov_b64_e32 v[62:63], v[126:127]
	v_mov_b64_e32 v[58:59], v[118:119]
	v_mov_b64_e32 v[54:55], v[122:123]
	v_mov_b64_e32 v[50:51], v[110:111]
	v_mov_b64_e32 v[46:47], v[114:115]
	v_mov_b64_e32 v[42:43], v[102:103]
	v_mov_b64_e32 v[38:39], v[106:107]
	v_mov_b64_e32 v[34:35], v[94:95]
	v_mov_b64_e32 v[30:31], v[98:99]
	v_mov_b64_e32 v[26:27], v[86:87]
	v_mov_b64_e32 v[22:23], v[90:91]
	v_mov_b64_e32 v[18:19], v[78:79]
	v_mov_b64_e32 v[14:15], v[82:83]
	v_mov_b64_e32 v[10:11], v[70:71]
	v_mov_b64_e32 v[6:7], v[74:75]
	v_mov_b64_e32 v[2:3], v[66:67]
	v_mov_b64_e32 v[64:65], v[128:129]
	v_mov_b64_e32 v[60:61], v[120:121]
	v_mov_b64_e32 v[56:57], v[124:125]
	v_mov_b64_e32 v[52:53], v[112:113]
	v_mov_b64_e32 v[48:49], v[116:117]
	v_mov_b64_e32 v[44:45], v[104:105]
	v_mov_b64_e32 v[40:41], v[108:109]
	v_mov_b64_e32 v[36:37], v[96:97]
	v_mov_b64_e32 v[32:33], v[100:101]
	v_mov_b64_e32 v[28:29], v[88:89]
	v_mov_b64_e32 v[24:25], v[92:93]
	v_mov_b64_e32 v[20:21], v[80:81]
	v_mov_b64_e32 v[16:17], v[84:85]
	v_mov_b64_e32 v[12:13], v[72:73]
	v_mov_b64_e32 v[8:9], v[76:77]
	v_mov_b64_e32 v[4:5], v[68:69]
	s_mov_b64 s[0:1], s[34:35]
	s_mov_b32 s3, s58
	s_mov_b32 s23, s40
	v_mov_b32_e32 v162, v132
	v_mov_b32_e32 v161, v133
	v_mov_b32_e32 v164, v134
	v_mov_b32_e32 v163, v135
	v_mov_b32_e32 v166, v136
	v_mov_b32_e32 v165, v137
	v_mov_b32_e32 v168, v183
	v_mov_b32_e32 v167, v184
	v_mov_b32_e32 v171, v138
	v_mov_b32_e32 v170, v139
	v_mov_b32_e32 v173, v140
	v_mov_b32_e32 v172, v141
	v_mov_b32_e32 v175, v142
	v_mov_b32_e32 v174, v143
	v_mov_b32_e32 v178, v185
	v_mov_b32_e32 v176, v186
	s_branch .LBB0_57

; __device__ __forceinline__ unsigned cvt_pk_bf16(float lo, float hi) { unsigned r; asm volatile("v_cvt_pk_bf16_f32 %0, %1, %2" : "=v"(r) : "v"(lo), "v"(hi)); return r; }
;     __device__ __forceinline__ void operator()(const f32x4 (&acc)[2][2][4][2], const State& st, const Unit& u, int wr, int wc, int fr, int fq) const {
;     ...
;                 if (u.pn >= 16) {
;                     const f32x4 q0 = v[0][0] * v[1][0], q1 = v[0][1] * v[1][1];
;                     u32x4 w; w.x = cvt_pk_bf16(q0[0], q0[1]); w.y = cvt_pk_bf16(q0[2], q0[3]); w.z = cvt_pk_bf16(q1[0], q1[1]); w.w = cvt_pk_bf16(q1[2], q1[3]);
;                     *(u32x4*)(O + (size_t)row * ldc + 4096 + (u.pn - 16) * 128 + wc * 32 + 8 * fq) = w;
;                 } else {
;                 bf16_t* rowp = O + (size_t)row * ldc + col0;
; #pragma unroll
;                 for (int bj = 0; bj < 2; ++bj) { u32x4 w; w.x = cvt_pk_bf16(v[bj][0][0], v[bj][0][1]); w.y = cvt_pk_bf16(v[bj][0][2], v[bj][0][3]); w.z = cvt_pk_bf16(v[bj][1][0], v[bj][1][1]); w.w = cvt_pk_bf16(v[bj][1][2], v[bj][1][3]);
;                     *(u32x4*)(rowp + 32 * bj) = w; } } }
.LBB0_187:
	s_cmp_lt_i32 s79, 16
	v_lshl_or_b32 v128, s79, 8, v198
	s_cselect_b64 s[0:1], -1, 0
	v_lshl_add_u32 v200, s14, 8, v161
	v_ashrrev_i32_e32 v129, 31, v128
	s_mov_b64 s[6:7], -1
	s_and_b64 vcc, exec, s[0:1]
	s_cbranch_vccz .LBB0_189
	v_mov_b64_e32 v[202:203], s[18:19]
	v_mad_i64_i32 v[202:203], s[6:7], v200, s70, v[202:203]
	v_lshl_add_u64 v[206:207], v[128:129], 1, v[202:203]
	v_cvt_pk_bf16_f32 v202, v140, v141
	v_cvt_pk_bf16_f32 v203, v142, v143
	v_cvt_pk_bf16_f32 v204, v136, v137
	v_cvt_pk_bf16_f32 v205, v138, v139
	global_store_dwordx4 v[206:207], v[202:205], off sc0 sc1
	s_mov_b64 s[6:7], 0
	s_nop 0
	v_cvt_pk_bf16_f32 v202, v132, v133
	v_cvt_pk_bf16_f32 v203, v134, v135
	v_cvt_pk_bf16_f32 v204, v184, v185
	v_cvt_pk_bf16_f32 v205, v130, v131
	global_store_dwordx4 v[206:207], v[202:205], off offset:64 sc0 sc1
.LBB0_189:
	s_andn2_b64 vcc, exec, s[6:7]
	v_lshlrev_b32_e32 v144, 1, v160
	s_cbranch_vccnz .LBB0_191
	v_pk_mul_f32 v[134:135], v[134:135], v[142:143]
	v_pk_mul_f32 v[132:133], v[132:133], v[140:141]
	v_pk_mul_f32 v[138:139], v[130:131], v[138:139]
	v_cvt_pk_bf16_f32 v130, v132, v133
	v_cvt_pk_bf16_f32 v131, v134, v135
	v_mov_b64_e32 v[134:135], s[18:19]
	v_mad_i64_i32 v[134:135], s[6:7], v200, s70, v[134:135]
	s_lshl_b32 s14, s79, 8
	v_lshl_add_u64 v[134:135], v[134:135], 0, s[14:15]
	s_lshl_b32 s14, s71, 1
	v_lshl_add_u64 v[134:135], v[134:135], 0, s[14:15]
	v_lshl_add_u64 v[134:135], v[134:135], 0, v[144:145]
	v_add_co_u32_e32 v134, vcc, 0x1000, v134
	v_pk_mul_f32 v[136:137], v[184:185], v[136:137]
	s_nop 0
	v_addc_co_u32_e32 v135, vcc, 0, v135, vcc
	v_cvt_pk_bf16_f32 v132, v136, v137
	v_cvt_pk_bf16_f32 v133, v138, v139
	global_store_dwordx4 v[134:135], v[130:133], off sc0 sc1

; __device__ __forceinline__ unsigned cvt_pk_bf16(float lo, float hi) { unsigned r; asm volatile("v_cvt_pk_bf16_f32 %0, %1, %2" : "=v"(r) : "v"(lo), "v"(hi)); return r; }
;     __device__ __forceinline__ void operator()(const f32x4 (&acc)[2][2][4][2], const State& st, const Unit& u, int wr, int wc, int fr, int fq) const {
;     ...
;                 if (u.pn >= 16) {
;                     const f32x4 q0 = v[0][0] * v[1][0], q1 = v[0][1] * v[1][1];
;                     u32x4 w; w.x = cvt_pk_bf16(q0[0], q0[1]); w.y = cvt_pk_bf16(q0[2], q0[3]); w.z = cvt_pk_bf16(q1[0], q1[1]); w.w = cvt_pk_bf16(q1[2], q1[3]);
;                     *(u32x4*)(O + (size_t)row * ldc + 4096 + (u.pn - 16) * 128 + wc * 32 + 8 * fq) = w;
;                 } else {
;                 bf16_t* rowp = O + (size_t)row * ldc + col0;
; #pragma unroll
;                 for (int bj = 0; bj < 2; ++bj) { u32x4 w; w.x = cvt_pk_bf16(v[bj][0][0], v[bj][0][1]); w.y = cvt_pk_bf16(v[bj][0][2], v[bj][0][3]); w.z = cvt_pk_bf16(v[bj][1][0], v[bj][1][1]); w.w = cvt_pk_bf16(v[bj][1][2], v[bj][1][3]);
;                     *(u32x4*)(rowp + 32 * bj) = w; } } }
.LBB0_193:
	v_cndmask_b32_e64 v131, 0, 1, s[0:1]
	v_or_b32_e32 v130, 16, v200
	v_cmp_ne_u32_e64 s[42:43], 1, v131
	s_andn2_b64 vcc, exec, s[0:1]
	s_mov_b64 s[0:1], -1
	s_cbranch_vccnz .LBB0_195
	v_mov_b64_e32 v[132:133], s[18:19]
	v_mad_i64_i32 v[132:133], s[0:1], v130, s70, v[132:133]
	v_lshl_add_u64 v[136:137], v[128:129], 1, v[132:133]
	v_cvt_pk_bf16_f32 v132, v124, v125
	v_cvt_pk_bf16_f32 v133, v126, v127
	v_cvt_pk_bf16_f32 v134, v120, v121
	v_cvt_pk_bf16_f32 v135, v122, v123
	s_mov_b64 s[0:1], 0
	global_store_dwordx4 v[136:137], v[132:135], off sc0 sc1
	s_nop 1
	v_cvt_pk_bf16_f32 v132, v116, v117
	v_cvt_pk_bf16_f32 v133, v118, v119
	v_cvt_pk_bf16_f32 v134, v112, v113
	v_cvt_pk_bf16_f32 v135, v114, v115
	global_store_dwordx4 v[136:137], v[132:135], off offset:64 sc0 sc1
.LBB0_195:
	s_andn2_b64 vcc, exec, s[0:1]
	s_cbranch_vccnz .LBB0_197
	v_pk_mul_f32 v[116:117], v[116:117], v[124:125]
	v_pk_mul_f32 v[122:123], v[114:115], v[122:123]
	v_pk_mul_f32 v[114:115], v[112:113], v[120:121]
	v_cvt_pk_bf16_f32 v112, v116, v117
	v_mov_b64_e32 v[116:117], s[18:19]
	v_mad_i64_i32 v[116:117], s[0:1], v130, s70, v[116:117]
	s_lshl_b32 s14, s79, 8
	v_lshl_add_u64 v[116:117], v[116:117], 0, s[14:15]
	s_lshl_b32 s14, s71, 1
	v_lshl_add_u64 v[116:117], v[116:117], 0, s[14:15]
	v_lshl_add_u64 v[116:117], v[116:117], 0, v[144:145]
	v_add_co_u32_e32 v116, vcc, 0x1000, v116
	v_pk_mul_f32 v[118:119], v[118:119], v[126:127]
	s_nop 0
	v_addc_co_u32_e32 v117, vcc, 0, v117, vcc
	v_cvt_pk_bf16_f32 v113, v118, v119
	v_cvt_pk_bf16_f32 v114, v114, v115
	v_cvt_pk_bf16_f32 v115, v122, v123
	global_store_dwordx4 v[116:117], v[112:115], off sc0 sc1

; __device__ __forceinline__ unsigned cvt_pk_bf16(float lo, float hi) { unsigned r; asm volatile("v_cvt_pk_bf16_f32 %0, %1, %2" : "=v"(r) : "v"(lo), "v"(hi)); return r; }
;     __device__ __forceinline__ void operator()(const f32x4 (&acc)[2][2][4][2], const State& st, const Unit& u, int wr, int wc, int fr, int fq) const {
;     ...
;                 if (u.pn >= 16) {
;                     const f32x4 q0 = v[0][0] * v[1][0], q1 = v[0][1] * v[1][1];
;                     u32x4 w; w.x = cvt_pk_bf16(q0[0], q0[1]); w.y = cvt_pk_bf16(q0[2], q0[3]); w.z = cvt_pk_bf16(q1[0], q1[1]); w.w = cvt_pk_bf16(q1[2], q1[3]);
;                     *(u32x4*)(O + (size_t)row * ldc + 4096 + (u.pn - 16) * 128 + wc * 32 + 8 * fq) = w;
;                 } else {
;                 bf16_t* rowp = O + (size_t)row * ldc + col0;
; #pragma unroll
;                 for (int bj = 0; bj < 2; ++bj) { u32x4 w; w.x = cvt_pk_bf16(v[bj][0][0], v[bj][0][1]); w.y = cvt_pk_bf16(v[bj][0][2], v[bj][0][3]); w.z = cvt_pk_bf16(v[bj][1][0], v[bj][1][1]); w.w = cvt_pk_bf16(v[bj][1][2], v[bj][1][3]);
;                     *(u32x4*)(rowp + 32 * bj) = w; } } }
.LBB0_200:
	v_pk_mul_f32 v[100:101], v[100:101], v[108:109]
	v_pk_mul_f32 v[106:107], v[98:99], v[106:107]
	v_pk_mul_f32 v[98:99], v[96:97], v[104:105]
	v_cvt_pk_bf16_f32 v96, v100, v101
	v_mov_b64_e32 v[100:101], s[18:19]
	v_mad_i64_i32 v[100:101], s[0:1], v112, s70, v[100:101]
	s_lshl_b32 s14, s79, 8
	v_lshl_add_u64 v[100:101], v[100:101], 0, s[14:15]
	s_lshl_b32 s14, s71, 1
	v_lshl_add_u64 v[100:101], v[100:101], 0, s[14:15]
	v_lshl_add_u64 v[100:101], v[100:101], 0, v[144:145]
	v_add_co_u32_e32 v100, vcc, 0x1000, v100
	v_pk_mul_f32 v[102:103], v[102:103], v[110:111]
	s_nop 0
	v_addc_co_u32_e32 v101, vcc, 0, v101, vcc
	v_cvt_pk_bf16_f32 v97, v102, v103
	v_cvt_pk_bf16_f32 v98, v98, v99
	v_cvt_pk_bf16_f32 v99, v106, v107
	global_store_dwordx4 v[100:101], v[96:99], off sc0 sc1

; __device__ __forceinline__ unsigned cvt_pk_bf16(float lo, float hi) { unsigned r; asm volatile("v_cvt_pk_bf16_f32 %0, %1, %2" : "=v"(r) : "v"(lo), "v"(hi)); return r; }
;     __device__ __forceinline__ void operator()(const f32x4 (&acc)[2][2][4][2], const State& st, const Unit& u, int wr, int wc, int fr, int fq) const {
;     ...
;                 if (u.pn >= 16) {
;                     const f32x4 q0 = v[0][0] * v[1][0], q1 = v[0][1] * v[1][1];
;                     u32x4 w; w.x = cvt_pk_bf16(q0[0], q0[1]); w.y = cvt_pk_bf16(q0[2], q0[3]); w.z = cvt_pk_bf16(q1[0], q1[1]); w.w = cvt_pk_bf16(q1[2], q1[3]);
;                     *(u32x4*)(O + (size_t)row * ldc + 4096 + (u.pn - 16) * 128 + wc * 32 + 8 * fq) = w;
;                 } else {
;                 bf16_t* rowp = O + (size_t)row * ldc + col0;
; #pragma unroll
;                 for (int bj = 0; bj < 2; ++bj) { u32x4 w; w.x = cvt_pk_bf16(v[bj][0][0], v[bj][0][1]); w.y = cvt_pk_bf16(v[bj][0][2], v[bj][0][3]); w.z = cvt_pk_bf16(v[bj][1][0], v[bj][1][1]); w.w = cvt_pk_bf16(v[bj][1][2], v[bj][1][3]);
;                     *(u32x4*)(rowp + 32 * bj) = w; } } }
.LBB0_204:
	v_pk_mul_f32 v[84:85], v[84:85], v[92:93]
	v_pk_mul_f32 v[90:91], v[82:83], v[90:91]
	v_pk_mul_f32 v[82:83], v[80:81], v[88:89]
	v_cvt_pk_bf16_f32 v80, v84, v85
	v_mov_b64_e32 v[84:85], s[18:19]
	v_mad_i64_i32 v[84:85], s[0:1], v96, s70, v[84:85]
	s_lshl_b32 s14, s79, 8
	v_lshl_add_u64 v[84:85], v[84:85], 0, s[14:15]
	s_lshl_b32 s14, s71, 1
	v_lshl_add_u64 v[84:85], v[84:85], 0, s[14:15]
	v_lshl_add_u64 v[84:85], v[84:85], 0, v[144:145]
	v_add_co_u32_e32 v84, vcc, 0x1000, v84
	v_pk_mul_f32 v[86:87], v[86:87], v[94:95]
	s_nop 0
	v_addc_co_u32_e32 v85, vcc, 0, v85, vcc
	v_cvt_pk_bf16_f32 v81, v86, v87
	v_cvt_pk_bf16_f32 v82, v82, v83
	v_cvt_pk_bf16_f32 v83, v90, v91
	global_store_dwordx4 v[84:85], v[80:83], off sc0 sc1

; __device__ __forceinline__ unsigned cvt_pk_bf16(float lo, float hi) { unsigned r; asm volatile("v_cvt_pk_bf16_f32 %0, %1, %2" : "=v"(r) : "v"(lo), "v"(hi)); return r; }
;     __device__ __forceinline__ void operator()(const f32x4 (&acc)[2][2][4][2], const State& st, const Unit& u, int wr, int wc, int fr, int fq) const {
;     ...
;                 if (u.pn >= 16) {
;                     const f32x4 q0 = v[0][0] * v[1][0], q1 = v[0][1] * v[1][1];
;                     u32x4 w; w.x = cvt_pk_bf16(q0[0], q0[1]); w.y = cvt_pk_bf16(q0[2], q0[3]); w.z = cvt_pk_bf16(q1[0], q1[1]); w.w = cvt_pk_bf16(q1[2], q1[3]);
;                     *(u32x4*)(O + (size_t)row * ldc + 4096 + (u.pn - 16) * 128 + wc * 32 + 8 * fq) = w;
;                 } else {
;                 bf16_t* rowp = O + (size_t)row * ldc + col0;
; #pragma unroll
;                 for (int bj = 0; bj < 2; ++bj) { u32x4 w; w.x = cvt_pk_bf16(v[bj][0][0], v[bj][0][1]); w.y = cvt_pk_bf16(v[bj][0][2], v[bj][0][3]); w.z = cvt_pk_bf16(v[bj][1][0], v[bj][1][1]); w.w = cvt_pk_bf16(v[bj][1][2], v[bj][1][3]);
;                     *(u32x4*)(rowp + 32 * bj) = w; } } }
.LBB0_208:
	v_pk_mul_f32 v[68:69], v[68:69], v[76:77]
	v_pk_mul_f32 v[74:75], v[66:67], v[74:75]
	v_pk_mul_f32 v[66:67], v[64:65], v[72:73]
	v_cvt_pk_bf16_f32 v64, v68, v69
	v_mov_b64_e32 v[68:69], s[18:19]
	v_mad_i64_i32 v[68:69], s[0:1], v80, s70, v[68:69]
	s_lshl_b32 s14, s79, 8
	v_lshl_add_u64 v[68:69], v[68:69], 0, s[14:15]
	s_lshl_b32 s14, s71, 1
	v_lshl_add_u64 v[68:69], v[68:69], 0, s[14:15]
	v_lshl_add_u64 v[68:69], v[68:69], 0, v[144:145]
	v_add_co_u32_e32 v68, vcc, 0x1000, v68
	v_pk_mul_f32 v[70:71], v[70:71], v[78:79]
	s_nop 0
	v_addc_co_u32_e32 v69, vcc, 0, v69, vcc
	v_cvt_pk_bf16_f32 v65, v70, v71
	v_cvt_pk_bf16_f32 v66, v66, v67
	v_cvt_pk_bf16_f32 v67, v74, v75
	global_store_dwordx4 v[68:69], v[64:67], off sc0 sc1

; __device__ __forceinline__ unsigned cvt_pk_bf16(float lo, float hi) { unsigned r; asm volatile("v_cvt_pk_bf16_f32 %0, %1, %2" : "=v"(r) : "v"(lo), "v"(hi)); return r; }
;     __device__ __forceinline__ void operator()(const f32x4 (&acc)[2][2][4][2], const State& st, const Unit& u, int wr, int wc, int fr, int fq) const {
;     ...
;                 if (u.pn >= 16) {
;                     const f32x4 q0 = v[0][0] * v[1][0], q1 = v[0][1] * v[1][1];
;                     u32x4 w; w.x = cvt_pk_bf16(q0[0], q0[1]); w.y = cvt_pk_bf16(q0[2], q0[3]); w.z = cvt_pk_bf16(q1[0], q1[1]); w.w = cvt_pk_bf16(q1[2], q1[3]);
;                     *(u32x4*)(O + (size_t)row * ldc + 4096 + (u.pn - 16) * 128 + wc * 32 + 8 * fq) = w;
;                 } else {
;                 bf16_t* rowp = O + (size_t)row * ldc + col0;
; #pragma unroll
;                 for (int bj = 0; bj < 2; ++bj) { u32x4 w; w.x = cvt_pk_bf16(v[bj][0][0], v[bj][0][1]); w.y = cvt_pk_bf16(v[bj][0][2], v[bj][0][3]); w.z = cvt_pk_bf16(v[bj][1][0], v[bj][1][1]); w.w = cvt_pk_bf16(v[bj][1][2], v[bj][1][3]);
;                     *(u32x4*)(rowp + 32 * bj) = w; } } }
.LBB0_212:
	v_pk_mul_f32 v[36:37], v[36:37], v[44:45]
	v_pk_mul_f32 v[42:43], v[34:35], v[42:43]
	v_pk_mul_f32 v[34:35], v[32:33], v[40:41]
	v_cvt_pk_bf16_f32 v32, v36, v37
	v_mov_b64_e32 v[36:37], s[18:19]
	v_mad_i64_i32 v[36:37], s[0:1], v64, s70, v[36:37]
	s_lshl_b32 s14, s79, 8
	v_lshl_add_u64 v[36:37], v[36:37], 0, s[14:15]
	s_lshl_b32 s14, s71, 1
	v_lshl_add_u64 v[36:37], v[36:37], 0, s[14:15]
	v_lshl_add_u64 v[36:37], v[36:37], 0, v[144:145]
	v_add_co_u32_e32 v36, vcc, 0x1000, v36
	v_pk_mul_f32 v[38:39], v[38:39], v[46:47]
	s_nop 0
	v_addc_co_u32_e32 v37, vcc, 0, v37, vcc
	v_cvt_pk_bf16_f32 v33, v38, v39
	v_cvt_pk_bf16_f32 v34, v34, v35
	v_cvt_pk_bf16_f32 v35, v42, v43
	global_store_dwordx4 v[36:37], v[32:35], off sc0 sc1

; __device__ __forceinline__ unsigned cvt_pk_bf16(float lo, float hi) { unsigned r; asm volatile("v_cvt_pk_bf16_f32 %0, %1, %2" : "=v"(r) : "v"(lo), "v"(hi)); return r; }
;     __device__ __forceinline__ void operator()(const f32x4 (&acc)[2][2][4][2], const State& st, const Unit& u, int wr, int wc, int fr, int fq) const {
;     ...
;                 if (u.pn >= 16) {
;                     const f32x4 q0 = v[0][0] * v[1][0], q1 = v[0][1] * v[1][1];
;                     u32x4 w; w.x = cvt_pk_bf16(q0[0], q0[1]); w.y = cvt_pk_bf16(q0[2], q0[3]); w.z = cvt_pk_bf16(q1[0], q1[1]); w.w = cvt_pk_bf16(q1[2], q1[3]);
;                     *(u32x4*)(O + (size_t)row * ldc + 4096 + (u.pn - 16) * 128 + wc * 32 + 8 * fq) = w;
;                 } else {
;                 bf16_t* rowp = O + (size_t)row * ldc + col0;
; #pragma unroll
;                 for (int bj = 0; bj < 2; ++bj) { u32x4 w; w.x = cvt_pk_bf16(v[bj][0][0], v[bj][0][1]); w.y = cvt_pk_bf16(v[bj][0][2], v[bj][0][3]); w.z = cvt_pk_bf16(v[bj][1][0], v[bj][1][1]); w.w = cvt_pk_bf16(v[bj][1][2], v[bj][1][3]);
;                     *(u32x4*)(rowp + 32 * bj) = w; } } }
.LBB0_216:
	v_pk_mul_f32 v[20:21], v[20:21], v[28:29]
	v_pk_mul_f32 v[26:27], v[18:19], v[26:27]
	v_pk_mul_f32 v[18:19], v[16:17], v[24:25]
	v_cvt_pk_bf16_f32 v16, v20, v21
	v_mov_b64_e32 v[20:21], s[18:19]
	v_mad_i64_i32 v[20:21], s[0:1], v32, s70, v[20:21]
	s_lshl_b32 s14, s79, 8
	v_lshl_add_u64 v[20:21], v[20:21], 0, s[14:15]
	s_lshl_b32 s14, s71, 1
	v_lshl_add_u64 v[20:21], v[20:21], 0, s[14:15]
	v_lshl_add_u64 v[20:21], v[20:21], 0, v[144:145]
	v_add_co_u32_e32 v20, vcc, 0x1000, v20
	v_pk_mul_f32 v[22:23], v[22:23], v[30:31]
	s_nop 0
	v_addc_co_u32_e32 v21, vcc, 0, v21, vcc
	v_cvt_pk_bf16_f32 v17, v22, v23
	v_cvt_pk_bf16_f32 v18, v18, v19
	v_cvt_pk_bf16_f32 v19, v26, v27
	global_store_dwordx4 v[20:21], v[16:19], off sc0 sc1

; __device__ __forceinline__ unsigned cvt_pk_bf16(float lo, float hi) { unsigned r; asm volatile("v_cvt_pk_bf16_f32 %0, %1, %2" : "=v"(r) : "v"(lo), "v"(hi)); return r; }
;     __device__ __forceinline__ void operator()(const f32x4 (&acc)[2][2][4][2], const State& st, const Unit& u, int wr, int wc, int fr, int fq) const {
;     ...
;                 if (u.pn >= 16) {
;                     const f32x4 q0 = v[0][0] * v[1][0], q1 = v[0][1] * v[1][1];
;                     u32x4 w; w.x = cvt_pk_bf16(q0[0], q0[1]); w.y = cvt_pk_bf16(q0[2], q0[3]); w.z = cvt_pk_bf16(q1[0], q1[1]); w.w = cvt_pk_bf16(q1[2], q1[3]);
;                     *(u32x4*)(O + (size_t)row * ldc + 4096 + (u.pn - 16) * 128 + wc * 32 + 8 * fq) = w;
;                 } else {
;                 bf16_t* rowp = O + (size_t)row * ldc + col0;
; #pragma unroll
;                 for (int bj = 0; bj < 2; ++bj) { u32x4 w; w.x = cvt_pk_bf16(v[bj][0][0], v[bj][0][1]); w.y = cvt_pk_bf16(v[bj][0][2], v[bj][0][3]); w.z = cvt_pk_bf16(v[bj][1][0], v[bj][1][1]); w.w = cvt_pk_bf16(v[bj][1][2], v[bj][1][3]);
;                     *(u32x4*)(rowp + 32 * bj) = w; } } }
.LBB0_220:
	v_pk_mul_f32 v[4:5], v[4:5], v[12:13]
	v_pk_mul_f32 v[10:11], v[2:3], v[10:11]
	v_pk_mul_f32 v[2:3], v[0:1], v[8:9]
	v_cvt_pk_bf16_f32 v0, v4, v5
	v_mov_b64_e32 v[4:5], s[18:19]
	v_mad_i64_i32 v[4:5], s[0:1], v16, s70, v[4:5]
	s_lshl_b32 s14, s79, 8
	v_lshl_add_u64 v[4:5], v[4:5], 0, s[14:15]
	s_lshl_b32 s14, s71, 1
	v_lshl_add_u64 v[4:5], v[4:5], 0, s[14:15]
	v_lshl_add_u64 v[4:5], v[4:5], 0, v[144:145]
	v_add_co_u32_e32 v4, vcc, 0x1000, v4
	v_pk_mul_f32 v[6:7], v[6:7], v[14:15]
	s_nop 0
	v_addc_co_u32_e32 v5, vcc, 0, v5, vcc
	v_cvt_pk_bf16_f32 v1, v6, v7
	v_cvt_pk_bf16_f32 v2, v2, v3
	v_cvt_pk_bf16_f32 v3, v10, v11
	global_store_dwordx4 v[4:5], v[0:3], off sc0 sc1
	s_andn2_b64 vcc, exec, s[38:39]
	s_mov_b64 s[0:1], -1
	s_cbranch_vccnz .LBB0_166
	s_branch .LBB0_234

; __device__ __forceinline__ unsigned cvt_pk_bf16(float lo, float hi) { unsigned r; asm volatile("v_cvt_pk_bf16_f32 %0, %1, %2" : "=v"(r) : "v"(lo), "v"(hi)); return r; }
;     __device__ __forceinline__ void operator()(const f32x4 (&acc)[2][2][4][2], const State& st, const Unit& u, int wr, int wc, int fr, int fq) const {
;     ...
;                 if (u.pn >= 16) {
;                     const f32x4 q0 = v[0][0] * v[1][0], q1 = v[0][1] * v[1][1];
;                     u32x4 w; w.x = cvt_pk_bf16(q0[0], q0[1]); w.y = cvt_pk_bf16(q0[2], q0[3]); w.z = cvt_pk_bf16(q1[0], q1[1]); w.w = cvt_pk_bf16(q1[2], q1[3]);
;                     *(u32x4*)(O + (size_t)row * ldc + 4096 + (u.pn - 16) * 128 + wc * 32 + 8 * fq) = w;
;                 } else {
;                 bf16_t* rowp = O + (size_t)row * ldc + col0;
; #pragma unroll
;                 for (int bj = 0; bj < 2; ++bj) { u32x4 w; w.x = cvt_pk_bf16(v[bj][0][0], v[bj][0][1]); w.y = cvt_pk_bf16(v[bj][0][2], v[bj][0][3]); w.z = cvt_pk_bf16(v[bj][1][0], v[bj][1][1]); w.w = cvt_pk_bf16(v[bj][1][2], v[bj][1][3]);
;                     *(u32x4*)(rowp + 32 * bj) = w; } } }
.LBB0_222:
	v_mov_b64_e32 v[114:115], s[18:19]
	v_mad_i64_i32 v[114:115], s[0:1], v112, s70, v[114:115]
	v_lshl_add_u64 v[118:119], v[128:129], 1, v[114:115]
	v_cvt_pk_bf16_f32 v114, v108, v109
	v_cvt_pk_bf16_f32 v115, v110, v111
	v_cvt_pk_bf16_f32 v116, v104, v105
	v_cvt_pk_bf16_f32 v117, v106, v107
	global_store_dwordx4 v[118:119], v[114:117], off sc0 sc1
	s_nop 1
	v_cvt_pk_bf16_f32 v114, v100, v101
	v_cvt_pk_bf16_f32 v115, v102, v103
	v_cvt_pk_bf16_f32 v116, v96, v97
	v_cvt_pk_bf16_f32 v117, v98, v99
	global_store_dwordx4 v[118:119], v[114:117], off offset:64 sc0 sc1
	s_cbranch_execz .LBB0_200
	s_branch .LBB0_201

; __device__ __forceinline__ unsigned cvt_pk_bf16(float lo, float hi) { unsigned r; asm volatile("v_cvt_pk_bf16_f32 %0, %1, %2" : "=v"(r) : "v"(lo), "v"(hi)); return r; }
;     __device__ __forceinline__ void operator()(const f32x4 (&acc)[2][2][4][2], const State& st, const Unit& u, int wr, int wc, int fr, int fq) const {
;     ...
;                 if (u.pn >= 16) {
;                     const f32x4 q0 = v[0][0] * v[1][0], q1 = v[0][1] * v[1][1];
;                     u32x4 w; w.x = cvt_pk_bf16(q0[0], q0[1]); w.y = cvt_pk_bf16(q0[2], q0[3]); w.z = cvt_pk_bf16(q1[0], q1[1]); w.w = cvt_pk_bf16(q1[2], q1[3]);
;                     *(u32x4*)(O + (size_t)row * ldc + 4096 + (u.pn - 16) * 128 + wc * 32 + 8 * fq) = w;
;                 } else {
;                 bf16_t* rowp = O + (size_t)row * ldc + col0;
; #pragma unroll
;                 for (int bj = 0; bj < 2; ++bj) { u32x4 w; w.x = cvt_pk_bf16(v[bj][0][0], v[bj][0][1]); w.y = cvt_pk_bf16(v[bj][0][2], v[bj][0][3]); w.z = cvt_pk_bf16(v[bj][1][0], v[bj][1][1]); w.w = cvt_pk_bf16(v[bj][1][2], v[bj][1][3]);
;                     *(u32x4*)(rowp + 32 * bj) = w; } } }
.LBB0_224:
	v_mov_b64_e32 v[98:99], s[18:19]
	v_mad_i64_i32 v[98:99], s[0:1], v96, s70, v[98:99]
	v_lshl_add_u64 v[102:103], v[128:129], 1, v[98:99]
	v_cvt_pk_bf16_f32 v98, v92, v93
	v_cvt_pk_bf16_f32 v99, v94, v95
	v_cvt_pk_bf16_f32 v100, v88, v89
	v_cvt_pk_bf16_f32 v101, v90, v91
	global_store_dwordx4 v[102:103], v[98:101], off sc0 sc1
	s_nop 1
	v_cvt_pk_bf16_f32 v98, v84, v85
	v_cvt_pk_bf16_f32 v99, v86, v87
	v_cvt_pk_bf16_f32 v100, v80, v81
	v_cvt_pk_bf16_f32 v101, v82, v83
	global_store_dwordx4 v[102:103], v[98:101], off offset:64 sc0 sc1
	s_cbranch_execz .LBB0_204
	s_branch .LBB0_205

; __device__ __forceinline__ unsigned cvt_pk_bf16(float lo, float hi) { unsigned r; asm volatile("v_cvt_pk_bf16_f32 %0, %1, %2" : "=v"(r) : "v"(lo), "v"(hi)); return r; }
;     __device__ __forceinline__ void operator()(const f32x4 (&acc)[2][2][4][2], const State& st, const Unit& u, int wr, int wc, int fr, int fq) const {
;     ...
;                 if (u.pn >= 16) {
;                     const f32x4 q0 = v[0][0] * v[1][0], q1 = v[0][1] * v[1][1];
;                     u32x4 w; w.x = cvt_pk_bf16(q0[0], q0[1]); w.y = cvt_pk_bf16(q0[2], q0[3]); w.z = cvt_pk_bf16(q1[0], q1[1]); w.w = cvt_pk_bf16(q1[2], q1[3]);
;                     *(u32x4*)(O + (size_t)row * ldc + 4096 + (u.pn - 16) * 128 + wc * 32 + 8 * fq) = w;
;                 } else {
;                 bf16_t* rowp = O + (size_t)row * ldc + col0;
; #pragma unroll
;                 for (int bj = 0; bj < 2; ++bj) { u32x4 w; w.x = cvt_pk_bf16(v[bj][0][0], v[bj][0][1]); w.y = cvt_pk_bf16(v[bj][0][2], v[bj][0][3]); w.z = cvt_pk_bf16(v[bj][1][0], v[bj][1][1]); w.w = cvt_pk_bf16(v[bj][1][2], v[bj][1][3]);
;                     *(u32x4*)(rowp + 32 * bj) = w; } } }
.LBB0_226:
	v_mov_b64_e32 v[82:83], s[18:19]
	v_mad_i64_i32 v[82:83], s[0:1], v80, s70, v[82:83]
	v_lshl_add_u64 v[86:87], v[128:129], 1, v[82:83]
	v_cvt_pk_bf16_f32 v82, v76, v77
	v_cvt_pk_bf16_f32 v83, v78, v79
	v_cvt_pk_bf16_f32 v84, v72, v73
	v_cvt_pk_bf16_f32 v85, v74, v75
	global_store_dwordx4 v[86:87], v[82:85], off sc0 sc1
	s_nop 1
	v_cvt_pk_bf16_f32 v82, v68, v69
	v_cvt_pk_bf16_f32 v83, v70, v71
	v_cvt_pk_bf16_f32 v84, v64, v65
	v_cvt_pk_bf16_f32 v85, v66, v67
	global_store_dwordx4 v[86:87], v[82:85], off offset:64 sc0 sc1
	s_cbranch_execz .LBB0_208
	s_branch .LBB0_209

; __device__ __forceinline__ unsigned cvt_pk_bf16(float lo, float hi) { unsigned r; asm volatile("v_cvt_pk_bf16_f32 %0, %1, %2" : "=v"(r) : "v"(lo), "v"(hi)); return r; }
;     __device__ __forceinline__ void operator()(const f32x4 (&acc)[2][2][4][2], const State& st, const Unit& u, int wr, int wc, int fr, int fq) const {
;     ...
;                 if (u.pn >= 16) {
;                     const f32x4 q0 = v[0][0] * v[1][0], q1 = v[0][1] * v[1][1];
;                     u32x4 w; w.x = cvt_pk_bf16(q0[0], q0[1]); w.y = cvt_pk_bf16(q0[2], q0[3]); w.z = cvt_pk_bf16(q1[0], q1[1]); w.w = cvt_pk_bf16(q1[2], q1[3]);
;                     *(u32x4*)(O + (size_t)row * ldc + 4096 + (u.pn - 16) * 128 + wc * 32 + 8 * fq) = w;
;                 } else {
;                 bf16_t* rowp = O + (size_t)row * ldc + col0;
; #pragma unroll
;                 for (int bj = 0; bj < 2; ++bj) { u32x4 w; w.x = cvt_pk_bf16(v[bj][0][0], v[bj][0][1]); w.y = cvt_pk_bf16(v[bj][0][2], v[bj][0][3]); w.z = cvt_pk_bf16(v[bj][1][0], v[bj][1][1]); w.w = cvt_pk_bf16(v[bj][1][2], v[bj][1][3]);
;                     *(u32x4*)(rowp + 32 * bj) = w; } } }
.LBB0_228:
	v_mov_b64_e32 v[66:67], s[18:19]
	v_mad_i64_i32 v[66:67], s[0:1], v64, s70, v[66:67]
	v_lshl_add_u64 v[70:71], v[128:129], 1, v[66:67]
	v_cvt_pk_bf16_f32 v66, v44, v45
	v_cvt_pk_bf16_f32 v67, v46, v47
	v_cvt_pk_bf16_f32 v68, v40, v41
	v_cvt_pk_bf16_f32 v69, v42, v43
	global_store_dwordx4 v[70:71], v[66:69], off sc0 sc1
	s_nop 1
	v_cvt_pk_bf16_f32 v66, v36, v37
	v_cvt_pk_bf16_f32 v67, v38, v39
	v_cvt_pk_bf16_f32 v68, v32, v33
	v_cvt_pk_bf16_f32 v69, v34, v35
	global_store_dwordx4 v[70:71], v[66:69], off offset:64 sc0 sc1
	s_cbranch_execz .LBB0_212
	s_branch .LBB0_213

; __device__ __forceinline__ unsigned cvt_pk_bf16(float lo, float hi) { unsigned r; asm volatile("v_cvt_pk_bf16_f32 %0, %1, %2" : "=v"(r) : "v"(lo), "v"(hi)); return r; }
;     __device__ __forceinline__ void operator()(const f32x4 (&acc)[2][2][4][2], const State& st, const Unit& u, int wr, int wc, int fr, int fq) const {
;     ...
;                 if (u.pn >= 16) {
;                     const f32x4 q0 = v[0][0] * v[1][0], q1 = v[0][1] * v[1][1];
;                     u32x4 w; w.x = cvt_pk_bf16(q0[0], q0[1]); w.y = cvt_pk_bf16(q0[2], q0[3]); w.z = cvt_pk_bf16(q1[0], q1[1]); w.w = cvt_pk_bf16(q1[2], q1[3]);
;                     *(u32x4*)(O + (size_t)row * ldc + 4096 + (u.pn - 16) * 128 + wc * 32 + 8 * fq) = w;
;                 } else {
;                 bf16_t* rowp = O + (size_t)row * ldc + col0;
; #pragma unroll
;                 for (int bj = 0; bj < 2; ++bj) { u32x4 w; w.x = cvt_pk_bf16(v[bj][0][0], v[bj][0][1]); w.y = cvt_pk_bf16(v[bj][0][2], v[bj][0][3]); w.z = cvt_pk_bf16(v[bj][1][0], v[bj][1][1]); w.w = cvt_pk_bf16(v[bj][1][2], v[bj][1][3]);
;                     *(u32x4*)(rowp + 32 * bj) = w; } } }
.LBB0_230:
	v_mov_b64_e32 v[34:35], s[18:19]
	v_mad_i64_i32 v[34:35], s[0:1], v32, s70, v[34:35]
	v_lshl_add_u64 v[38:39], v[128:129], 1, v[34:35]
	v_cvt_pk_bf16_f32 v34, v28, v29
	v_cvt_pk_bf16_f32 v35, v30, v31
	v_cvt_pk_bf16_f32 v36, v24, v25
	v_cvt_pk_bf16_f32 v37, v26, v27
	global_store_dwordx4 v[38:39], v[34:37], off sc0 sc1
	s_nop 1
	v_cvt_pk_bf16_f32 v34, v20, v21
	v_cvt_pk_bf16_f32 v35, v22, v23
	v_cvt_pk_bf16_f32 v36, v16, v17
	v_cvt_pk_bf16_f32 v37, v18, v19
	global_store_dwordx4 v[38:39], v[34:37], off offset:64 sc0 sc1
	s_cbranch_execz .LBB0_216
	s_branch .LBB0_217

; __device__ __forceinline__ unsigned cvt_pk_bf16(float lo, float hi) { unsigned r; asm volatile("v_cvt_pk_bf16_f32 %0, %1, %2" : "=v"(r) : "v"(lo), "v"(hi)); return r; }
;     __device__ __forceinline__ void operator()(const f32x4 (&acc)[2][2][4][2], const State& st, const Unit& u, int wr, int wc, int fr, int fq) const {
;     ...
;                 if (u.pn >= 16) {
;                     const f32x4 q0 = v[0][0] * v[1][0], q1 = v[0][1] * v[1][1];
;                     u32x4 w; w.x = cvt_pk_bf16(q0[0], q0[1]); w.y = cvt_pk_bf16(q0[2], q0[3]); w.z = cvt_pk_bf16(q1[0], q1[1]); w.w = cvt_pk_bf16(q1[2], q1[3]);
;                     *(u32x4*)(O + (size_t)row * ldc + 4096 + (u.pn - 16) * 128 + wc * 32 + 8 * fq) = w;
;                 } else {
;                 bf16_t* rowp = O + (size_t)row * ldc + col0;
; #pragma unroll
;                 for (int bj = 0; bj < 2; ++bj) { u32x4 w; w.x = cvt_pk_bf16(v[bj][0][0], v[bj][0][1]); w.y = cvt_pk_bf16(v[bj][0][2], v[bj][0][3]); w.z = cvt_pk_bf16(v[bj][1][0], v[bj][1][1]); w.w = cvt_pk_bf16(v[bj][1][2], v[bj][1][3]);
;                     *(u32x4*)(rowp + 32 * bj) = w; } } }
.LBB0_232:
	v_mov_b64_e32 v[18:19], s[18:19]
	v_mad_i64_i32 v[18:19], s[0:1], v16, s70, v[18:19]
	v_lshl_add_u64 v[22:23], v[128:129], 1, v[18:19]
	v_cvt_pk_bf16_f32 v18, v12, v13
	v_cvt_pk_bf16_f32 v19, v14, v15
	v_cvt_pk_bf16_f32 v20, v8, v9
	v_cvt_pk_bf16_f32 v21, v10, v11
	global_store_dwordx4 v[22:23], v[18:21], off sc0 sc1
	s_nop 1
	v_cvt_pk_bf16_f32 v18, v4, v5
	v_cvt_pk_bf16_f32 v19, v6, v7
	v_cvt_pk_bf16_f32 v20, v0, v1
	v_cvt_pk_bf16_f32 v21, v2, v3
	global_store_dwordx4 v[22:23], v[18:21], off offset:64 sc0 sc1
	s_cbranch_execz .LBB0_220

; __device__ __forceinline__ unsigned cvtpk(float lo, float hi) { unsigned r; asm volatile("v_cvt_pk_bf16_f32 %0, %1, %2" : "=v"(r) : "v"(lo), "v"(hi)); return r; }
; __device__ __forceinline__ void conv_item(const bf16* __restrict__ P, bf16* __restrict__ MIX, const float* __restrict__ cw, int it, int lane) {
;     ...
;       } else { const u32x4 gp = *(const u32x4*)(Pu + (size_t)t * PW + 4096 + c0);
; #pragma unroll
;         for (int e = 0; e < 4; ++e) { p[k][2 * e] = __uint_as_float(gp[e] << 16); p[k][2 * e + 1] = __uint_as_float(gp[e] & 0xffff0000u); } } }
; #pragma unroll
;     for (int i = 0; i < 4; ++i) { const u32x4 gb = *(const u32x4*)(Pu + (size_t)(t0 + i) * PW + 3072 + c0); float r[8];
; #pragma unroll
;       for (int e = 0; e < 4; ++e) { r[2 * e] = __uint_as_float(gb[e] << 16) * (w0[2 * e] * p[i][2 * e] + w1[2 * e] * p[i + 1][2 * e] + w2[2 * e] * p[i + 2][2 * e]);
;         r[2 * e + 1] = __uint_as_float(gb[e] & 0xffff0000u) * (w0[2 * e + 1] * p[i][2 * e + 1] + w1[2 * e + 1] * p[i + 1][2 * e + 1] + w2[2 * e + 1] * p[i + 2][2 * e + 1]); }
;       u32x4 o; o.x = cvtpk(r[0], r[1]); o.y = cvtpk(r[2], r[3]); o.z = cvtpk(r[4], r[5]); o.w = cvtpk(r[6], r[7]);
;       *(u32x4*)(Mu + (size_t)(t0 + i) * DMODEL + 1024 + c0) = o; } }
.LBB0_298:
	global_load_dwordx4 v[32:35], v42, s[22:23]
	global_load_dwordx4 v[36:39], v42, s[26:27]
	global_load_dwordx4 v[20:23], v42, s[76:77]
	global_load_dwordx4 v[24:27], v42, s[96:97]
	global_load_dwordx4 v[70:73], v42, s[28:29]
	s_waitcnt vmcnt(9)
	v_mov_b32_e32 v62, v12
	s_waitcnt vmcnt(6)
	v_mov_b32_e32 v63, v28
	v_mov_b32_e32 v60, v13
	v_mov_b32_e32 v61, v29
	v_mov_b32_e32 v56, v14
	v_mov_b32_e32 v57, v30
	v_mov_b32_e32 v54, v15
	v_mov_b32_e32 v55, v31
	v_mov_b32_e32 v52, v0
	s_waitcnt vmcnt(5)
	v_mov_b32_e32 v53, v8
	v_mov_b32_e32 v50, v1
	v_mov_b32_e32 v51, v9
	v_mov_b32_e32 v48, v2
	v_mov_b32_e32 v49, v10
	v_mov_b32_e32 v46, v3
	v_mov_b32_e32 v47, v11
	s_mov_b64 s[78:79], s[62:63]
	s_waitcnt vmcnt(0)
	v_lshlrev_b32_e32 v78, 16, v70
	v_and_b32_e32 v79, 0xffff0000, v70
	v_lshlrev_b32_e32 v70, 16, v32
	v_mov_b32_e32 v65, v70
	v_pk_mul_f32 v[64:65], v[62:63], v[64:65]
	v_lshlrev_b32_e32 v82, 16, v71
	v_fma_f32 v64, v16, v75, v64
	v_and_b32_e32 v83, 0xffff0000, v71
	v_lshlrev_b32_e32 v93, 16, v72
	v_and_b32_e32 v94, 0xffff0000, v72
	v_lshlrev_b32_e32 v95, 16, v73
	v_and_b32_e32 v43, 0xffff0000, v73
	v_lshlrev_b32_e32 v71, 16, v36
	v_add_f32_e32 v64, v64, v65
	v_mov_b32_e32 v72, v16
	v_mov_b32_e32 v73, v28
	v_mul_f32_e32 v78, v64, v78
	v_pk_mul_f32 v[64:65], v[72:73], v[70:71]
	s_nop 0
	v_fma_f32 v28, v12, v75, v64
	v_and_b32_e32 v64, 0xffff0000, v32
	v_mov_b32_e32 v75, v64
	v_pk_mul_f32 v[74:75], v[60:61], v[74:75]
	v_add_f32_e32 v91, v28, v65
	v_fma_f32 v28, v17, v67, v74
	v_add_f32_e32 v28, v28, v75
	v_mul_f32_e32 v28, v28, v79
	v_and_b32_e32 v65, 0xffff0000, v36
	v_cvt_pk_bf16_f32 v32, v78, v28
	v_mov_b32_e32 v28, v17
	v_pk_mul_f32 v[74:75], v[28:29], v[64:65]
	v_mov_b32_e32 v78, v18
	v_fma_f32 v36, v13, v67, v74
	v_lshlrev_b32_e32 v74, 16, v33
	v_mov_b32_e32 v67, v74
	v_pk_mul_f32 v[66:67], v[56:57], v[66:67]
	v_add_f32_e32 v92, v36, v75
	v_lshlrev_b32_e32 v75, 16, v37
	v_fma_f32 v36, v18, v77, v66
	v_mov_b32_e32 v79, v30
	v_add_f32_e32 v36, v36, v67
	v_pk_mul_f32 v[66:67], v[78:79], v[74:75]
	v_mul_f32_e32 v82, v36, v82
	v_fma_f32 v30, v14, v77, v66
	v_and_b32_e32 v66, 0xffff0000, v33
	v_mov_b32_e32 v77, v66
	v_add_f32_e32 v96, v30, v67
	v_and_b32_e32 v67, 0xffff0000, v37
	v_pk_mul_f32 v[36:37], v[54:55], v[76:77]
	v_lshlrev_b32_e32 v76, 16, v34
	v_fma_f32 v30, v19, v69, v36
	v_add_f32_e32 v30, v30, v37
	v_mul_f32_e32 v30, v30, v83
	v_cvt_pk_bf16_f32 v33, v82, v30
	v_mov_b32_e32 v30, v19
	v_pk_mul_f32 v[36:37], v[30:31], v[66:67]
	v_lshlrev_b32_e32 v77, 16, v38
	v_fma_f32 v36, v15, v69, v36
	v_mov_b32_e32 v69, v76
	v_add_f32_e32 v97, v36, v37
	v_pk_mul_f32 v[36:37], v[52:53], v[68:69]
	v_mov_b32_e32 v82, v4
	v_fma_f32 v36, v4, v81, v36
	v_add_f32_e32 v36, v36, v37
	v_mov_b32_e32 v83, v8
	v_mul_f32_e32 v93, v36, v93
	v_pk_mul_f32 v[36:37], v[82:83], v[76:77]
	v_and_b32_e32 v68, 0xffff0000, v34
	v_fma_f32 v8, v0, v81, v36
	v_mov_b32_e32 v81, v68
	v_add_f32_e32 v98, v8, v37
	v_pk_mul_f32 v[36:37], v[50:51], v[80:81]
	v_and_b32_e32 v69, 0xffff0000, v38
	v_fma_f32 v8, v5, v85, v36
	v_add_f32_e32 v8, v8, v37
	v_mul_f32_e32 v8, v8, v94
	v_cvt_pk_bf16_f32 v34, v93, v8
	v_mov_b32_e32 v8, v5
	v_pk_mul_f32 v[36:37], v[8:9], v[68:69]
	v_lshlrev_b32_e32 v80, 16, v35
	v_fma_f32 v36, v1, v85, v36
	v_mov_b32_e32 v85, v80
	v_add_f32_e32 v93, v36, v37
	v_pk_mul_f32 v[36:37], v[48:49], v[84:85]
	v_lshlrev_b32_e32 v81, 16, v39
	v_fma_f32 v36, v6, v89, v36
	v_add_f32_e32 v36, v36, v37
	v_mov_b32_e32 v84, v6
	v_mov_b32_e32 v85, v10
	v_mul_f32_e32 v94, v36, v95
	v_pk_mul_f32 v[36:37], v[84:85], v[80:81]
	s_nop 0
	v_fma_f32 v10, v2, v89, v36
	v_and_b32_e32 v36, 0xffff0000, v35
	v_mov_b32_e32 v89, v36
	v_add_f32_e32 v10, v10, v37
	v_and_b32_e32 v37, 0xffff0000, v39
	v_pk_mul_f32 v[38:39], v[46:47], v[88:89]
	s_nop 0
	v_fma_f32 v35, v7, v90, v38
	v_add_f32_e32 v35, v35, v39
	v_mul_f32_e32 v35, v35, v43
	v_cvt_pk_bf16_f32 v35, v94, v35
	global_store_dwordx4 v[86:87], v[32:35], off offset:3072 sc0 sc1
	global_load_dwordx4 v[32:35], v42, s[44:45]
	s_waitcnt vmcnt(0)
; __device__ __forceinline__ unsigned cvtpk(float lo, float hi) { unsigned r; asm volatile("v_cvt_pk_bf16_f32 %0, %1, %2" : "=v"(r) : "v"(lo), "v"(hi)); return r; }
; __device__ __forceinline__ void conv_item(const bf16* __restrict__ P, bf16* __restrict__ MIX, const float* __restrict__ cw, int it, int lane) {
;     ...
;     for (int i = 0; i < 4; ++i) { const u32x4 gb = *(const u32x4*)(Pu + (size_t)(t0 + i) * PW + 3072 + c0); float r[8];
; #pragma unroll
;       for (int e = 0; e < 4; ++e) { r[2 * e] = __uint_as_float(gb[e] << 16) * (w0[2 * e] * p[i][2 * e] + w1[2 * e] * p[i + 1][2 * e] + w2[2 * e] * p[i + 2][2 * e]);
;         r[2 * e + 1] = __uint_as_float(gb[e] & 0xffff0000u) * (w0[2 * e + 1] * p[i][2 * e + 1] + w1[2 * e + 1] * p[i + 1][2 * e + 1] + w2[2 * e + 1] * p[i + 2][2 * e + 1]); }
;       u32x4 o; o.x = cvtpk(r[0], r[1]); o.y = cvtpk(r[2], r[3]); o.z = cvtpk(r[4], r[5]); o.w = cvtpk(r[6], r[7]);
;       *(u32x4*)(Mu + (size_t)(t0 + i) * DMODEL + 1024 + c0) = o; } }
	v_lshlrev_b32_e32 v38, 16, v32
	v_and_b32_e32 v32, 0xffff0000, v32
	v_mul_f32_e32 v39, v92, v32
	v_lshlrev_b32_e32 v32, 16, v33
	v_mul_f32_e32 v43, v96, v32
	v_and_b32_e32 v32, 0xffff0000, v33
	v_mul_f32_e32 v86, v97, v32
	v_lshlrev_b32_e32 v32, 16, v34
	v_mul_f32_e32 v87, v98, v32
	v_and_b32_e32 v32, 0xffff0000, v34
	v_mul_f32_e32 v34, v93, v32
	v_lshlrev_b32_e32 v32, 16, v35
	v_mul_f32_e32 v88, v10, v32
	v_mov_b32_e32 v10, v7
	v_pk_mul_f32 v[32:33], v[10:11], v[36:37]
	v_and_b32_e32 v35, 0xffff0000, v35
	v_fma_f32 v32, v3, v90, v32
	v_add_f32_e32 v32, v32, v33
	v_mul_f32_e32 v35, v32, v35
	v_mul_f32_e32 v38, v91, v38
	v_cvt_pk_bf16_f32 v32, v38, v39
	v_cvt_pk_bf16_f32 v33, v43, v86
	v_cvt_pk_bf16_f32 v34, v87, v34
	v_cvt_pk_bf16_f32 v35, v88, v35
	global_store_dwordx4 v[58:59], v[32:35], off offset:3072 sc0 sc1
	global_load_dwordx4 v[32:35], v42, s[24:25]
	v_mov_b32_e32 v38, v70
	s_waitcnt vmcnt(0)
	v_lshlrev_b32_e32 v86, 16, v34
	v_and_b32_e32 v87, 0xffff0000, v34
	v_lshlrev_b32_e32 v34, 16, v20
	v_mov_b32_e32 v39, v34
	v_lshlrev_b32_e32 v43, 16, v32
	v_and_b32_e32 v58, 0xffff0000, v32
	v_lshlrev_b32_e32 v88, 16, v35
	v_and_b32_e32 v32, 0xffff0000, v35
	v_lshlrev_b32_e32 v35, 16, v24
	v_pk_mul_f32 v[38:39], v[62:63], v[38:39]
	v_pk_mul_f32 v[34:35], v[72:73], v[34:35]
	v_fma_f32 v16, v16, v71, v38
	v_add_f32_e32 v16, v16, v39
	v_fma_f32 v12, v12, v71, v34
	v_mul_f32_e32 v43, v16, v43
	v_add_f32_e32 v16, v12, v35
	v_and_b32_e32 v35, 0xffff0000, v24
	v_and_b32_e32 v34, 0xffff0000, v20
	v_mov_b32_e32 v38, v64
	v_mov_b32_e32 v39, v34
	v_pk_mul_f32 v[28:29], v[28:29], v[34:35]
	v_pk_mul_f32 v[38:39], v[60:61], v[38:39]
	v_fma_f32 v13, v13, v65, v28
	v_fma_f32 v12, v17, v65, v38
	v_add_f32_e32 v17, v13, v29
	v_lshlrev_b32_e32 v28, 16, v21
	v_lshlrev_b32_e32 v29, 16, v25
	v_and_b32_e32 v24, 0xffff0000, v21
	v_mov_b32_e32 v34, v74
	v_mov_b32_e32 v35, v28
	v_pk_mul_f32 v[28:29], v[78:79], v[28:29]
	v_mov_b32_e32 v20, v66
	v_mov_b32_e32 v21, v24
	v_pk_mul_f32 v[34:35], v[56:57], v[34:35]
	v_fma_f32 v14, v14, v75, v28
	v_pk_mul_f32 v[20:21], v[54:55], v[20:21]
	v_fma_f32 v13, v18, v75, v34
	v_add_f32_e32 v18, v14, v29
	v_fma_f32 v14, v19, v67, v20
	v_lshlrev_b32_e32 v59, 16, v33
	v_and_b32_e32 v33, 0xffff0000, v33
	v_add_f32_e32 v12, v12, v39
	v_add_f32_e32 v13, v13, v35
	v_and_b32_e32 v25, 0xffff0000, v25
	v_add_f32_e32 v14, v14, v21
	v_mul_f32_e32 v12, v12, v58
	v_mul_f32_e32 v13, v13, v59
	v_mul_f32_e32 v14, v14, v33
	v_pk_mul_f32 v[20:21], v[30:31], v[24:25]
	v_cvt_pk_bf16_f32 v12, v43, v12
	v_cvt_pk_bf16_f32 v13, v13, v14
	s_nop 0
	v_fma_f32 v14, v15, v67, v20
	v_add_f32_e32 v19, v14, v21
	v_lshlrev_b32_e32 v14, 16, v22
	v_lshlrev_b32_e32 v15, 16, v26
	v_mov_b32_e32 v20, v76
	v_mov_b32_e32 v21, v14
	v_pk_mul_f32 v[20:21], v[52:53], v[20:21]
	v_pk_mul_f32 v[14:15], v[82:83], v[14:15]
	v_fma_f32 v4, v4, v77, v20
	v_fma_f32 v0, v0, v77, v14
	v_and_b32_e32 v20, 0xffff0000, v22
	v_add_f32_e32 v24, v0, v15
	v_mov_b32_e32 v14, v68
	v_mov_b32_e32 v15, v20
	v_pk_mul_f32 v[14:15], v[50:51], v[14:15]
	v_add_f32_e32 v4, v4, v21
	v_fma_f32 v0, v5, v69, v14
	v_mul_f32_e32 v4, v4, v86
	v_and_b32_e32 v21, 0xffff0000, v26
	v_add_f32_e32 v0, v0, v15
	v_mul_f32_e32 v0, v0, v87
	v_cvt_pk_bf16_f32 v14, v4, v0
	v_pk_mul_f32 v[4:5], v[8:9], v[20:21]
	s_nop 0
	v_fma_f32 v0, v1, v69, v4
	v_add_f32_e32 v8, v0, v5
	v_lshlrev_b32_e32 v0, 16, v23
	v_lshlrev_b32_e32 v1, 16, v27
	v_mov_b32_e32 v4, v80
	v_mov_b32_e32 v5, v0
	v_pk_mul_f32 v[4:5], v[48:49], v[4:5]
	v_pk_mul_f32 v[0:1], v[84:85], v[0:1]
	v_fma_f32 v4, v6, v81, v4
	v_fma_f32 v0, v2, v81, v0
	v_add_f32_e32 v4, v4, v5
	v_add_f32_e32 v2, v0, v1
	v_and_b32_e32 v0, 0xffff0000, v23
	v_mul_f32_e32 v6, v4, v88
	v_mov_b32_e32 v4, v36
	v_mov_b32_e32 v5, v0
	v_pk_mul_f32 v[4:5], v[46:47], v[4:5]
	v_and_b32_e32 v1, 0xffff0000, v27
	v_fma_f32 v4, v7, v37, v4
	v_add_f32_e32 v4, v4, v5
	v_mul_f32_e32 v4, v4, v32
	v_cvt_pk_bf16_f32 v15, v6, v4
	global_load_dwordx4 v[4:7], v42, s[40:41]
	v_pk_mul_f32 v[0:1], v[10:11], v[0:1]
	global_store_dwordx4 v[44:45], v[12:15], off offset:3072 sc0 sc1
	v_fma_f32 v0, v3, v37, v0
	v_add_f32_e32 v0, v0, v1
	s_waitcnt vmcnt(1)
	v_lshlrev_b32_e32 v13, 16, v6
	v_and_b32_e32 v6, 0xffff0000, v6
	v_mul_f32_e32 v6, v8, v6
	v_lshlrev_b32_e32 v8, 16, v7
	v_mul_f32_e32 v8, v2, v8
	v_and_b32_e32 v2, 0xffff0000, v7
	v_lshlrev_b32_e32 v9, 16, v4
	v_and_b32_e32 v4, 0xffff0000, v4
	v_lshlrev_b32_e32 v12, 16, v5
	v_and_b32_e32 v5, 0xffff0000, v5
	v_mul_f32_e32 v3, v0, v2
	v_mul_f32_e32 v9, v16, v9
	v_mul_f32_e32 v4, v17, v4
	v_mul_f32_e32 v12, v18, v12
	v_mul_f32_e32 v5, v19, v5
	v_mul_f32_e32 v13, v24, v13
	v_cvt_pk_bf16_f32 v0, v9, v4
	v_cvt_pk_bf16_f32 v1, v12, v5
	v_cvt_pk_bf16_f32 v2, v13, v6
	v_cvt_pk_bf16_f32 v3, v8, v3
	global_store_dwordx4 v[40:41], v[0:3], off offset:3072 sc0 sc1

; __device__ __forceinline__ unsigned cvtpk(float lo, float hi) { unsigned r; asm volatile("v_cvt_pk_bf16_f32 %0, %1, %2" : "=v"(r) : "v"(lo), "v"(hi)); return r; }
; __device__ __forceinline__ void conv_item(const bf16* __restrict__ P, bf16* __restrict__ MIX, const float* __restrict__ cw, int it, int lane) {
;     ...
;     for (int i = 0; i < 4; ++i) { const u32x4 gb = *(const u32x4*)(Pu + (size_t)(t0 + i) * PW + 3072 + c0); float r[8];
; #pragma unroll
;       for (int e = 0; e < 4; ++e) { r[2 * e] = __uint_as_float(gb[e] << 16) * (w0[2 * e] * p[i][2 * e] + w1[2 * e] * p[i + 1][2 * e] + w2[2 * e] * p[i + 2][2 * e]);
;         r[2 * e + 1] = __uint_as_float(gb[e] & 0xffff0000u) * (w0[2 * e + 1] * p[i][2 * e + 1] + w1[2 * e + 1] * p[i + 1][2 * e + 1] + w2[2 * e + 1] * p[i + 2][2 * e + 1]); }
;       u32x4 o; o.x = cvtpk(r[0], r[1]); o.y = cvtpk(r[2], r[3]); o.z = cvtpk(r[4], r[5]); o.w = cvtpk(r[6], r[7]);
.Lmy_w1_c:
	v_and_b32_e32 v72, s59, v72
	v_and_b32_e32 v73, s59, v73
	v_and_b32_e32 v74, s59, v74
	v_and_b32_e32 v75, s59, v75
	v_and_b32_e32 v76, s59, v76
	v_and_b32_e32 v77, s59, v77
	v_and_b32_e32 v78, s59, v78
	v_and_b32_e32 v79, s59, v79
	v_lshlrev_b32_e32 v212, 16, v72
	v_and_b32_e32 v213, 0xffff0000, v72
	v_lshlrev_b32_e32 v214, 16, v76
	v_and_b32_e32 v215, 0xffff0000, v76
	v_lshlrev_b32_e32 v216, 16, v80
	v_and_b32_e32 v217, 0xffff0000, v80
	v_lshlrev_b32_e32 v218, 16, v84
	v_and_b32_e32 v219, 0xffff0000, v84
	v_lshlrev_b32_e32 v220, 16, v88
	v_and_b32_e32 v221, 0xffff0000, v88
	v_lshlrev_b32_e32 v222, 16, v92
	v_and_b32_e32 v223, 0xffff0000, v92
	v_lshlrev_b32_e32 v224, 16, v112
	v_and_b32_e32 v225, 0xffff0000, v112
	v_lshlrev_b32_e32 v226, 16, v116
	v_and_b32_e32 v227, 0xffff0000, v116
	v_lshlrev_b32_e32 v228, 16, v120
	v_and_b32_e32 v229, 0xffff0000, v120
	v_lshlrev_b32_e32 v230, 16, v124
	v_and_b32_e32 v231, 0xffff0000, v124
	v_pk_mul_f32 v[232:233], v[24:25], v[212:213]
	v_pk_mul_f32 v[234:235], v[24:25], v[214:215]
	v_pk_mul_f32 v[236:237], v[24:25], v[216:217]
	v_pk_mul_f32 v[238:239], v[24:25], v[218:219]
	v_pk_fma_f32 v[232:233], v[32:33], v[214:215], v[232:233]
	v_pk_fma_f32 v[234:235], v[32:33], v[216:217], v[234:235]
	v_pk_fma_f32 v[236:237], v[32:33], v[218:219], v[236:237]
	v_pk_fma_f32 v[238:239], v[32:33], v[220:221], v[238:239]
	v_pk_fma_f32 v[232:233], v[40:41], v[216:217], v[232:233]
	v_pk_fma_f32 v[234:235], v[40:41], v[218:219], v[234:235]
	v_pk_fma_f32 v[236:237], v[40:41], v[220:221], v[236:237]
	v_pk_fma_f32 v[238:239], v[40:41], v[222:223], v[238:239]
	v_pk_mul_f32 v[232:233], v[224:225], v[232:233]
	v_pk_mul_f32 v[234:235], v[226:227], v[234:235]
	v_pk_mul_f32 v[236:237], v[228:229], v[236:237]
	v_pk_mul_f32 v[238:239], v[230:231], v[238:239]
	v_cvt_pk_bf16_f32 v112, v232, v233
	v_cvt_pk_bf16_f32 v116, v234, v235
	v_cvt_pk_bf16_f32 v120, v236, v237
	v_cvt_pk_bf16_f32 v124, v238, v239
	v_lshlrev_b32_e32 v212, 16, v73
	v_and_b32_e32 v213, 0xffff0000, v73
	v_lshlrev_b32_e32 v214, 16, v77
	v_and_b32_e32 v215, 0xffff0000, v77
	v_lshlrev_b32_e32 v216, 16, v81
	v_and_b32_e32 v217, 0xffff0000, v81
	v_lshlrev_b32_e32 v218, 16, v85
	v_and_b32_e32 v219, 0xffff0000, v85
	v_lshlrev_b32_e32 v220, 16, v89
	v_and_b32_e32 v221, 0xffff0000, v89
	v_lshlrev_b32_e32 v222, 16, v93
	v_and_b32_e32 v223, 0xffff0000, v93
	v_lshlrev_b32_e32 v224, 16, v113
	v_and_b32_e32 v225, 0xffff0000, v113
	v_lshlrev_b32_e32 v226, 16, v117
	v_and_b32_e32 v227, 0xffff0000, v117
	v_lshlrev_b32_e32 v228, 16, v121
	v_and_b32_e32 v229, 0xffff0000, v121
	v_lshlrev_b32_e32 v230, 16, v125
	v_and_b32_e32 v231, 0xffff0000, v125
	v_pk_mul_f32 v[232:233], v[26:27], v[212:213]
	v_pk_mul_f32 v[234:235], v[26:27], v[214:215]
	v_pk_mul_f32 v[236:237], v[26:27], v[216:217]
	v_pk_mul_f32 v[238:239], v[26:27], v[218:219]
	v_pk_fma_f32 v[232:233], v[34:35], v[214:215], v[232:233]
	v_pk_fma_f32 v[234:235], v[34:35], v[216:217], v[234:235]
	v_pk_fma_f32 v[236:237], v[34:35], v[218:219], v[236:237]
	v_pk_fma_f32 v[238:239], v[34:35], v[220:221], v[238:239]
	v_pk_fma_f32 v[232:233], v[42:43], v[216:217], v[232:233]
	v_pk_fma_f32 v[234:235], v[42:43], v[218:219], v[234:235]
	v_pk_fma_f32 v[236:237], v[42:43], v[220:221], v[236:237]
	v_pk_fma_f32 v[238:239], v[42:43], v[222:223], v[238:239]
	v_pk_mul_f32 v[232:233], v[224:225], v[232:233]
	v_pk_mul_f32 v[234:235], v[226:227], v[234:235]
	v_pk_mul_f32 v[236:237], v[228:229], v[236:237]
	v_pk_mul_f32 v[238:239], v[230:231], v[238:239]
	v_cvt_pk_bf16_f32 v113, v232, v233
	v_cvt_pk_bf16_f32 v117, v234, v235
	v_cvt_pk_bf16_f32 v121, v236, v237
	v_cvt_pk_bf16_f32 v125, v238, v239
	v_lshlrev_b32_e32 v212, 16, v74
	v_and_b32_e32 v213, 0xffff0000, v74
	v_lshlrev_b32_e32 v214, 16, v78
	v_and_b32_e32 v215, 0xffff0000, v78
; __device__ __forceinline__ unsigned cvtpk(float lo, float hi) { unsigned r; asm volatile("v_cvt_pk_bf16_f32 %0, %1, %2" : "=v"(r) : "v"(lo), "v"(hi)); return r; }
; __device__ __forceinline__ void conv_item(const bf16* __restrict__ P, bf16* __restrict__ MIX, const float* __restrict__ cw, int it, int lane) {
;     ...
;     for (int i = 0; i < 4; ++i) { const u32x4 gb = *(const u32x4*)(Pu + (size_t)(t0 + i) * PW + 3072 + c0); float r[8];
; #pragma unroll
;       for (int e = 0; e < 4; ++e) { r[2 * e] = __uint_as_float(gb[e] << 16) * (w0[2 * e] * p[i][2 * e] + w1[2 * e] * p[i + 1][2 * e] + w2[2 * e] * p[i + 2][2 * e]);
;         r[2 * e + 1] = __uint_as_float(gb[e] & 0xffff0000u) * (w0[2 * e + 1] * p[i][2 * e + 1] + w1[2 * e + 1] * p[i + 1][2 * e + 1] + w2[2 * e + 1] * p[i + 2][2 * e + 1]); }
;       u32x4 o; o.x = cvtpk(r[0], r[1]); o.y = cvtpk(r[2], r[3]); o.z = cvtpk(r[4], r[5]); o.w = cvtpk(r[6], r[7]);
;       *(u32x4*)(Mu + (size_t)(t0 + i) * DMODEL + 1024 + c0) = o; } }
	v_lshlrev_b32_e32 v216, 16, v82
	v_and_b32_e32 v217, 0xffff0000, v82
	v_lshlrev_b32_e32 v218, 16, v86
	v_and_b32_e32 v219, 0xffff0000, v86
	v_lshlrev_b32_e32 v220, 16, v90
	v_and_b32_e32 v221, 0xffff0000, v90
	v_lshlrev_b32_e32 v222, 16, v94
	v_and_b32_e32 v223, 0xffff0000, v94
	v_lshlrev_b32_e32 v224, 16, v114
	v_and_b32_e32 v225, 0xffff0000, v114
	v_lshlrev_b32_e32 v226, 16, v118
	v_and_b32_e32 v227, 0xffff0000, v118
	v_lshlrev_b32_e32 v228, 16, v122
	v_and_b32_e32 v229, 0xffff0000, v122
	v_lshlrev_b32_e32 v230, 16, v126
	v_and_b32_e32 v231, 0xffff0000, v126
	v_pk_mul_f32 v[232:233], v[28:29], v[212:213]
	v_pk_mul_f32 v[234:235], v[28:29], v[214:215]
	v_pk_mul_f32 v[236:237], v[28:29], v[216:217]
	v_pk_mul_f32 v[238:239], v[28:29], v[218:219]
	v_pk_fma_f32 v[232:233], v[36:37], v[214:215], v[232:233]
	v_pk_fma_f32 v[234:235], v[36:37], v[216:217], v[234:235]
	v_pk_fma_f32 v[236:237], v[36:37], v[218:219], v[236:237]
	v_pk_fma_f32 v[238:239], v[36:37], v[220:221], v[238:239]
	v_pk_fma_f32 v[232:233], v[44:45], v[216:217], v[232:233]
	v_pk_fma_f32 v[234:235], v[44:45], v[218:219], v[234:235]
	v_pk_fma_f32 v[236:237], v[44:45], v[220:221], v[236:237]
	v_pk_fma_f32 v[238:239], v[44:45], v[222:223], v[238:239]
	v_pk_mul_f32 v[232:233], v[224:225], v[232:233]
	v_pk_mul_f32 v[234:235], v[226:227], v[234:235]
	v_pk_mul_f32 v[236:237], v[228:229], v[236:237]
	v_pk_mul_f32 v[238:239], v[230:231], v[238:239]
	v_cvt_pk_bf16_f32 v114, v232, v233
	v_cvt_pk_bf16_f32 v118, v234, v235
	v_cvt_pk_bf16_f32 v122, v236, v237
	v_cvt_pk_bf16_f32 v126, v238, v239
	v_lshlrev_b32_e32 v212, 16, v75
	v_and_b32_e32 v213, 0xffff0000, v75
	v_lshlrev_b32_e32 v214, 16, v79
	v_and_b32_e32 v215, 0xffff0000, v79
	v_lshlrev_b32_e32 v216, 16, v83
	v_and_b32_e32 v217, 0xffff0000, v83
	v_lshlrev_b32_e32 v218, 16, v87
	v_and_b32_e32 v219, 0xffff0000, v87
	v_lshlrev_b32_e32 v220, 16, v91
	v_and_b32_e32 v221, 0xffff0000, v91
	v_lshlrev_b32_e32 v222, 16, v95
	v_and_b32_e32 v223, 0xffff0000, v95
	v_lshlrev_b32_e32 v224, 16, v115
	v_and_b32_e32 v225, 0xffff0000, v115
	v_lshlrev_b32_e32 v226, 16, v119
	v_and_b32_e32 v227, 0xffff0000, v119
	v_lshlrev_b32_e32 v228, 16, v123
	v_and_b32_e32 v229, 0xffff0000, v123
	v_lshlrev_b32_e32 v230, 16, v127
	v_and_b32_e32 v231, 0xffff0000, v127
	v_pk_mul_f32 v[232:233], v[30:31], v[212:213]
	v_pk_mul_f32 v[234:235], v[30:31], v[214:215]
	v_pk_mul_f32 v[236:237], v[30:31], v[216:217]
	v_pk_mul_f32 v[238:239], v[30:31], v[218:219]
	v_pk_fma_f32 v[232:233], v[38:39], v[214:215], v[232:233]
	v_pk_fma_f32 v[234:235], v[38:39], v[216:217], v[234:235]
	v_pk_fma_f32 v[236:237], v[38:39], v[218:219], v[236:237]
	v_pk_fma_f32 v[238:239], v[38:39], v[220:221], v[238:239]
	v_pk_fma_f32 v[232:233], v[46:47], v[216:217], v[232:233]
	v_pk_fma_f32 v[234:235], v[46:47], v[218:219], v[234:235]
	v_pk_fma_f32 v[236:237], v[46:47], v[220:221], v[236:237]
	v_pk_fma_f32 v[238:239], v[46:47], v[222:223], v[238:239]
	v_pk_mul_f32 v[232:233], v[224:225], v[232:233]
	v_pk_mul_f32 v[234:235], v[226:227], v[234:235]
	v_pk_mul_f32 v[236:237], v[228:229], v[236:237]
	v_pk_mul_f32 v[238:239], v[230:231], v[238:239]
	v_cvt_pk_bf16_f32 v115, v232, v233
	v_cvt_pk_bf16_f32 v119, v234, v235
	v_cvt_pk_bf16_f32 v123, v236, v237
	v_cvt_pk_bf16_f32 v127, v238, v239
	global_store_dwordx4 v198, v[96:99], s[0:1] offset:2048 sc0 sc1
	global_store_dwordx4 v207, v[100:103], s[0:1] offset:2048 sc0 sc1
	global_store_dwordx4 v208, v[104:107], s[0:1] offset:2048 sc0 sc1
	global_store_dwordx4 v199, v[108:111], s[0:1] offset:2048 sc0 sc1
	global_store_dwordx4 v198, v[112:115], s[0:1] offset:3072 sc0 sc1
	global_store_dwordx4 v207, v[116:119], s[0:1] offset:3072 sc0 sc1
	global_store_dwordx4 v208, v[120:123], s[0:1] offset:3072 sc0 sc1
	global_store_dwordx4 v199, v[124:127], s[0:1] offset:3072 sc0 sc1

; __device__ __forceinline__ unsigned cvtpk(float lo, float hi) { unsigned r; asm volatile("v_cvt_pk_bf16_f32 %0, %1, %2" : "=v"(r) : "v"(lo), "v"(hi)); return r; }
; __device__ __forceinline__ void conv_item(const bf16* __restrict__ P, bf16* __restrict__ MIX, const float* __restrict__ cw, int it, int lane) {
;     ...
;     for (int k = 0; k < 6; ++k) { const int t = t0 - 2 + k;
;       if (k < 2 && first) {
; #pragma unroll
;         for (int e = 0; e < 8; ++e) p[k][e] = 0.f;
;       } else { const u32x4 gp = *(const u32x4*)(Pu + (size_t)t * PW + 4096 + c0);
; #pragma unroll
;         for (int e = 0; e < 4; ++e) { p[k][2 * e] = __uint_as_float(gp[e] << 16); p[k][2 * e + 1] = __uint_as_float(gp[e] & 0xffff0000u); } } }
; #pragma unroll
;     for (int i = 0; i < 4; ++i) { const u32x4 gb = *(const u32x4*)(Pu + (size_t)(t0 + i) * PW + 3072 + c0); float r[8];
; #pragma unroll
;       for (int e = 0; e < 4; ++e) { r[2 * e] = __uint_as_float(gb[e] << 16) * (w0[2 * e] * p[i][2 * e] + w1[2 * e] * p[i + 1][2 * e] + w2[2 * e] * p[i + 2][2 * e]);
;         r[2 * e + 1] = __uint_as_float(gb[e] & 0xffff0000u) * (w0[2 * e + 1] * p[i][2 * e + 1] + w1[2 * e + 1] * p[i + 1][2 * e + 1] + w2[2 * e + 1] * p[i + 2][2 * e + 1]); }
;       u32x4 o; o.x = cvtpk(r[0], r[1]); o.y = cvtpk(r[2], r[3]); o.z = cvtpk(r[4], r[5]); o.w = cvtpk(r[6], r[7]);
;       *(u32x4*)(Mu + (size_t)(t0 + i) * DMODEL + 1024 + c0) = o; } }
.LBB0_378:
	s_ashr_i32 s81, s80, 31
	s_mul_i32 s1, s80, 0x3000
	s_mul_hi_i32 s0, s80, 0x3000
	s_add_u32 s1, s14, s1
	s_addc_u32 s0, s46, s0
	s_add_u32 s22, s1, 0x2000
	s_addc_u32 s23, s0, 0
	s_or_b32 s24, s80, 1
	s_ashr_i32 s25, s24, 31
	s_mul_i32 s7, s24, 0x3000
	s_mul_hi_i32 s6, s24, 0x3000
	s_add_u32 s8, s14, s7
	s_addc_u32 s9, s46, s6
	s_add_u32 s26, s8, 0x2000
	s_addc_u32 s27, s9, 0
	s_or_b32 s6, s80, 2
	s_ashr_i32 s7, s6, 31
	s_mul_i32 s29, s6, 0x3000
	s_mul_hi_i32 s28, s6, 0x3000
	s_add_u32 s59, s14, s29
	s_addc_u32 s60, s46, s28
	s_add_u32 s76, s59, 0x2000
	s_addc_u32 s77, s60, 0
	s_or_b32 vcc_lo, s80, 3
	s_ashr_i32 vcc_hi, vcc_lo, 31
	s_mul_i32 s29, vcc_lo, 0x3000
	s_mul_hi_i32 s28, vcc_lo, 0x3000
	s_add_u32 s40, s14, s29
	s_addc_u32 s41, s46, s28
	s_add_u32 s96, s40, 0x2000
	s_addc_u32 s97, s41, 0
	s_add_u32 s28, s1, 0x1800
	s_addc_u32 s29, s0, 0
	global_load_dwordx4 v[32:35], v144, s[22:23]
	global_load_dwordx4 v[36:39], v144, s[26:27]
	global_load_dwordx4 v[20:23], v144, s[76:77]
	global_load_dwordx4 v[64:67], v144, s[28:29]
	s_waitcnt vmcnt(8)
	v_mov_b32_e32 v56, v12
	s_waitcnt vmcnt(5)
	v_mov_b32_e32 v57, v24
	v_mov_b32_e32 v54, v13
	v_mov_b32_e32 v55, v25
	global_load_dwordx4 v[28:31], v144, s[96:97]
	v_mov_b32_e32 v52, v14
	v_mov_b32_e32 v53, v26
	v_mov_b32_e32 v50, v15
	v_mov_b32_e32 v51, v27
	v_mov_b32_e32 v48, v0
	s_waitcnt vmcnt(5)
	v_mov_b32_e32 v49, v4
	v_mov_b32_e32 v46, v1
	v_mov_b32_e32 v47, v5
	v_mov_b32_e32 v44, v2
	v_mov_b32_e32 v45, v6
	v_mov_b32_e32 v42, v3
	v_mov_b32_e32 v43, v7
	s_lshl_b64 s[0:1], s[80:81], 12
	s_add_u32 s0, s42, s0
	s_addc_u32 s1, s43, s1
	s_add_u32 s44, s8, 0x1800
	s_addc_u32 s45, s9, 0
	s_lshl_b64 s[8:9], s[24:25], 12
	s_add_u32 s78, s42, s8
	s_addc_u32 s79, s43, s9
	s_add_u32 s24, s59, 0x1800
	s_addc_u32 s25, s60, 0
	s_lshl_b64 s[6:7], s[6:7], 12
	s_add_u32 s6, s42, s6
	s_addc_u32 s7, s43, s7
	s_add_u32 s40, s40, 0x1800
	s_addc_u32 s41, s41, 0
	s_lshl_b64 s[8:9], vcc, 12
	s_add_u32 s8, s42, s8
	s_addc_u32 s9, s43, s9
	s_waitcnt vmcnt(1)
	v_lshlrev_b32_e32 v72, 16, v64
	v_and_b32_e32 v73, 0xffff0000, v64
	v_lshlrev_b32_e32 v64, 16, v32
	v_mov_b32_e32 v59, v64
	v_pk_mul_f32 v[58:59], v[56:57], v[58:59]
	v_lshlrev_b32_e32 v74, 16, v65
	v_fma_f32 v58, v16, v69, v58
	v_and_b32_e32 v75, 0xffff0000, v65
	v_lshlrev_b32_e32 v86, 16, v66
	v_and_b32_e32 v87, 0xffff0000, v66
	v_lshlrev_b32_e32 v85, 16, v67
	v_and_b32_e32 v83, 0xffff0000, v67
	v_lshlrev_b32_e32 v65, 16, v36
	v_add_f32_e32 v58, v58, v59
	v_mov_b32_e32 v66, v16
	v_mov_b32_e32 v67, v24
	v_mul_f32_e32 v72, v58, v72
	v_pk_mul_f32 v[58:59], v[66:67], v[64:65]
	s_nop 0
	v_fma_f32 v24, v12, v69, v58
	v_and_b32_e32 v58, 0xffff0000, v32
	v_mov_b32_e32 v69, v58
	v_pk_mul_f32 v[68:69], v[54:55], v[68:69]
	v_add_f32_e32 v84, v24, v59
	v_fma_f32 v24, v17, v61, v68
	v_add_f32_e32 v24, v24, v69
	v_mul_f32_e32 v24, v24, v73
	v_and_b32_e32 v59, 0xffff0000, v36
	v_cvt_pk_bf16_f32 v32, v72, v24
	v_mov_b32_e32 v24, v17
	v_pk_mul_f32 v[68:69], v[24:25], v[58:59]
	v_mov_b32_e32 v72, v18
	v_fma_f32 v36, v13, v61, v68
	v_lshlrev_b32_e32 v68, 16, v33
	v_mov_b32_e32 v61, v68
	v_pk_mul_f32 v[60:61], v[52:53], v[60:61]
	v_add_f32_e32 v88, v36, v69
	v_lshlrev_b32_e32 v69, 16, v37
	v_fma_f32 v36, v18, v71, v60
	v_mov_b32_e32 v73, v26
	v_add_f32_e32 v36, v36, v61
	v_pk_mul_f32 v[60:61], v[72:73], v[68:69]
	v_mul_f32_e32 v74, v36, v74
	v_fma_f32 v26, v14, v71, v60
	v_and_b32_e32 v60, 0xffff0000, v33
	v_mov_b32_e32 v71, v60
	v_add_f32_e32 v89, v26, v61
	v_and_b32_e32 v61, 0xffff0000, v37
	v_pk_mul_f32 v[36:37], v[50:51], v[70:71]
	v_lshlrev_b32_e32 v70, 16, v34
	v_fma_f32 v26, v19, v63, v36
	v_add_f32_e32 v26, v26, v37
	v_mul_f32_e32 v26, v26, v75
	v_cvt_pk_bf16_f32 v33, v74, v26
	v_mov_b32_e32 v26, v19
	v_pk_mul_f32 v[36:37], v[26:27], v[60:61]
	v_lshlrev_b32_e32 v71, 16, v38
	v_fma_f32 v36, v15, v63, v36
	v_mov_b32_e32 v63, v70
	v_add_f32_e32 v90, v36, v37
	v_pk_mul_f32 v[36:37], v[48:49], v[62:63]
	v_mov_b32_e32 v74, v8
	v_fma_f32 v36, v8, v77, v36
	v_add_f32_e32 v36, v36, v37
	v_mov_b32_e32 v75, v4
	v_mul_f32_e32 v86, v36, v86
	v_pk_mul_f32 v[36:37], v[74:75], v[70:71]
	v_and_b32_e32 v62, 0xffff0000, v34
	v_fma_f32 v4, v0, v77, v36
	v_mov_b32_e32 v77, v62
	v_add_f32_e32 v91, v4, v37
	v_pk_mul_f32 v[36:37], v[46:47], v[76:77]
	v_and_b32_e32 v63, 0xffff0000, v38
	v_fma_f32 v4, v9, v79, v36
	v_add_f32_e32 v4, v4, v37
	v_mul_f32_e32 v4, v4, v87
	v_cvt_pk_bf16_f32 v34, v86, v4
	v_mov_b32_e32 v4, v9
	v_pk_mul_f32 v[36:37], v[4:5], v[62:63]
	v_lshlrev_b32_e32 v76, 16, v35
	v_fma_f32 v36, v1, v79, v36
	v_mov_b32_e32 v79, v76
	v_add_f32_e32 v86, v36, v37
	v_pk_mul_f32 v[36:37], v[44:45], v[78:79]
	v_lshlrev_b32_e32 v77, 16, v39
	v_fma_f32 v36, v10, v81, v36
	v_add_f32_e32 v36, v36, v37
	v_mov_b32_e32 v78, v10
	v_mov_b32_e32 v79, v6
	v_mul_f32_e32 v85, v36, v85
	v_pk_mul_f32 v[36:37], v[78:79], v[76:77]
	s_nop 0
	v_fma_f32 v6, v2, v81, v36
	v_and_b32_e32 v36, 0xffff0000, v35
	v_mov_b32_e32 v81, v36
	v_add_f32_e32 v6, v6, v37
	v_and_b32_e32 v37, 0xffff0000, v39
	v_pk_mul_f32 v[38:39], v[42:43], v[80:81]
	s_nop 0
	v_fma_f32 v35, v11, v82, v38
	v_add_f32_e32 v35, v35, v39
	v_mul_f32_e32 v35, v35, v83
	v_cvt_pk_bf16_f32 v35, v85, v35
	global_store_dwordx4 v144, v[32:35], s[0:1] offset:2048 sc0 sc1
	global_load_dwordx4 v[32:35], v144, s[44:45]
	s_waitcnt vmcnt(0)
; __device__ __forceinline__ unsigned cvtpk(float lo, float hi) { unsigned r; asm volatile("v_cvt_pk_bf16_f32 %0, %1, %2" : "=v"(r) : "v"(lo), "v"(hi)); return r; }
; __device__ __forceinline__ void conv_item(const bf16* __restrict__ P, bf16* __restrict__ MIX, const float* __restrict__ cw, int it, int lane) {
;     ...
;   for (int j = 0; j < 2; ++j) { const int c0 = j * 512 + lane * 8;
;     float w0[8], w1[8], w2[8];
; #pragma unroll
;     for (int e = 0; e < 8; ++e) { w0[e] = cw[c0 + e]; w1[e] = cw[1024 + c0 + e]; w2[e] = cw[2048 + c0 + e]; }
;     float p[6][8];
; #pragma unroll
;     for (int k = 0; k < 6; ++k) { const int t = t0 - 2 + k;
;       if (k < 2 && first) {
; #pragma unroll
;         for (int e = 0; e < 8; ++e) p[k][e] = 0.f;
;       } else { const u32x4 gp = *(const u32x4*)(Pu + (size_t)t * PW + 4096 + c0);
; #pragma unroll
;         for (int e = 0; e < 4; ++e) { p[k][2 * e] = __uint_as_float(gp[e] << 16); p[k][2 * e + 1] = __uint_as_float(gp[e] & 0xffff0000u); } } }
; #pragma unroll
;     for (int i = 0; i < 4; ++i) { const u32x4 gb = *(const u32x4*)(Pu + (size_t)(t0 + i) * PW + 3072 + c0); float r[8];
; #pragma unroll
;       for (int e = 0; e < 4; ++e) { r[2 * e] = __uint_as_float(gb[e] << 16) * (w0[2 * e] * p[i][2 * e] + w1[2 * e] * p[i + 1][2 * e] + w2[2 * e] * p[i + 2][2 * e]);
;         r[2 * e + 1] = __uint_as_float(gb[e] & 0xffff0000u) * (w0[2 * e + 1] * p[i][2 * e + 1] + w1[2 * e + 1] * p[i + 1][2 * e + 1] + w2[2 * e + 1] * p[i + 2][2 * e + 1]); }
;       u32x4 o; o.x = cvtpk(r[0], r[1]); o.y = cvtpk(r[2], r[3]); o.z = cvtpk(r[4], r[5]); o.w = cvtpk(r[6], r[7]);
;       *(u32x4*)(Mu + (size_t)(t0 + i) * DMODEL + 1024 + c0) = o; } }
	v_lshlrev_b32_e32 v38, 16, v32
	v_and_b32_e32 v32, 0xffff0000, v32
	v_mul_f32_e32 v39, v88, v32
	v_lshlrev_b32_e32 v32, 16, v33
	v_mul_f32_e32 v80, v89, v32
	v_and_b32_e32 v32, 0xffff0000, v33
	v_mul_f32_e32 v81, v90, v32
	v_lshlrev_b32_e32 v32, 16, v34
	v_mul_f32_e32 v83, v91, v32
	v_and_b32_e32 v32, 0xffff0000, v34
	v_mul_f32_e32 v34, v86, v32
	v_lshlrev_b32_e32 v32, 16, v35
	v_mul_f32_e32 v38, v84, v38
	v_mul_f32_e32 v84, v6, v32
	v_mov_b32_e32 v6, v11
	v_pk_mul_f32 v[32:33], v[6:7], v[36:37]
	v_and_b32_e32 v35, 0xffff0000, v35
	v_fma_f32 v32, v3, v82, v32
	v_add_f32_e32 v32, v32, v33
	v_mul_f32_e32 v35, v32, v35
	v_cvt_pk_bf16_f32 v32, v38, v39
	v_cvt_pk_bf16_f32 v33, v80, v81
	v_cvt_pk_bf16_f32 v34, v83, v34
	v_cvt_pk_bf16_f32 v35, v84, v35
	global_store_dwordx4 v144, v[32:35], s[78:79] offset:2048 sc0 sc1
	global_load_dwordx4 v[32:35], v144, s[24:25]
	v_mov_b32_e32 v38, v64
	v_mov_b32_e32 v90, 0
	v_mov_b32_e32 v88, 0
	v_mov_b32_e32 v64, 0
	s_waitcnt vmcnt(0)
	v_lshlrev_b32_e32 v83, 16, v34
	v_and_b32_e32 v84, 0xffff0000, v34
	v_lshlrev_b32_e32 v34, 16, v20
	v_mov_b32_e32 v39, v34
	v_lshlrev_b32_e32 v80, 16, v32
	v_and_b32_e32 v81, 0xffff0000, v32
	v_lshlrev_b32_e32 v85, 16, v35
	v_and_b32_e32 v32, 0xffff0000, v35
	v_lshlrev_b32_e32 v35, 16, v28
	v_pk_mul_f32 v[38:39], v[56:57], v[38:39]
	v_pk_mul_f32 v[34:35], v[66:67], v[34:35]
	v_fma_f32 v16, v16, v65, v38
	v_add_f32_e32 v16, v16, v39
	v_fma_f32 v12, v12, v65, v34
	v_mul_f32_e32 v56, v16, v80
	v_add_f32_e32 v16, v12, v35
	v_and_b32_e32 v35, 0xffff0000, v28
	v_and_b32_e32 v34, 0xffff0000, v20
	v_mov_b32_e32 v38, v58
	v_mov_b32_e32 v39, v34
	v_pk_mul_f32 v[24:25], v[24:25], v[34:35]
	v_pk_mul_f32 v[38:39], v[54:55], v[38:39]
	v_fma_f32 v13, v13, v59, v24
	v_fma_f32 v12, v17, v59, v38
	v_add_f32_e32 v17, v13, v25
	v_lshlrev_b32_e32 v24, 16, v21
	v_lshlrev_b32_e32 v25, 16, v29
	v_mov_b32_e32 v35, v24
	v_pk_mul_f32 v[24:25], v[72:73], v[24:25]
	v_mov_b32_e32 v34, v68
	v_fma_f32 v14, v14, v69, v24
	v_and_b32_e32 v24, 0xffff0000, v21
	v_mov_b32_e32 v20, v60
	v_mov_b32_e32 v21, v24
	v_pk_mul_f32 v[34:35], v[52:53], v[34:35]
	v_pk_mul_f32 v[20:21], v[50:51], v[20:21]
	v_fma_f32 v13, v18, v69, v34
	v_add_f32_e32 v18, v14, v25
	v_fma_f32 v14, v19, v61, v20
	v_lshlrev_b32_e32 v82, 16, v33
	v_and_b32_e32 v33, 0xffff0000, v33
	v_add_f32_e32 v12, v12, v39
	v_add_f32_e32 v13, v13, v35
	v_and_b32_e32 v25, 0xffff0000, v29
	v_add_f32_e32 v14, v14, v21
	v_mul_f32_e32 v12, v12, v81
	v_mul_f32_e32 v13, v13, v82
	v_mul_f32_e32 v14, v14, v33
	v_pk_mul_f32 v[20:21], v[26:27], v[24:25]
	v_cvt_pk_bf16_f32 v12, v56, v12
	v_cvt_pk_bf16_f32 v13, v13, v14
	v_mov_b32_e32 v80, 0
	v_fma_f32 v14, v15, v61, v20
	v_add_f32_e32 v19, v14, v21
	v_lshlrev_b32_e32 v14, 16, v22
	v_lshlrev_b32_e32 v15, 16, v30
	v_mov_b32_e32 v20, v70
	v_mov_b32_e32 v21, v14
	v_pk_mul_f32 v[20:21], v[48:49], v[20:21]
	v_pk_mul_f32 v[14:15], v[74:75], v[14:15]
	v_fma_f32 v8, v8, v71, v20
	v_fma_f32 v0, v0, v71, v14
	v_and_b32_e32 v20, 0xffff0000, v22
	v_add_f32_e32 v24, v0, v15
	v_mov_b32_e32 v14, v62
	v_mov_b32_e32 v15, v20
	v_pk_mul_f32 v[14:15], v[46:47], v[14:15]
	v_add_f32_e32 v8, v8, v21
	v_fma_f32 v0, v9, v63, v14
	v_and_b32_e32 v21, 0xffff0000, v30
	v_add_f32_e32 v0, v0, v15
	v_mul_f32_e32 v0, v0, v84
	v_pk_mul_f32 v[4:5], v[4:5], v[20:21]
	v_mul_f32_e32 v8, v8, v83
	v_cvt_pk_bf16_f32 v14, v8, v0
	v_fma_f32 v0, v1, v63, v4
	v_add_f32_e32 v20, v0, v5
	v_lshlrev_b32_e32 v0, 16, v23
	v_lshlrev_b32_e32 v1, 16, v31
	v_mov_b32_e32 v4, v76
	v_mov_b32_e32 v5, v0
	v_pk_mul_f32 v[4:5], v[44:45], v[4:5]
	v_pk_mul_f32 v[0:1], v[78:79], v[0:1]
	v_fma_f32 v4, v10, v77, v4
	v_fma_f32 v0, v2, v77, v0
	v_add_f32_e32 v4, v4, v5
	v_add_f32_e32 v2, v0, v1
	v_and_b32_e32 v0, 0xffff0000, v23
	v_mul_f32_e32 v8, v4, v85
	v_mov_b32_e32 v4, v36
	v_mov_b32_e32 v5, v0
	v_pk_mul_f32 v[4:5], v[42:43], v[4:5]
	v_and_b32_e32 v1, 0xffff0000, v31
	v_fma_f32 v4, v11, v37, v4
	v_add_f32_e32 v4, v4, v5
	v_mul_f32_e32 v4, v4, v32
	v_cvt_pk_bf16_f32 v15, v8, v4
	global_load_dwordx4 v[8:11], v144, s[40:41]
	v_pk_mul_f32 v[0:1], v[6:7], v[0:1]
	global_store_dwordx4 v144, v[12:15], s[6:7] offset:2048 sc0 sc1
	v_fma_f32 v0, v3, v37, v0
	v_add_co_u32_e32 v6, vcc, 0x1000, v40
	v_add_f32_e32 v0, v0, v1
	s_nop 0
	v_addc_co_u32_e32 v7, vcc, 0, v41, vcc
	v_mov_b32_e32 v84, 0
	v_mov_b32_e32 v68, 0
	v_mov_b32_e32 v76, 0
	v_mov_b32_e32 v66, 0
	v_mov_b32_e32 v74, 0
	s_waitcnt vmcnt(1)
	v_lshlrev_b32_e32 v12, 16, v10
	v_and_b32_e32 v10, 0xffff0000, v10
	v_lshlrev_b32_e32 v13, 16, v11
	v_lshlrev_b32_e32 v4, 16, v8
	v_and_b32_e32 v5, 0xffff0000, v8
	v_lshlrev_b32_e32 v8, 16, v9
	v_and_b32_e32 v9, 0xffff0000, v9
	v_mul_f32_e32 v10, v20, v10
	v_mul_f32_e32 v13, v2, v13
	v_and_b32_e32 v2, 0xffff0000, v11
	v_mul_f32_e32 v4, v16, v4
	v_mul_f32_e32 v5, v17, v5
	v_mul_f32_e32 v8, v18, v8
	v_mul_f32_e32 v9, v19, v9
	v_mul_f32_e32 v12, v24, v12
	v_mul_f32_e32 v3, v0, v2
	v_cvt_pk_bf16_f32 v0, v4, v5
	v_cvt_pk_bf16_f32 v1, v8, v9
	v_cvt_pk_bf16_f32 v2, v12, v10
	v_add_co_u32_e32 v10, vcc, 0x2000, v40
	v_cvt_pk_bf16_f32 v3, v13, v3
	global_store_dwordx4 v144, v[0:3], s[8:9] offset:2048 sc0 sc1
	v_lshl_add_u64 v[4:5], v[40:41], 0, s[82:83]
	v_lshl_add_u64 v[8:9], v[40:41], 0, s[86:87]
	v_addc_co_u32_e32 v11, vcc, 0, v41, vcc
	global_load_dwordx4 v[0:3], v[40:41], off offset:2064
	global_load_dwordx4 v[12:15], v[40:41], off offset:2048
	global_load_dwordx4 v[16:19], v[6:7], off offset:2048
	s_nop 0
	global_load_dwordx4 v[4:7], v[4:5], off offset:16
	s_nop 0
	global_load_dwordx4 v[28:31], v[10:11], off offset:2048
	s_nop 0
	global_load_dwordx4 v[8:11], v[8:9], off offset:16
	v_or_b32_e32 v20, 0x200, v113
	s_and_b64 vcc, exec, s[38:39]
	v_lshlrev_b32_e32 v42, 1, v20
	s_cbranch_vccnz .LBB0_380
	s_add_u32 s60, s14, s56
	s_addc_u32 s61, s46, s34
	v_mov_b32_e32 v43, v145
	v_lshl_add_u64 v[20:21], s[60:61], 0, v[42:43]
	v_add_co_u32_e32 v20, vcc, 0x2000, v20
	s_nop 1
	v_addc_co_u32_e32 v21, vcc, 0, v21, vcc
	global_load_dwordx4 v[20:23], v[20:21], off
	s_waitcnt vmcnt(0)
	v_lshlrev_b32_e32 v64, 16, v20
	v_and_b32_e32 v74, 0xffff0000, v20
	v_lshlrev_b32_e32 v66, 16, v21
	v_and_b32_e32 v76, 0xffff0000, v21
	v_lshlrev_b32_e32 v68, 16, v22
	v_and_b32_e32 v80, 0xffff0000, v22
	v_lshlrev_b32_e32 v84, 16, v23
	v_and_b32_e32 v88, 0xffff0000, v23

; #define PG8_STAGE(bufoff, gbase, voff) do { _Pragma("unroll") for (int _i = 0; _i < 2; ++_i) \
;         __builtin_amdgcn_global_load_lds((const unsigned*)((const char*)(gbase) + (voff)[_i]), (PG8_LAS unsigned*)(lds + (bufoff) + ldsw + _i * 8192), 16, 0, 0); } while (0)
; #define PG8_LDA(dst, b, h) do { _Pragma("unroll") for (int m = 0; m < 4; ++m) _Pragma("unroll") for (int k = 0; k < 2; ++k) dst[m][k] = *(const PG8_LAS bf16x8*)(lds + PG8_SA(b, h) + aoff + m * 2048 + k * 1024); } while (0)
; #define PG8_LDB(dst, b, h) do { _Pragma("unroll") for (int n = 0; n < 2; ++n) _Pragma("unroll") for (int k = 0; k < 2; ++k) dst[n][k] = *(const PG8_LAS bf16x8*)(lds + PG8_SB(b, h) + boff + n * 2048 + k * 1024); } while (0)
; #define PG8_MMA(ai, bj, At, Bt) do { __builtin_amdgcn_s_setprio(1); _Pragma("unroll") for (int m = 0; m < 4; ++m) _Pragma("unroll") for (int n = 0; n < 2; ++n) _Pragma("unroll") for (int k = 0; k < 2; ++k) \
;         acc[ai][bj][m][n] = __builtin_amdgcn_mfma_f32_16x16x32_bf16(Bt[n][k], At[m][k], acc[ai][bj][m][n], 0, 0, 0); __builtin_amdgcn_s_setprio(0); } while (0)
; #define PG8_WAIT_V(n) asm volatile("s_waitcnt vmcnt(" #n ")" ::: "memory")
; #define PG8_WAIT_L(n) asm volatile("s_waitcnt lgkmcnt(" #n ")" ::: "memory")
; #define PG8_BAR __builtin_amdgcn_s_barrier()
; #define PG8_SCHED __builtin_amdgcn_sched_barrier(0)
; template <class Epi, class Sched, bool ALIGN_EPI = false, bool SP2 = false>
; __device__ __forceinline__ void gemm_phase(PG8_LAS unsigned char* lds, const Gemm g, const Sched& S, const Epi& E) {
;     ...
;             PG8_LDB(B0, 0, 0); PG8_LDB(B1, 0, 1); PG8_SCHED; PG8_LDA(At, 0, 0); PG8_STAGE(PG8_SA(1, 1), a1 + hstepA, voffA);
;             PG8_WAIT_V(8); PG8_WAIT_L(0); PG8_BAR; PG8_MMA(0, 0, At, B0); PG8_MMA(0, 1, At, B1); PG8_BAR; PG8_SCHED;
;             PG8_LDA(At, 0, 1); PG8_STAGE(PG8_SB(0, 0), b2, voffB); PG8_STAGE(PG8_SB(0, 1), b2 + hstepB, voffB); PG8_STAGE(PG8_SA(0, 0), a2, voffA);
;             PG8_WAIT_V(8); PG8_WAIT_L(0); PG8_BAR; PG8_MMA(1, 0, At, B0); PG8_MMA(1, 1, At, B1); PG8_BAR; PG8_SCHED;
.LBB0_458:
	s_add_u32 s6, s0, 0xfff80080
	s_addc_u32 s7, s1, -1
	s_add_i32 s41, 0, 0x10000
	s_cmp_eq_u32 s40, 28
	s_cselect_b32 s9, s25, s7
	s_cselect_b32 s8, s26, s6
	v_add_u32_e32 v144, s41, v166
	s_cselect_b32 s7, s27, s23
	s_cselect_b32 s6, s31, s22
	s_add_i32 s43, 0, 0x14000
	ds_read_b128 v[140:143], v144
	ds_read_b128 v[160:163], v144 offset:1024
	ds_read_b128 v[170:173], v144 offset:2048
	ds_read_b128 v[198:201], v144 offset:3072
	v_add_u32_e32 v144, s43, v166
	ds_read_b128 v[202:205], v144
	ds_read_b128 v[206:209], v144 offset:1024
	ds_read_b128 v[210:213], v144 offset:2048
	ds_read_b128 v[214:217], v144 offset:3072
	v_lshl_add_u64 v[174:175], s[0:1], 0, v[136:137]
	s_add_i32 m0, s53, 0xc000
	ds_read_b128 v[218:221], v168
	ds_read_b128 v[222:225], v168 offset:1024
	ds_read_b128 v[226:229], v168 offset:2048
	ds_read_b128 v[230:233], v168 offset:3072
	ds_read_b128 v[234:237], v168 offset:4096
	ds_read_b128 v[238:241], v168 offset:5120
	ds_read_b128 v[242:245], v168 offset:6144
	ds_read_b128 v[246:249], v168 offset:7168
	global_load_lds_dwordx4 v[174:175], off
	v_lshl_add_u64 v[174:175], s[0:1], 0, v[138:139]
	s_add_i32 m0, s53, 0xe000
	s_nop 0
	global_load_lds_dwordx4 v[174:175], off
	s_waitcnt vmcnt(8)
	s_waitcnt lgkmcnt(0)
	s_barrier
	s_setprio 1
	s_waitcnt lgkmcnt(0)
	v_mfma_f32_16x16x32_bf16 v[8:11], v[140:143], v[218:221], v[8:11]
	v_mfma_f32_16x16x32_bf16 v[12:15], v[170:173], v[218:221], v[12:15]
	v_mfma_f32_16x16x32_bf16 v[4:7], v[140:143], v[226:229], v[4:7]
	v_mfma_f32_16x16x32_bf16 v[0:3], v[170:173], v[226:229], v[0:3]
	v_mfma_f32_16x16x32_bf16 v[16:19], v[140:143], v[234:237], v[16:19]
	v_mfma_f32_16x16x32_bf16 v[36:39], v[170:173], v[234:237], v[36:39]
	v_mfma_f32_16x16x32_bf16 v[44:47], v[140:143], v[242:245], v[44:47]
	v_mfma_f32_16x16x32_bf16 v[40:43], v[170:173], v[242:245], v[40:43]
	v_mfma_f32_16x16x32_bf16 v[8:11], v[160:163], v[222:225], v[8:11]
	v_mfma_f32_16x16x32_bf16 v[12:15], v[198:201], v[222:225], v[12:15]
	v_mfma_f32_16x16x32_bf16 v[4:7], v[160:163], v[230:233], v[4:7]
	v_mfma_f32_16x16x32_bf16 v[0:3], v[198:201], v[230:233], v[0:3]
	v_mfma_f32_16x16x32_bf16 v[16:19], v[160:163], v[238:241], v[16:19]
	v_mfma_f32_16x16x32_bf16 v[36:39], v[198:201], v[238:241], v[36:39]
	v_mfma_f32_16x16x32_bf16 v[44:47], v[160:163], v[246:249], v[44:47]
	v_mfma_f32_16x16x32_bf16 v[40:43], v[198:201], v[246:249], v[40:43]
	s_setprio 0
	s_setprio 1
	v_mfma_f32_16x16x32_bf16 v[28:31], v[202:205], v[218:221], v[28:31]
	v_mfma_f32_16x16x32_bf16 v[32:35], v[210:213], v[218:221], v[32:35]
	v_mfma_f32_16x16x32_bf16 v[20:23], v[202:205], v[226:229], v[20:23]
	v_mfma_f32_16x16x32_bf16 v[24:27], v[210:213], v[226:229], v[24:27]
	v_mfma_f32_16x16x32_bf16 v[48:51], v[202:205], v[234:237], v[48:51]
	v_mfma_f32_16x16x32_bf16 v[56:59], v[210:213], v[234:237], v[56:59]
	v_mfma_f32_16x16x32_bf16 v[52:55], v[202:205], v[242:245], v[52:55]
	v_mfma_f32_16x16x32_bf16 v[76:79], v[210:213], v[242:245], v[76:79]
	v_mfma_f32_16x16x32_bf16 v[28:31], v[206:209], v[222:225], v[28:31]
	v_mfma_f32_16x16x32_bf16 v[32:35], v[214:217], v[222:225], v[32:35]
	v_mfma_f32_16x16x32_bf16 v[20:23], v[206:209], v[230:233], v[20:23]
	v_mfma_f32_16x16x32_bf16 v[24:27], v[214:217], v[230:233], v[24:27]
	v_mfma_f32_16x16x32_bf16 v[48:51], v[206:209], v[238:241], v[48:51]
	v_mfma_f32_16x16x32_bf16 v[56:59], v[214:217], v[238:241], v[56:59]
	v_mfma_f32_16x16x32_bf16 v[52:55], v[206:209], v[246:249], v[52:55]
	v_mfma_f32_16x16x32_bf16 v[76:79], v[214:217], v[246:249], v[76:79]
	s_setprio 0
	s_barrier
	s_add_i32 s41, s41, s44
	v_lshl_add_u64 v[174:175], s[6:7], 0, v[130:131]
	s_mov_b32 m0, s41
	ds_read_b128 v[218:221], v168 offset:16384
	ds_read_b128 v[222:225], v168 offset:17408
	ds_read_b128 v[226:229], v168 offset:18432
	ds_read_b128 v[230:233], v168 offset:19456
	ds_read_b128 v[234:237], v168 offset:20480
	ds_read_b128 v[238:241], v168 offset:21504
	ds_read_b128 v[242:245], v168 offset:22528
	ds_read_b128 v[246:249], v168 offset:23552
	global_load_lds_dwordx4 v[174:175], off
	s_add_i32 m0, s41, 0x2000
	s_add_u32 s60, s6, 0x4000
	v_lshl_add_u64 v[174:175], s[6:7], 0, v[134:135]
	s_addc_u32 s61, s7, 0
	s_add_i32 s41, s43, s44
	global_load_lds_dwordx4 v[174:175], off
	v_lshl_add_u64 v[174:175], s[60:61], 0, v[130:131]
	s_mov_b32 m0, s41
	v_lshl_add_u64 v[178:179], s[8:9], 0, v[132:133]
	global_load_lds_dwordx4 v[174:175], off
	v_lshl_add_u64 v[174:175], s[60:61], 0, v[134:135]
	s_add_i32 m0, s41, 0x2000
	s_nop 0
	global_load_lds_dwordx4 v[174:175], off
	v_lshl_add_u64 v[174:175], s[8:9], 0, v[128:129]
	s_mov_b32 m0, s53
	s_nop 0
	global_load_lds_dwordx4 v[174:175], off
	s_mov_b32 m0, s54
	s_nop 0
	global_load_lds_dwordx4 v[178:179], off
	s_waitcnt vmcnt(8)
	s_waitcnt lgkmcnt(0)
	s_barrier
; #define PG8_STAGE(bufoff, gbase, voff) do { _Pragma("unroll") for (int _i = 0; _i < 2; ++_i) \
;         __builtin_amdgcn_global_load_lds((const unsigned*)((const char*)(gbase) + (voff)[_i]), (PG8_LAS unsigned*)(lds + (bufoff) + ldsw + _i * 8192), 16, 0, 0); } while (0)
; #define PG8_LDA(dst, b, h) do { _Pragma("unroll") for (int m = 0; m < 4; ++m) _Pragma("unroll") for (int k = 0; k < 2; ++k) dst[m][k] = *(const PG8_LAS bf16x8*)(lds + PG8_SA(b, h) + aoff + m * 2048 + k * 1024); } while (0)
; #define PG8_LDB(dst, b, h) do { _Pragma("unroll") for (int n = 0; n < 2; ++n) _Pragma("unroll") for (int k = 0; k < 2; ++k) dst[n][k] = *(const PG8_LAS bf16x8*)(lds + PG8_SB(b, h) + boff + n * 2048 + k * 1024); } while (0)
; #define PG8_MMA(ai, bj, At, Bt) do { __builtin_amdgcn_s_setprio(1); _Pragma("unroll") for (int m = 0; m < 4; ++m) _Pragma("unroll") for (int n = 0; n < 2; ++n) _Pragma("unroll") for (int k = 0; k < 2; ++k) \
;         acc[ai][bj][m][n] = __builtin_amdgcn_mfma_f32_16x16x32_bf16(Bt[n][k], At[m][k], acc[ai][bj][m][n], 0, 0, 0); __builtin_amdgcn_s_setprio(0); } while (0)
; #define PG8_WAIT_V(n) asm volatile("s_waitcnt vmcnt(" #n ")" ::: "memory")
; #define PG8_WAIT_L(n) asm volatile("s_waitcnt lgkmcnt(" #n ")" ::: "memory")
; #define PG8_BAR __builtin_amdgcn_s_barrier()
; #define PG8_SCHED __builtin_amdgcn_sched_barrier(0)
; template <class Epi, class Sched, bool ALIGN_EPI = false, bool SP2 = false>
; __device__ __forceinline__ void gemm_phase(PG8_LAS unsigned char* lds, const Gemm g, const Sched& S, const Epi& E) {
;     ...
;             PG8_WAIT_V(8); PG8_WAIT_L(0); PG8_BAR; PG8_MMA(1, 0, At, B0); PG8_MMA(1, 1, At, B1); PG8_BAR; PG8_SCHED;
;             PG8_LDB(B0, 1, 0); PG8_LDB(B1, 1, 1); PG8_SCHED; PG8_LDA(At, 1, 0); PG8_STAGE(PG8_SA(0, 1), a2 + hstepA, voffA);
;             PG8_WAIT_V(8); PG8_WAIT_L(0); PG8_BAR; PG8_MMA(0, 0, At, B0); PG8_MMA(0, 1, At, B1); PG8_BAR; PG8_SCHED;
;             PG8_LDA(At, 1, 1); PG8_STAGE(PG8_SB(1, 0), b3, voffB); PG8_STAGE(PG8_SB(1, 1), b3 + hstepB, voffB); PG8_STAGE(PG8_SA(1, 0), a3, voffA);
	s_setprio 1
	s_waitcnt lgkmcnt(0)
	v_mfma_f32_16x16x32_bf16 v[64:67], v[140:143], v[218:221], v[64:67]
	v_mfma_f32_16x16x32_bf16 v[84:87], v[170:173], v[218:221], v[84:87]
	v_mfma_f32_16x16x32_bf16 v[60:63], v[140:143], v[226:229], v[60:63]
	v_mfma_f32_16x16x32_bf16 v[80:83], v[170:173], v[226:229], v[80:83]
	v_mfma_f32_16x16x32_bf16 v[68:71], v[140:143], v[234:237], v[68:71]
	v_mfma_f32_16x16x32_bf16 v[88:91], v[170:173], v[234:237], v[88:91]
	v_mfma_f32_16x16x32_bf16 v[72:75], v[140:143], v[242:245], v[72:75]
	v_mfma_f32_16x16x32_bf16 v[92:95], v[170:173], v[242:245], v[92:95]
	v_mfma_f32_16x16x32_bf16 v[64:67], v[160:163], v[222:225], v[64:67]
	v_mfma_f32_16x16x32_bf16 v[84:87], v[198:201], v[222:225], v[84:87]
	v_mfma_f32_16x16x32_bf16 v[60:63], v[160:163], v[230:233], v[60:63]
	v_mfma_f32_16x16x32_bf16 v[80:83], v[198:201], v[230:233], v[80:83]
	v_mfma_f32_16x16x32_bf16 v[68:71], v[160:163], v[238:241], v[68:71]
	v_mfma_f32_16x16x32_bf16 v[88:91], v[198:201], v[238:241], v[88:91]
	v_mfma_f32_16x16x32_bf16 v[72:75], v[160:163], v[246:249], v[72:75]
	v_mfma_f32_16x16x32_bf16 v[92:95], v[198:201], v[246:249], v[92:95]
	s_setprio 0
	s_setprio 1
	v_mfma_f32_16x16x32_bf16 v[100:103], v[202:205], v[218:221], v[100:103]
	v_mfma_f32_16x16x32_bf16 v[120:123], v[210:213], v[218:221], v[120:123]
	v_mfma_f32_16x16x32_bf16 v[96:99], v[202:205], v[226:229], v[96:99]
	v_mfma_f32_16x16x32_bf16 v[112:115], v[210:213], v[226:229], v[112:115]
	v_mfma_f32_16x16x32_bf16 v[104:107], v[202:205], v[234:237], v[104:107]
	v_mfma_f32_16x16x32_bf16 v[116:119], v[210:213], v[234:237], v[116:119]
	v_mfma_f32_16x16x32_bf16 v[108:111], v[202:205], v[242:245], v[108:111]
	v_mfma_f32_16x16x32_bf16 v[124:127], v[210:213], v[242:245], v[124:127]
	v_mfma_f32_16x16x32_bf16 v[100:103], v[206:209], v[222:225], v[100:103]
	v_mfma_f32_16x16x32_bf16 v[120:123], v[214:217], v[222:225], v[120:123]
	v_mfma_f32_16x16x32_bf16 v[96:99], v[206:209], v[230:233], v[96:99]
	v_mfma_f32_16x16x32_bf16 v[112:115], v[214:217], v[230:233], v[112:115]
	v_mfma_f32_16x16x32_bf16 v[104:107], v[206:209], v[238:241], v[104:107]
	v_mfma_f32_16x16x32_bf16 v[116:119], v[214:217], v[238:241], v[116:119]
	v_mfma_f32_16x16x32_bf16 v[108:111], v[206:209], v[246:249], v[108:111]
	v_mfma_f32_16x16x32_bf16 v[124:127], v[214:217], v[246:249], v[124:127]
	s_setprio 0
	s_barrier
	s_add_i32 s41, 0, 0x18000
	v_add_u32_e32 v144, s41, v166
	s_add_i32 s43, 0, 0x1c000
	ds_read_b128 v[140:143], v144
	ds_read_b128 v[160:163], v144 offset:1024
	ds_read_b128 v[170:173], v144 offset:2048
	ds_read_b128 v[198:201], v144 offset:3072
	v_add_u32_e32 v144, s43, v166
	ds_read_b128 v[202:205], v144
	ds_read_b128 v[206:209], v144 offset:1024
	ds_read_b128 v[210:213], v144 offset:2048
	ds_read_b128 v[214:217], v144 offset:3072
	s_add_u32 s8, s8, 0x80000
	s_addc_u32 s9, s9, 0
	s_mov_b32 m0, s55
	v_lshl_add_u64 v[180:181], s[8:9], 0, v[128:129]
	ds_read_b128 v[218:221], v168 offset:32768
	ds_read_b128 v[222:225], v168 offset:33792
	ds_read_b128 v[226:229], v168 offset:34816
	ds_read_b128 v[230:233], v168 offset:35840
	ds_read_b128 v[234:237], v168 offset:36864
	ds_read_b128 v[238:241], v168 offset:37888
	ds_read_b128 v[242:245], v168 offset:38912
	ds_read_b128 v[246:249], v168 offset:39936
	global_load_lds_dwordx4 v[180:181], off
	v_lshl_add_u64 v[180:181], s[8:9], 0, v[132:133]
	s_mov_b32 m0, s66
	s_nop 0
	global_load_lds_dwordx4 v[180:181], off
	s_waitcnt vmcnt(8)
	s_waitcnt lgkmcnt(0)
	s_barrier
	s_setprio 1
	s_waitcnt lgkmcnt(0)
	v_mfma_f32_16x16x32_bf16 v[8:11], v[140:143], v[218:221], v[8:11]
	v_mfma_f32_16x16x32_bf16 v[12:15], v[170:173], v[218:221], v[12:15]
	v_mfma_f32_16x16x32_bf16 v[4:7], v[140:143], v[226:229], v[4:7]
	v_mfma_f32_16x16x32_bf16 v[0:3], v[170:173], v[226:229], v[0:3]
	v_mfma_f32_16x16x32_bf16 v[16:19], v[140:143], v[234:237], v[16:19]
	v_mfma_f32_16x16x32_bf16 v[36:39], v[170:173], v[234:237], v[36:39]
	v_mfma_f32_16x16x32_bf16 v[44:47], v[140:143], v[242:245], v[44:47]
	v_mfma_f32_16x16x32_bf16 v[40:43], v[170:173], v[242:245], v[40:43]
	v_mfma_f32_16x16x32_bf16 v[8:11], v[160:163], v[222:225], v[8:11]
	v_mfma_f32_16x16x32_bf16 v[12:15], v[198:201], v[222:225], v[12:15]
	v_mfma_f32_16x16x32_bf16 v[4:7], v[160:163], v[230:233], v[4:7]
	v_mfma_f32_16x16x32_bf16 v[0:3], v[198:201], v[230:233], v[0:3]
	v_mfma_f32_16x16x32_bf16 v[16:19], v[160:163], v[238:241], v[16:19]
	v_mfma_f32_16x16x32_bf16 v[36:39], v[198:201], v[238:241], v[36:39]
	v_mfma_f32_16x16x32_bf16 v[44:47], v[160:163], v[246:249], v[44:47]
	v_mfma_f32_16x16x32_bf16 v[40:43], v[198:201], v[246:249], v[40:43]
	s_setprio 0
	s_setprio 1
	v_mfma_f32_16x16x32_bf16 v[28:31], v[202:205], v[218:221], v[28:31]
	v_mfma_f32_16x16x32_bf16 v[32:35], v[210:213], v[218:221], v[32:35]
	v_mfma_f32_16x16x32_bf16 v[20:23], v[202:205], v[226:229], v[20:23]
	v_mfma_f32_16x16x32_bf16 v[24:27], v[210:213], v[226:229], v[24:27]
	v_mfma_f32_16x16x32_bf16 v[48:51], v[202:205], v[234:237], v[48:51]
	v_mfma_f32_16x16x32_bf16 v[56:59], v[210:213], v[234:237], v[56:59]
	v_mfma_f32_16x16x32_bf16 v[52:55], v[202:205], v[242:245], v[52:55]
	v_mfma_f32_16x16x32_bf16 v[76:79], v[210:213], v[242:245], v[76:79]
	v_mfma_f32_16x16x32_bf16 v[28:31], v[206:209], v[222:225], v[28:31]
	v_mfma_f32_16x16x32_bf16 v[32:35], v[214:217], v[222:225], v[32:35]
	v_mfma_f32_16x16x32_bf16 v[20:23], v[206:209], v[230:233], v[20:23]
	v_mfma_f32_16x16x32_bf16 v[24:27], v[214:217], v[230:233], v[24:27]
	v_mfma_f32_16x16x32_bf16 v[48:51], v[206:209], v[238:241], v[48:51]
	v_mfma_f32_16x16x32_bf16 v[56:59], v[214:217], v[238:241], v[56:59]
	v_mfma_f32_16x16x32_bf16 v[52:55], v[206:209], v[246:249], v[52:55]
	v_mfma_f32_16x16x32_bf16 v[76:79], v[214:217], v[246:249], v[76:79]
	s_setprio 0
	s_barrier
; __device__ __forceinline__ unsigned cvt_pk_bf16(float lo, float hi) { unsigned r; asm volatile("v_cvt_pk_bf16_f32 %0, %1, %2" : "=v"(r) : "v"(lo), "v"(hi)); return r; }
;     __device__ __forceinline__ size_t xb_off(int row, int col) const { return ((size_t)(row >> 8) * (ldc >> 6) + (col >> 6)) * (256 * 64) + blk_off(row & 255, col & 63); }
; #define PG8_STAGE(bufoff, gbase, voff) do { _Pragma("unroll") for (int _i = 0; _i < 2; ++_i) \
;         __builtin_amdgcn_global_load_lds((const unsigned*)((const char*)(gbase) + (voff)[_i]), (PG8_LAS unsigned*)(lds + (bufoff) + ldsw + _i * 8192), 16, 0, 0); } while (0)
; #define PG8_LDA(dst, b, h) do { _Pragma("unroll") for (int m = 0; m < 4; ++m) _Pragma("unroll") for (int k = 0; k < 2; ++k) dst[m][k] = *(const PG8_LAS bf16x8*)(lds + PG8_SA(b, h) + aoff + m * 2048 + k * 1024); } while (0)
;     __device__ __forceinline__ void operator()(const f32x4 (&acc)[2][2][4][2], const State&, const Unit& u, int wr, int wc, int fr, int fq) const {
;     ...
;             for (int ai = 0; ai < 2; ++ai)
; #pragma unroll
;                 for (int m = 0; m < 4; ++m) { const int row = row0 + ai * HALF + m * 16; const size_t off = (size_t)row * ldc + col0; float ss = 0.f;
; #pragma unroll
;                     for (int bj = 0; bj < 2; ++bj) { const f32x4 v0 = acc[ai][bj][m][0], v1 = acc[ai][bj][m][1];
;                         u32x4 w; w.x = cvt_pk_bf16(v0[0], v0[1]); w.y = cvt_pk_bf16(v0[2], v0[3]); w.z = cvt_pk_bf16(v1[0], v1[1]); w.w = cvt_pk_bf16(v1[2], v1[3]);
;                         *(u32x4*)(xb + xb_off(row, col0 + bj * HALF)) = w;
;                         ss += ((v0[0] * v0[0] + v0[1] * v0[1]) + (v0[2] * v0[2] + v0[3] * v0[3])) + ((v1[0] * v1[0] + v1[1] * v1[1]) + (v1[2] * v1[2] + v1[3] * v1[3])); }
;                     ss += __shfl_xor(ss, 16); ss += __shfl_xor(ss, 32);
;                     if (fq == 0) ssq[(size_t)row * 32 + u.pn * 4 + wc] = ss; }
; template <class Epi, class Sched, bool ALIGN_EPI = false, bool SP2 = false>
; __device__ __forceinline__ void gemm_phase(PG8_LAS unsigned char* lds, const Gemm g, const Sched& S, const Epi& E) {
;     ...
;             PG8_LDA(At, 1, 1); PG8_STAGE(PG8_SB(1, 0), b3, voffB); PG8_STAGE(PG8_SB(1, 1), b3 + hstepB, voffB); PG8_STAGE(PG8_SA(1, 0), a3, voffA);
;             PG8_WAIT_V(8); PG8_WAIT_L(0); PG8_BAR; PG8_MMA(1, 0, At, B0); PG8_MMA(1, 1, At, B1); PG8_BAR; PG8_SCHED;
	s_add_u32 s8, s6, 0x8000
	s_addc_u32 s9, s7, 0
	s_add_i32 s41, s41, s44
	v_lshl_add_u64 v[180:181], s[8:9], 0, v[130:131]
	s_mov_b32 m0, s41
	ds_read_b128 v[218:221], v168 offset:49152
	ds_read_b128 v[222:225], v168 offset:50176
	ds_read_b128 v[226:229], v168 offset:51200
	ds_read_b128 v[230:233], v168 offset:52224
	ds_read_b128 v[234:237], v168 offset:53248
	ds_read_b128 v[238:241], v168 offset:54272
	ds_read_b128 v[242:245], v168 offset:55296
	ds_read_b128 v[246:249], v168 offset:56320
	global_load_lds_dwordx4 v[180:181], off
	s_add_i32 m0, s41, 0x2000
	s_add_u32 s6, s6, 0xc000
	v_lshl_add_u64 v[180:181], s[8:9], 0, v[134:135]
	s_addc_u32 s7, s7, 0
	s_add_i32 s8, s43, s44
	global_load_lds_dwordx4 v[180:181], off
	v_lshl_add_u64 v[180:181], s[6:7], 0, v[130:131]
	s_mov_b32 m0, s8
	v_lshl_add_u64 v[174:175], v[174:175], 0, s[94:95]
	global_load_lds_dwordx4 v[180:181], off
	v_lshl_add_u64 v[180:181], s[6:7], 0, v[134:135]
	s_add_i32 m0, s8, 0x2000
	s_nop 0
	global_load_lds_dwordx4 v[180:181], off
	s_mov_b32 m0, s67
	s_nop 0
	global_load_lds_dwordx4 v[174:175], off
	v_lshl_add_u64 v[174:175], v[178:179], 0, s[94:95]
	s_mov_b32 m0, s68
	s_nop 0
	global_load_lds_dwordx4 v[174:175], off
	s_waitcnt vmcnt(8)
	s_waitcnt lgkmcnt(0)
	s_barrier
	s_setprio 1
	s_waitcnt lgkmcnt(0)
	v_mfma_f32_16x16x32_bf16 v[64:67], v[140:143], v[218:221], v[64:67]
	v_mfma_f32_16x16x32_bf16 v[84:87], v[170:173], v[218:221], v[84:87]
	v_mfma_f32_16x16x32_bf16 v[60:63], v[140:143], v[226:229], v[60:63]
	v_mfma_f32_16x16x32_bf16 v[80:83], v[170:173], v[226:229], v[80:83]
	v_mfma_f32_16x16x32_bf16 v[68:71], v[140:143], v[234:237], v[68:71]
	v_mfma_f32_16x16x32_bf16 v[88:91], v[170:173], v[234:237], v[88:91]
	v_mfma_f32_16x16x32_bf16 v[72:75], v[140:143], v[242:245], v[72:75]
	v_mfma_f32_16x16x32_bf16 v[92:95], v[170:173], v[242:245], v[92:95]
	v_mfma_f32_16x16x32_bf16 v[64:67], v[160:163], v[222:225], v[64:67]
	v_mfma_f32_16x16x32_bf16 v[84:87], v[198:201], v[222:225], v[84:87]
	v_mfma_f32_16x16x32_bf16 v[60:63], v[160:163], v[230:233], v[60:63]
	v_mfma_f32_16x16x32_bf16 v[80:83], v[198:201], v[230:233], v[80:83]
	v_mfma_f32_16x16x32_bf16 v[68:71], v[160:163], v[238:241], v[68:71]
	v_mfma_f32_16x16x32_bf16 v[88:91], v[198:201], v[238:241], v[88:91]
	v_mfma_f32_16x16x32_bf16 v[72:75], v[160:163], v[246:249], v[72:75]
	v_mfma_f32_16x16x32_bf16 v[92:95], v[198:201], v[246:249], v[92:95]
	s_setprio 0
	s_setprio 1
	v_mfma_f32_16x16x32_bf16 v[100:103], v[202:205], v[218:221], v[100:103]
	v_mfma_f32_16x16x32_bf16 v[120:123], v[210:213], v[218:221], v[120:123]
	v_mfma_f32_16x16x32_bf16 v[96:99], v[202:205], v[226:229], v[96:99]
	v_mfma_f32_16x16x32_bf16 v[112:115], v[210:213], v[226:229], v[112:115]
	v_mfma_f32_16x16x32_bf16 v[104:107], v[202:205], v[234:237], v[104:107]
	v_mfma_f32_16x16x32_bf16 v[116:119], v[210:213], v[234:237], v[116:119]
	v_mfma_f32_16x16x32_bf16 v[108:111], v[202:205], v[242:245], v[108:111]
	v_mfma_f32_16x16x32_bf16 v[124:127], v[210:213], v[242:245], v[124:127]
	v_mfma_f32_16x16x32_bf16 v[100:103], v[206:209], v[222:225], v[100:103]
	v_mfma_f32_16x16x32_bf16 v[120:123], v[214:217], v[222:225], v[120:123]
	v_mfma_f32_16x16x32_bf16 v[96:99], v[206:209], v[230:233], v[96:99]
	v_mfma_f32_16x16x32_bf16 v[112:115], v[214:217], v[230:233], v[112:115]
	v_mfma_f32_16x16x32_bf16 v[104:107], v[206:209], v[238:241], v[104:107]
	v_mfma_f32_16x16x32_bf16 v[116:119], v[214:217], v[238:241], v[116:119]
	v_mfma_f32_16x16x32_bf16 v[108:111], v[206:209], v[246:249], v[108:111]
	v_mfma_f32_16x16x32_bf16 v[124:127], v[214:217], v[246:249], v[124:127]
	s_setprio 0
	s_barrier
	s_add_i32 s40, s40, 2
	s_add_u32 s0, s0, 0x100
	s_addc_u32 s1, s1, 0
	s_add_u32 s22, s22, 0x10000
	s_addc_u32 s23, s23, 0
	s_cmp_gt_u32 s40, 29
	s_cbranch_scc0 .LBB0_458
	v_cvt_pk_bf16_f32 v160, v8, v9
	v_mul_f32_e32 v9, v9, v9
	v_fmac_f32_e32 v9, v8, v8
	v_mul_f32_e32 v8, v11, v11
	v_fmac_f32_e32 v8, v10, v10
	v_cvt_pk_bf16_f32 v161, v10, v11
	v_add_f32_e32 v8, v9, v8
	v_mul_f32_e32 v9, v13, v13
	v_mul_f32_e32 v10, v15, v15
	v_fmac_f32_e32 v9, v12, v12
	v_fmac_f32_e32 v10, v14, v14
	v_add_f32_e32 v9, v9, v10
	v_add_f32_e32 v8, v8, v9
	v_mul_f32_e32 v9, v29, v29
	v_mul_f32_e32 v10, v31, v31
	v_fmac_f32_e32 v9, v28, v28
	v_fmac_f32_e32 v10, v30, v30
	v_add_f32_e32 v9, v9, v10
	v_mul_f32_e32 v10, v33, v33
	v_mul_f32_e32 v11, v35, v35
	s_lshl_b32 s0, s14, 8
	v_fmac_f32_e32 v10, v32, v32
	v_fmac_f32_e32 v11, v34, v34
	s_add_i32 s8, s0, s29
	v_add_f32_e32 v10, v10, v11
	s_lshl_b32 s0, s24, 8
	s_ashr_i32 s6, s8, 8
	v_add_f32_e32 v9, v9, v10
	v_cmp_lt_i32_e64 s[40:41], v191, v192
	v_or_b32_e32 v140, s8, v164
	s_or_b32 s9, s0, s34
	s_ashr_i32 s7, s6, 31
	v_add_f32_e32 v8, v8, v9
	v_cndmask_b32_e64 v9, v190, v191, s[40:41]
	s_lshl_b32 s0, s24, 2
	s_lshl_b32 s8, s8, 6
	v_lshlrev_b32_e32 v141, 5, v140
	s_lshl_b64 s[24:25], s[6:7], 5
	s_ashr_i32 s6, s9, 6
	v_lshlrev_b32_e32 v10, 2, v9
	s_ashr_i32 s1, s0, 31
	s_and_b32 s8, s8, 0x2000
	v_and_b32_e32 v142, 0x1e0, v141
	s_ashr_i32 s7, s6, 31
	ds_bpermute_b32 v9, v10, v8
	v_or3_b32 v141, s8, v142, v167
	s_add_u32 s8, s24, s6
	s_addc_u32 s9, s25, s7
	s_lshl_b64 s[8:9], s[8:9], 15
	s_add_u32 s22, s16, s8
	v_cmp_lt_i32_e64 s[40:41], v193, v192
	s_addc_u32 s23, s17, s9
	s_or_b32 s8, s6, 2
	s_waitcnt lgkmcnt(0)
	v_add_f32_e32 v8, v8, v9
	v_cndmask_b32_e64 v9, v190, v193, s[40:41]
	s_ashr_i32 s9, s8, 31
	v_lshlrev_b32_e32 v11, 2, v9
	s_add_u32 s24, s24, s8
	ds_bpermute_b32 v9, v11, v8
	s_addc_u32 s25, s25, s9
	s_lshl_b64 s[24:25], s[24:25], 15
	s_add_u32 s24, s16, s24
	v_lshlrev_b32_e32 v141, 1, v141
	s_addc_u32 s25, s17, s25
	v_cvt_pk_bf16_f32 v162, v12, v13
	v_cvt_pk_bf16_f32 v163, v14, v15
	global_store_dwordx4 v141, v[160:163], s[22:23] sc0 sc1
	v_cvt_pk_bf16_f32 v12, v28, v29
	v_cvt_pk_bf16_f32 v13, v30, v31
	v_cvt_pk_bf16_f32 v14, v32, v33
	v_cvt_pk_bf16_f32 v15, v34, v35
	global_store_dwordx4 v141, v[12:15], s[24:25] sc0 sc1
	s_and_saveexec_b64 s[26:27], s[38:39]
	s_cbranch_execz .LBB0_461
	v_ashrrev_i32_e32 v141, 31, v140
	v_lshlrev_b64 v[12:13], 7, v[140:141]
	v_lshl_add_u64 v[12:13], s[20:21], 0, v[12:13]
	v_lshl_add_u64 v[12:13], s[0:1], 2, v[12:13]
	s_lshl_b32 s14, s28, 2
	v_lshl_add_u64 v[12:13], v[12:13], 0, s[14:15]
	s_waitcnt lgkmcnt(0)
	v_add_f32_e32 v8, v8, v9
	global_store_dword v[12:13], v8, off
; __device__ __forceinline__ unsigned cvt_pk_bf16(float lo, float hi) { unsigned r; asm volatile("v_cvt_pk_bf16_f32 %0, %1, %2" : "=v"(r) : "v"(lo), "v"(hi)); return r; }
;     __device__ __forceinline__ size_t xb_off(int row, int col) const { return ((size_t)(row >> 8) * (ldc >> 6) + (col >> 6)) * (256 * 64) + blk_off(row & 255, col & 63); }
;     __device__ __forceinline__ void operator()(const f32x4 (&acc)[2][2][4][2], const State&, const Unit& u, int wr, int wc, int fr, int fq) const {
;     ...
;             for (int ai = 0; ai < 2; ++ai)
; #pragma unroll
;                 for (int m = 0; m < 4; ++m) { const int row = row0 + ai * HALF + m * 16; const size_t off = (size_t)row * ldc + col0; float ss = 0.f;
; #pragma unroll
;                     for (int bj = 0; bj < 2; ++bj) { const f32x4 v0 = acc[ai][bj][m][0], v1 = acc[ai][bj][m][1];
;                         u32x4 w; w.x = cvt_pk_bf16(v0[0], v0[1]); w.y = cvt_pk_bf16(v0[2], v0[3]); w.z = cvt_pk_bf16(v1[0], v1[1]); w.w = cvt_pk_bf16(v1[2], v1[3]);
;                         *(u32x4*)(xb + xb_off(row, col0 + bj * HALF)) = w;
;                         ss += ((v0[0] * v0[0] + v0[1] * v0[1]) + (v0[2] * v0[2] + v0[3] * v0[3])) + ((v1[0] * v1[0] + v1[1] * v1[1]) + (v1[2] * v1[2] + v1[3] * v1[3])); }
;                     ss += __shfl_xor(ss, 16); ss += __shfl_xor(ss, 32);
;                     if (fq == 0) ssq[(size_t)row * 32 + u.pn * 4 + wc] = ss; }
.LBB0_461:
	s_or_b64 exec, exec, s[26:27]
	v_cvt_pk_bf16_f32 v28, v4, v5
	v_cvt_pk_bf16_f32 v29, v6, v7
	v_cvt_pk_bf16_f32 v30, v0, v1
	v_mul_f32_e32 v5, v5, v5
	v_mul_f32_e32 v1, v1, v1
	v_fmac_f32_e32 v5, v4, v4
	v_mul_f32_e32 v4, v7, v7
	v_fmac_f32_e32 v1, v0, v0
	v_mul_f32_e32 v0, v3, v3
	v_fmac_f32_e32 v4, v6, v6
	v_fmac_f32_e32 v0, v2, v2
	v_add_f32_e32 v4, v5, v4
	v_add_f32_e32 v0, v1, v0
	v_add_f32_e32 v0, v4, v0
	v_mul_f32_e32 v1, v21, v21
	v_mul_f32_e32 v4, v23, v23
	v_fmac_f32_e32 v1, v20, v20
	v_fmac_f32_e32 v4, v22, v22
	v_add_f32_e32 v1, v1, v4
	v_mul_f32_e32 v4, v25, v25
	v_mul_f32_e32 v5, v27, v27
	v_fmac_f32_e32 v4, v24, v24
	v_fmac_f32_e32 v5, v26, v26
	v_add_f32_e32 v4, v4, v5
	v_add_f32_e32 v1, v1, v4
	v_add_f32_e32 v0, v0, v1
	ds_bpermute_b32 v1, v10, v0
	v_or_b32_e32 v8, 16, v140
	s_waitcnt lgkmcnt(0)
	v_lshlrev_b32_e32 v9, 6, v140
	v_and_b32_e32 v12, 0x2000, v9
	v_lshrrev_b32_e32 v9, 3, v8
	v_add_f32_e32 v0, v0, v1
	ds_bpermute_b32 v1, v11, v0
	v_and_or_b32 v9, v9, 10, s69
	v_lshl_or_b32 v9, v9, 9, v12
	v_or3_b32 v9, v9, v142, v165
	v_lshlrev_b32_e32 v6, 1, v9
	v_cvt_pk_bf16_f32 v31, v2, v3
	global_store_dwordx4 v6, v[28:31], s[22:23] sc0 sc1
	v_cvt_pk_bf16_f32 v2, v20, v21
	v_cvt_pk_bf16_f32 v3, v22, v23
	v_cvt_pk_bf16_f32 v4, v24, v25
	v_cvt_pk_bf16_f32 v5, v26, v27
	global_store_dwordx4 v6, v[2:5], s[24:25] sc0 sc1
	s_and_saveexec_b64 s[26:27], s[38:39]
	s_cbranch_execz .LBB0_463
	v_ashrrev_i32_e32 v9, 31, v8
	v_lshlrev_b64 v[2:3], 7, v[8:9]
	v_lshl_add_u64 v[2:3], s[20:21], 0, v[2:3]
	v_lshl_add_u64 v[2:3], s[0:1], 2, v[2:3]
	s_lshl_b32 s14, s28, 2
	v_lshl_add_u64 v[2:3], v[2:3], 0, s[14:15]
	s_waitcnt lgkmcnt(0)
	v_add_f32_e32 v0, v0, v1
	global_store_dword v[2:3], v0, off
.LBB0_463:
	s_or_b64 exec, exec, s[26:27]
	v_mul_f32_e32 v5, v17, v17
	v_mul_f32_e32 v6, v19, v19
	v_fmac_f32_e32 v5, v16, v16
	v_fmac_f32_e32 v6, v18, v18
	v_add_f32_e32 v5, v5, v6
	v_mul_f32_e32 v6, v37, v37
	v_mul_f32_e32 v7, v39, v39
	v_fmac_f32_e32 v6, v36, v36
	v_fmac_f32_e32 v7, v38, v38
	v_add_f32_e32 v6, v6, v7
	v_add_f32_e32 v5, v5, v6
	v_mul_f32_e32 v6, v49, v49
	v_mul_f32_e32 v7, v51, v51
	v_fmac_f32_e32 v6, v48, v48
	v_fmac_f32_e32 v7, v50, v50
	v_add_f32_e32 v6, v6, v7
	v_mul_f32_e32 v7, v57, v57
	v_mul_f32_e32 v8, v59, v59
	v_fmac_f32_e32 v7, v56, v56
	v_fmac_f32_e32 v8, v58, v58
	v_add_f32_e32 v7, v7, v8
	v_add_f32_e32 v6, v6, v7
	v_or_b32_e32 v0, 32, v140
	v_add_f32_e32 v6, v5, v6
	s_waitcnt lgkmcnt(0)
	v_lshrrev_b32_e32 v1, 3, v0
	ds_bpermute_b32 v7, v10, v6
	v_and_or_b32 v1, v1, 12, s69
	v_lshl_or_b32 v1, v1, 9, v12
	v_or3_b32 v1, v1, v142, v165
	v_cvt_pk_bf16_f32 v2, v16, v17
	v_lshlrev_b32_e32 v1, 1, v1
	v_cvt_pk_bf16_f32 v3, v18, v19
	v_cvt_pk_bf16_f32 v4, v36, v37
	v_cvt_pk_bf16_f32 v5, v38, v39
	global_store_dwordx4 v1, v[2:5], s[22:23] sc0 sc1
	s_waitcnt lgkmcnt(0)
	s_nop 0
	v_add_f32_e32 v2, v6, v7
	ds_bpermute_b32 v3, v11, v2
	v_cvt_pk_bf16_f32 v4, v48, v49
	v_cvt_pk_bf16_f32 v5, v50, v51
	v_cvt_pk_bf16_f32 v6, v56, v57
	v_cvt_pk_bf16_f32 v7, v58, v59
	global_store_dwordx4 v1, v[4:7], s[24:25] sc0 sc1
	s_and_saveexec_b64 s[26:27], s[38:39]
	s_cbranch_execz .LBB0_465
	v_ashrrev_i32_e32 v1, 31, v0
	v_lshlrev_b64 v[0:1], 7, v[0:1]
	v_lshl_add_u64 v[0:1], s[20:21], 0, v[0:1]
	v_lshl_add_u64 v[0:1], s[0:1], 2, v[0:1]
	s_lshl_b32 s14, s28, 2
	v_lshl_add_u64 v[0:1], v[0:1], 0, s[14:15]
	s_waitcnt lgkmcnt(0)
	v_add_f32_e32 v2, v2, v3
	global_store_dword v[0:1], v2, off
.LBB0_465:
	s_or_b64 exec, exec, s[26:27]
	v_mul_f32_e32 v5, v45, v45
	v_mul_f32_e32 v6, v47, v47
	v_fmac_f32_e32 v5, v44, v44
	v_fmac_f32_e32 v6, v46, v46
	v_add_f32_e32 v5, v5, v6
	v_mul_f32_e32 v6, v41, v41
	v_mul_f32_e32 v7, v43, v43
	v_fmac_f32_e32 v6, v40, v40
	v_fmac_f32_e32 v7, v42, v42
	v_add_f32_e32 v6, v6, v7
	v_add_f32_e32 v5, v5, v6
	v_mul_f32_e32 v6, v53, v53
	v_mul_f32_e32 v7, v55, v55
	v_fmac_f32_e32 v6, v52, v52
	v_fmac_f32_e32 v7, v54, v54
	v_add_f32_e32 v6, v6, v7
	v_mul_f32_e32 v7, v77, v77
	v_mul_f32_e32 v8, v79, v79
	v_fmac_f32_e32 v7, v76, v76
	v_fmac_f32_e32 v8, v78, v78
	v_add_f32_e32 v7, v7, v8
	v_add_f32_e32 v6, v6, v7
	v_or_b32_e32 v0, 48, v140
	v_add_f32_e32 v6, v5, v6
	v_lshrrev_b32_e32 v1, 3, v0
	ds_bpermute_b32 v7, v10, v6
	v_and_or_b32 v1, v1, 14, s69
	v_lshl_or_b32 v1, v1, 9, v12
	v_or3_b32 v1, v1, v142, v165
	v_cvt_pk_bf16_f32 v2, v44, v45
	v_lshlrev_b32_e32 v1, 1, v1
	s_waitcnt lgkmcnt(0)
	v_cvt_pk_bf16_f32 v3, v46, v47
	v_cvt_pk_bf16_f32 v4, v40, v41
	v_cvt_pk_bf16_f32 v5, v42, v43
	global_store_dwordx4 v1, v[2:5], s[22:23] sc0 sc1
	s_nop 1
	v_add_f32_e32 v2, v6, v7
	ds_bpermute_b32 v3, v11, v2
	v_cvt_pk_bf16_f32 v4, v52, v53
	v_cvt_pk_bf16_f32 v5, v54, v55
	v_cvt_pk_bf16_f32 v6, v76, v77
	v_cvt_pk_bf16_f32 v7, v78, v79
	global_store_dwordx4 v1, v[4:7], s[24:25] sc0 sc1
	s_and_saveexec_b64 s[22:23], s[38:39]
	s_cbranch_execz .LBB0_467
	v_ashrrev_i32_e32 v1, 31, v0
	v_lshlrev_b64 v[0:1], 7, v[0:1]
	v_lshl_add_u64 v[0:1], s[20:21], 0, v[0:1]
	v_lshl_add_u64 v[0:1], s[0:1], 2, v[0:1]
	s_lshl_b32 s14, s28, 2
	v_lshl_add_u64 v[0:1], v[0:1], 0, s[14:15]
	s_waitcnt lgkmcnt(0)
	v_add_f32_e32 v2, v2, v3
	global_store_dword v[0:1], v2, off
; __device__ __forceinline__ unsigned cvt_pk_bf16(float lo, float hi) { unsigned r; asm volatile("v_cvt_pk_bf16_f32 %0, %1, %2" : "=v"(r) : "v"(lo), "v"(hi)); return r; }
;     __device__ __forceinline__ size_t xb_off(int row, int col) const { return ((size_t)(row >> 8) * (ldc >> 6) + (col >> 6)) * (256 * 64) + blk_off(row & 255, col & 63); }
;     __device__ __forceinline__ void operator()(const f32x4 (&acc)[2][2][4][2], const State&, const Unit& u, int wr, int wc, int fr, int fq) const {
;     ...
;             for (int ai = 0; ai < 2; ++ai)
; #pragma unroll
;                 for (int m = 0; m < 4; ++m) { const int row = row0 + ai * HALF + m * 16; const size_t off = (size_t)row * ldc + col0; float ss = 0.f;
; #pragma unroll
;                     for (int bj = 0; bj < 2; ++bj) { const f32x4 v0 = acc[ai][bj][m][0], v1 = acc[ai][bj][m][1];
;                         u32x4 w; w.x = cvt_pk_bf16(v0[0], v0[1]); w.y = cvt_pk_bf16(v0[2], v0[3]); w.z = cvt_pk_bf16(v1[0], v1[1]); w.w = cvt_pk_bf16(v1[2], v1[3]);
;                         *(u32x4*)(xb + xb_off(row, col0 + bj * HALF)) = w;
;                         ss += ((v0[0] * v0[0] + v0[1] * v0[1]) + (v0[2] * v0[2] + v0[3] * v0[3])) + ((v1[0] * v1[0] + v1[1] * v1[1]) + (v1[2] * v1[2] + v1[3] * v1[3])); }
;                     ss += __shfl_xor(ss, 16); ss += __shfl_xor(ss, 32);
;                     if (fq == 0) ssq[(size_t)row * 32 + u.pn * 4 + wc] = ss; }
.LBB0_467:
	s_or_b64 exec, exec, s[22:23]
	v_add_u32_e32 v4, 0x80, v140
	v_ashrrev_i32_e32 v0, 8, v4
	v_lshlrev_b32_e32 v2, 6, v4
	s_waitcnt lgkmcnt(0)
	v_lshlrev_b32_e32 v3, 5, v4
	v_ashrrev_i32_e32 v1, 31, v0
	v_and_b32_e32 v2, 0x2000, v2
	v_and_b32_e32 v3, 0x1e0, v3
	v_or3_b32 v5, v2, v3, v167
	v_lshlrev_b64 v[2:3], 5, v[0:1]
	v_lshl_add_u64 v[0:1], v[2:3], 0, s[6:7]
	v_lshlrev_b64 v[0:1], 15, v[0:1]
	v_lshl_add_u64 v[0:1], s[16:17], 0, v[0:1]
	v_lshlrev_b32_e32 v144, 1, v5
	v_cvt_pk_bf16_f32 v6, v64, v65
	v_lshl_add_u64 v[12:13], v[0:1], 0, v[144:145]
	v_cvt_pk_bf16_f32 v7, v66, v67
	v_cvt_pk_bf16_f32 v8, v84, v85
	v_cvt_pk_bf16_f32 v9, v86, v87
	global_store_dwordx4 v[12:13], v[6:9], off sc0 sc1
	v_mul_f32_e32 v5, v65, v65
	v_fmac_f32_e32 v5, v64, v64
	v_mul_f32_e32 v6, v67, v67
	v_fmac_f32_e32 v6, v66, v66
	v_add_f32_e32 v5, v5, v6
	v_mul_f32_e32 v6, v85, v85
	v_mul_f32_e32 v7, v87, v87
	v_fmac_f32_e32 v6, v84, v84
	v_fmac_f32_e32 v7, v86, v86
	v_add_f32_e32 v6, v6, v7
	v_add_f32_e32 v5, v5, v6
	v_mul_f32_e32 v6, v101, v101
	v_mul_f32_e32 v7, v103, v103
	v_fmac_f32_e32 v6, v100, v100
	v_fmac_f32_e32 v7, v102, v102
	v_add_f32_e32 v6, v6, v7
	v_mul_f32_e32 v7, v121, v121
	v_mul_f32_e32 v8, v123, v123
	v_fmac_f32_e32 v7, v120, v120
	v_fmac_f32_e32 v8, v122, v122
	v_add_f32_e32 v7, v7, v8
	v_add_f32_e32 v6, v6, v7
	v_add_f32_e32 v5, v5, v6
	ds_bpermute_b32 v6, v10, v5
	v_lshl_add_u64 v[2:3], v[2:3], 0, s[8:9]
	v_lshlrev_b64 v[2:3], 15, v[2:3]
	v_lshl_add_u64 v[2:3], s[16:17], 0, v[2:3]
	v_lshl_add_u64 v[8:9], v[2:3], 0, v[144:145]
	s_waitcnt lgkmcnt(0)
	v_add_f32_e32 v6, v5, v6
	ds_bpermute_b32 v7, v11, v6
	v_cvt_pk_bf16_f32 v12, v100, v101
	v_cvt_pk_bf16_f32 v13, v102, v103
	v_cvt_pk_bf16_f32 v14, v120, v121
	v_cvt_pk_bf16_f32 v15, v122, v123
	global_store_dwordx4 v[8:9], v[12:15], off sc0 sc1
	s_and_saveexec_b64 s[6:7], s[38:39]
	s_cbranch_execz .LBB0_469
	v_ashrrev_i32_e32 v5, 31, v4
	v_lshlrev_b64 v[4:5], 7, v[4:5]
	v_lshl_add_u64 v[4:5], s[20:21], 0, v[4:5]
	v_lshl_add_u64 v[4:5], s[0:1], 2, v[4:5]
	s_lshl_b32 s14, s28, 2
	v_lshl_add_u64 v[4:5], v[4:5], 0, s[14:15]
	s_waitcnt lgkmcnt(0)
	v_add_f32_e32 v6, v6, v7
	global_store_dword v[4:5], v6, off
.LBB0_469:
	s_or_b64 exec, exec, s[6:7]
	v_add_u32_e32 v4, 0x90, v140
	v_lshlrev_b32_e32 v5, 6, v4
	v_lshrrev_b32_e32 v6, 3, v4
	v_and_b32_e32 v5, 0x2000, v5
	v_and_or_b32 v6, v6, 10, s69
	v_lshl_or_b32 v5, v6, 9, v5
	v_lshlrev_b32_e32 v6, 5, v4
	v_and_b32_e32 v6, 0x1e0, v6
	v_or3_b32 v5, v5, v6, v165
	v_lshlrev_b32_e32 v144, 1, v5
	v_mul_f32_e32 v5, v61, v61
	v_mul_f32_e32 v12, v63, v63
	v_fmac_f32_e32 v5, v60, v60
	v_fmac_f32_e32 v12, v62, v62
	v_add_f32_e32 v5, v5, v12
	v_mul_f32_e32 v12, v81, v81
	v_mul_f32_e32 v13, v83, v83
	v_fmac_f32_e32 v12, v80, v80
	v_fmac_f32_e32 v13, v82, v82
	v_add_f32_e32 v12, v12, v13
	v_add_f32_e32 v5, v5, v12
	v_mul_f32_e32 v12, v97, v97
	v_mul_f32_e32 v13, v99, v99
	v_fmac_f32_e32 v12, v96, v96
	v_fmac_f32_e32 v13, v98, v98
	v_add_f32_e32 v12, v12, v13
	v_mul_f32_e32 v13, v113, v113
	v_mul_f32_e32 v14, v115, v115
	v_fmac_f32_e32 v13, v112, v112
	v_fmac_f32_e32 v14, v114, v114
	v_add_f32_e32 v13, v13, v14
	v_add_f32_e32 v12, v12, v13
	v_add_f32_e32 v5, v5, v12
	ds_bpermute_b32 v14, v10, v5
	v_cvt_pk_bf16_f32 v6, v60, v61
	v_lshl_add_u64 v[12:13], v[0:1], 0, v[144:145]
	s_waitcnt lgkmcnt(0)
	v_cvt_pk_bf16_f32 v7, v62, v63
	v_cvt_pk_bf16_f32 v8, v80, v81
	v_cvt_pk_bf16_f32 v9, v82, v83
	global_store_dwordx4 v[12:13], v[6:9], off sc0 sc1
	v_cvt_pk_bf16_f32 v12, v96, v97
	v_cvt_pk_bf16_f32 v13, v98, v99
	s_nop 1
	v_add_f32_e32 v6, v5, v14
	ds_bpermute_b32 v7, v11, v6
	v_lshl_add_u64 v[8:9], v[2:3], 0, v[144:145]
	v_cvt_pk_bf16_f32 v14, v112, v113
	v_cvt_pk_bf16_f32 v15, v114, v115
	global_store_dwordx4 v[8:9], v[12:15], off sc0 sc1
	s_and_saveexec_b64 s[6:7], s[38:39]
	s_cbranch_execz .LBB0_471
	v_ashrrev_i32_e32 v5, 31, v4
	v_lshlrev_b64 v[4:5], 7, v[4:5]
	v_lshl_add_u64 v[4:5], s[20:21], 0, v[4:5]
	v_lshl_add_u64 v[4:5], s[0:1], 2, v[4:5]
	s_lshl_b32 s14, s28, 2
	v_lshl_add_u64 v[4:5], v[4:5], 0, s[14:15]
	s_waitcnt lgkmcnt(0)
	v_add_f32_e32 v6, v6, v7
	global_store_dword v[4:5], v6, off
; __device__ __forceinline__ unsigned cvt_pk_bf16(float lo, float hi) { unsigned r; asm volatile("v_cvt_pk_bf16_f32 %0, %1, %2" : "=v"(r) : "v"(lo), "v"(hi)); return r; }
;     __device__ __forceinline__ size_t xb_off(int row, int col) const { return ((size_t)(row >> 8) * (ldc >> 6) + (col >> 6)) * (256 * 64) + blk_off(row & 255, col & 63); }
;     __device__ __forceinline__ void operator()(const f32x4 (&acc)[2][2][4][2], const State&, const Unit& u, int wr, int wc, int fr, int fq) const {
;     ...
;             for (int ai = 0; ai < 2; ++ai)
; #pragma unroll
;                 for (int m = 0; m < 4; ++m) { const int row = row0 + ai * HALF + m * 16; const size_t off = (size_t)row * ldc + col0; float ss = 0.f;
; #pragma unroll
;                     for (int bj = 0; bj < 2; ++bj) { const f32x4 v0 = acc[ai][bj][m][0], v1 = acc[ai][bj][m][1];
;                         u32x4 w; w.x = cvt_pk_bf16(v0[0], v0[1]); w.y = cvt_pk_bf16(v0[2], v0[3]); w.z = cvt_pk_bf16(v1[0], v1[1]); w.w = cvt_pk_bf16(v1[2], v1[3]);
;                         *(u32x4*)(xb + xb_off(row, col0 + bj * HALF)) = w;
;                         ss += ((v0[0] * v0[0] + v0[1] * v0[1]) + (v0[2] * v0[2] + v0[3] * v0[3])) + ((v1[0] * v1[0] + v1[1] * v1[1]) + (v1[2] * v1[2] + v1[3] * v1[3])); }
;                     ss += __shfl_xor(ss, 16); ss += __shfl_xor(ss, 32);
;                     if (fq == 0) ssq[(size_t)row * 32 + u.pn * 4 + wc] = ss; }
.LBB0_471:
	s_or_b64 exec, exec, s[6:7]
	v_add_u32_e32 v4, 0xa0, v140
	v_lshlrev_b32_e32 v5, 6, v4
	v_lshrrev_b32_e32 v6, 3, v4
	v_and_b32_e32 v5, 0x2000, v5
	v_and_or_b32 v6, v6, 12, s69
	v_lshl_or_b32 v5, v6, 9, v5
	v_lshlrev_b32_e32 v6, 5, v4
	v_and_b32_e32 v6, 0x1e0, v6
	v_or3_b32 v5, v5, v6, v165
	v_lshlrev_b32_e32 v144, 1, v5
	v_mul_f32_e32 v5, v69, v69
	v_mul_f32_e32 v12, v71, v71
	v_fmac_f32_e32 v5, v68, v68
	v_fmac_f32_e32 v12, v70, v70
	v_add_f32_e32 v5, v5, v12
	v_mul_f32_e32 v12, v89, v89
	v_mul_f32_e32 v13, v91, v91
	v_fmac_f32_e32 v12, v88, v88
	v_fmac_f32_e32 v13, v90, v90
	v_add_f32_e32 v12, v12, v13
	v_add_f32_e32 v5, v5, v12
	v_mul_f32_e32 v12, v105, v105
	v_mul_f32_e32 v13, v107, v107
	v_fmac_f32_e32 v12, v104, v104
	v_fmac_f32_e32 v13, v106, v106
	v_add_f32_e32 v12, v12, v13
	v_mul_f32_e32 v13, v117, v117
	v_mul_f32_e32 v14, v119, v119
	v_fmac_f32_e32 v13, v116, v116
	v_fmac_f32_e32 v14, v118, v118
	v_add_f32_e32 v13, v13, v14
	v_add_f32_e32 v12, v12, v13
	v_add_f32_e32 v5, v5, v12
	ds_bpermute_b32 v14, v10, v5
	v_cvt_pk_bf16_f32 v6, v68, v69
	v_lshl_add_u64 v[12:13], v[0:1], 0, v[144:145]
	s_waitcnt lgkmcnt(0)
	v_cvt_pk_bf16_f32 v7, v70, v71
	v_cvt_pk_bf16_f32 v8, v88, v89
	v_cvt_pk_bf16_f32 v9, v90, v91
	global_store_dwordx4 v[12:13], v[6:9], off sc0 sc1
	v_cvt_pk_bf16_f32 v12, v104, v105
	v_cvt_pk_bf16_f32 v13, v106, v107
	s_nop 1
	v_add_f32_e32 v6, v5, v14
	ds_bpermute_b32 v7, v11, v6
	v_lshl_add_u64 v[8:9], v[2:3], 0, v[144:145]
	v_cvt_pk_bf16_f32 v14, v116, v117
	v_cvt_pk_bf16_f32 v15, v118, v119
	global_store_dwordx4 v[8:9], v[12:15], off sc0 sc1
	s_and_saveexec_b64 s[6:7], s[38:39]
	s_cbranch_execz .LBB0_473
	v_ashrrev_i32_e32 v5, 31, v4
	v_lshlrev_b64 v[4:5], 7, v[4:5]
	v_lshl_add_u64 v[4:5], s[20:21], 0, v[4:5]
	v_lshl_add_u64 v[4:5], s[0:1], 2, v[4:5]
	s_lshl_b32 s14, s28, 2
	v_lshl_add_u64 v[4:5], v[4:5], 0, s[14:15]
	s_waitcnt lgkmcnt(0)
	v_add_f32_e32 v6, v6, v7
	global_store_dword v[4:5], v6, off
.LBB0_473:
	s_or_b64 exec, exec, s[6:7]
	v_add_u32_e32 v4, 0xb0, v140
	v_lshlrev_b32_e32 v5, 6, v4
	v_lshrrev_b32_e32 v6, 3, v4
	v_and_b32_e32 v5, 0x2000, v5
	v_and_or_b32 v6, v6, 14, s69
	v_lshl_or_b32 v5, v6, 9, v5
	v_lshlrev_b32_e32 v6, 5, v4
	v_and_b32_e32 v6, 0x1e0, v6
	v_or3_b32 v5, v5, v6, v165
	v_lshlrev_b32_e32 v144, 1, v5
	v_mul_f32_e32 v5, v73, v73
	v_mul_f32_e32 v12, v75, v75
	v_fmac_f32_e32 v5, v72, v72
	v_fmac_f32_e32 v12, v74, v74
	v_add_f32_e32 v5, v5, v12
	v_mul_f32_e32 v12, v93, v93
	v_mul_f32_e32 v13, v95, v95
	v_fmac_f32_e32 v12, v92, v92
	v_fmac_f32_e32 v13, v94, v94
	v_add_f32_e32 v12, v12, v13
	v_add_f32_e32 v5, v5, v12
	v_mul_f32_e32 v12, v109, v109
	v_mul_f32_e32 v13, v111, v111
	v_fmac_f32_e32 v12, v108, v108
	v_fmac_f32_e32 v13, v110, v110
	v_add_f32_e32 v12, v12, v13
	v_mul_f32_e32 v13, v125, v125
	v_mul_f32_e32 v14, v127, v127
	v_fmac_f32_e32 v13, v124, v124
	v_fmac_f32_e32 v14, v126, v126
	v_add_f32_e32 v13, v13, v14
	v_add_f32_e32 v12, v12, v13
	v_add_f32_e32 v5, v5, v12
	ds_bpermute_b32 v10, v10, v5
	v_lshl_add_u64 v[0:1], v[0:1], 0, v[144:145]
	v_cvt_pk_bf16_f32 v6, v72, v73
	s_waitcnt lgkmcnt(0)
	v_cvt_pk_bf16_f32 v7, v74, v75
	v_cvt_pk_bf16_f32 v8, v92, v93
	v_cvt_pk_bf16_f32 v9, v94, v95
	global_store_dwordx4 v[0:1], v[6:9], off sc0 sc1
	v_add_f32_e32 v0, v5, v10
	ds_bpermute_b32 v1, v11, v0
	v_lshl_add_u64 v[2:3], v[2:3], 0, v[144:145]
	v_cvt_pk_bf16_f32 v6, v108, v109
	v_cvt_pk_bf16_f32 v7, v110, v111
	v_cvt_pk_bf16_f32 v8, v124, v125
	v_cvt_pk_bf16_f32 v9, v126, v127
	global_store_dwordx4 v[2:3], v[6:9], off sc0 sc1
	s_and_saveexec_b64 s[6:7], s[38:39]
	s_cbranch_execz .LBB0_475
	v_ashrrev_i32_e32 v5, 31, v4
	v_lshlrev_b64 v[2:3], 7, v[4:5]
	v_lshl_add_u64 v[2:3], s[20:21], 0, v[2:3]
	v_lshl_add_u64 v[2:3], s[0:1], 2, v[2:3]
	s_lshl_b32 s14, s28, 2
	v_lshl_add_u64 v[2:3], v[2:3], 0, s[14:15]
	s_waitcnt lgkmcnt(0)
	v_add_f32_e32 v0, v0, v1
	global_store_dword v[2:3], v0, off

; __host__ __device__ __forceinline__ int blk_off(int r, int c) { const int rr = r & 127; return (r >> 7) * 8192 + (((rr >> 4) * 2 + (c >> 5)) * 512) + (rr & 15) * 32 + (c & 31); }
; __device__ __forceinline__ unsigned cvt_pk_bf16(float lo, float hi) { unsigned r; asm volatile("v_cvt_pk_bf16_f32 %0, %1, %2" : "=v"(r) : "v"(lo), "v"(hi)); return r; }
;     __device__ __forceinline__ void operator()(const f32x4 (&acc)[2][2][4][2], const State& st, const Unit& u, int wr, int wc, int fr, int fq) const {
;         const int row0 = u.pm * BM + wr * 64 + fr, col0 = u.pn * BM + wc * 32 + 8 * fq;
;         const float rsv[2][4] = {{st.ra[0], st.ra[1], st.ra[2], st.ra[3]}, {st.rb[0], st.rb[1], st.rb[2], st.rb[3]}};
; #pragma unroll
;         for (int ai = 0; ai < 2; ++ai)
; #pragma unroll
;             for (int m = 0; m < 4; ++m) { const int row = row0 + ai * HALF + m * 16;
;                 const float rs = rsv[ai][m];
;                 bf16_t* rowp = O + (size_t)(row >> 8) * (ldc >> 6) * (256 * 64);
; #pragma unroll
;                 for (int bj = 0; bj < 2; ++bj) { f32x4 v0 = acc[ai][bj][m][0] * rs, v1 = acc[ai][bj][m][1] * rs;
; #pragma unroll
;                     for (int e = 0; e < 4; ++e) { const float a = fmaxf(v0[e], 0.f), b = fmaxf(v1[e], 0.f); v0[e] = a * a; v1[e] = b * b; }
;                     u32x4 w; w.x = cvt_pk_bf16(v0[0], v0[1]); w.y = cvt_pk_bf16(v0[2], v0[3]); w.z = cvt_pk_bf16(v1[0], v1[1]); w.w = cvt_pk_bf16(v1[2], v1[3]);
;                     { const int col = col0 + bj * HALF; *(u32x4*)(rowp + (size_t)(col >> 6) * (256 * 64) + blk_off(row & 255, col & 63)) = w; } } }
.LBB0_556:
	s_lshl_b32 s0, s60, 8
	s_add_i32 s6, s0, s14
	v_or_b32_e32 v165, s6, v129
	s_lshl_b32 s0, s66, 8
	s_or_b32 s7, s0, s50
	s_ashr_i32 s0, s6, 8
	s_lshl_b32 s6, s6, 6
	v_lshlrev_b32_e32 v144, 5, v165
	s_ashr_i32 s1, s0, 31
	s_and_b32 s6, s6, 0x2000
	v_and_b32_e32 v144, 0x1e0, v144
	v_or3_b32 v167, s6, v144, v131
	s_lshl_b64 s[0:1], s[0:1], 22
	s_add_u32 s8, s18, s0
	v_or_b32_e32 v144, s53, v167
	v_pk_mul_f32 v[122:123], v[128:129], v[122:123] op_sel_hi:[0,1]
	v_pk_mul_f32 v[120:121], v[128:129], v[120:121] op_sel_hi:[0,1]
	s_addc_u32 s9, s19, s1
	v_lshlrev_b32_e32 v144, 1, v144
	v_pk_mul_f32 v[126:127], v[128:129], v[126:127] op_sel_hi:[0,1]
	v_pk_mul_f32 v[124:125], v[128:129], v[124:125] op_sel_hi:[0,1]
	v_max_f32_e32 v120, 0, v120
	v_max_f32_e32 v121, 0, v121
	v_max_f32_e32 v122, 0, v122
	s_ashr_i32 s6, s7, 6
	v_lshl_add_u64 v[170:171], s[8:9], 0, v[144:145]
	v_max_f32_e32 v124, 0, v124
	v_mul_f32_e32 v144, v120, v120
	v_max_f32_e32 v120, 0, v125
	v_mul_f32_e32 v125, v121, v121
	v_max_f32_e32 v121, 0, v126
	v_mul_f32_e32 v126, v122, v122
	v_max_f32_e32 v122, 0, v127
	s_ashr_i32 s7, s6, 31
	v_mul_f32_e32 v124, v124, v124
	v_mul_f32_e32 v120, v120, v120
	v_mul_f32_e32 v121, v121, v121
	v_max_f32_e32 v123, 0, v123
	v_mul_f32_e32 v122, v122, v122
	s_lshl_b64 s[0:1], s[6:7], 15
	v_pk_mul_f32 v[114:115], v[128:129], v[114:115] op_sel_hi:[0,1]
	v_pk_mul_f32 v[112:113], v[128:129], v[112:113] op_sel_hi:[0,1]
	v_mul_f32_e32 v123, v123, v123
	v_cvt_pk_bf16_f32 v120, v124, v120
	v_cvt_pk_bf16_f32 v121, v121, v122
	v_cvt_pk_bf16_f32 v122, v144, v125
	v_lshl_add_u64 v[124:125], v[170:171], 0, s[0:1]
	v_pk_mul_f32 v[118:119], v[128:129], v[118:119] op_sel_hi:[0,1]
	v_pk_mul_f32 v[116:117], v[128:129], v[116:117] op_sel_hi:[0,1]
	v_max_f32_e32 v112, 0, v112
	v_max_f32_e32 v113, 0, v113
	v_max_f32_e32 v114, 0, v114
	s_or_b32 s6, s6, 2
	v_cvt_pk_bf16_f32 v123, v126, v123
	global_store_dwordx4 v[124:125], v[120:123], off sc0 sc1
	v_max_f32_e32 v116, 0, v116
	s_ashr_i32 s7, s6, 31
	v_mul_f32_e32 v120, v112, v112
	v_max_f32_e32 v112, 0, v117
	v_mul_f32_e32 v117, v113, v113
	v_max_f32_e32 v113, 0, v118
	v_mul_f32_e32 v118, v114, v114
	v_max_f32_e32 v114, 0, v119
	v_mul_f32_e32 v116, v116, v116
	v_mul_f32_e32 v112, v112, v112
	v_mul_f32_e32 v113, v113, v113
	v_max_f32_e32 v115, 0, v115
	v_mul_f32_e32 v114, v114, v114
	s_lshl_b64 s[6:7], s[6:7], 15
	v_mul_f32_e32 v115, v115, v115
	v_cvt_pk_bf16_f32 v112, v116, v112
	v_cvt_pk_bf16_f32 v113, v113, v114
	v_cvt_pk_bf16_f32 v114, v120, v117
	v_lshl_add_u64 v[116:117], v[170:171], 0, s[6:7]
	v_cvt_pk_bf16_f32 v115, v118, v115
	global_store_dwordx4 v[116:117], v[112:115], off sc0 sc1
	v_pk_mul_f32 v[106:107], v[130:131], v[106:107] op_sel_hi:[0,1]
	v_pk_mul_f32 v[104:105], v[130:131], v[104:105] op_sel_hi:[0,1]
	v_or_b32_e32 v112, s54, v167
	v_lshlrev_b32_e32 v114, 1, v112
	v_pk_mul_f32 v[110:111], v[130:131], v[110:111] op_sel_hi:[0,1]
	v_pk_mul_f32 v[108:109], v[130:131], v[108:109] op_sel_hi:[0,1]
	v_max_f32_e32 v104, 0, v104
	v_max_f32_e32 v105, 0, v105
	v_max_f32_e32 v106, 0, v106
	v_or_b32_e32 v144, 0x800, v114
	v_max_f32_e32 v108, 0, v108
	v_mul_f32_e32 v115, v104, v104
	v_max_f32_e32 v104, 0, v109
	v_mul_f32_e32 v109, v105, v105
	v_max_f32_e32 v105, 0, v110
	v_mul_f32_e32 v110, v106, v106
	v_max_f32_e32 v106, 0, v111
	v_lshl_add_u64 v[112:113], s[8:9], 0, v[144:145]
	v_mul_f32_e32 v108, v108, v108
	v_mul_f32_e32 v104, v104, v104
	v_mul_f32_e32 v105, v105, v105
	v_max_f32_e32 v107, 0, v107
	v_mul_f32_e32 v106, v106, v106
	v_pk_mul_f32 v[98:99], v[130:131], v[98:99] op_sel_hi:[0,1]
	v_pk_mul_f32 v[96:97], v[130:131], v[96:97] op_sel_hi:[0,1]
	v_mul_f32_e32 v107, v107, v107
	v_cvt_pk_bf16_f32 v104, v108, v104
	v_cvt_pk_bf16_f32 v105, v105, v106
	v_cvt_pk_bf16_f32 v106, v115, v109
	v_lshl_add_u64 v[108:109], v[112:113], 0, s[0:1]
	v_pk_mul_f32 v[102:103], v[130:131], v[102:103] op_sel_hi:[0,1]
	v_pk_mul_f32 v[100:101], v[130:131], v[100:101] op_sel_hi:[0,1]
	v_max_f32_e32 v96, 0, v96
	v_max_f32_e32 v97, 0, v97
	v_max_f32_e32 v98, 0, v98
	v_cvt_pk_bf16_f32 v107, v110, v107
	global_store_dwordx4 v[108:109], v[104:107], off sc0 sc1
	v_max_f32_e32 v100, 0, v100
	v_mul_f32_e32 v100, v100, v100
	v_mul_f32_e32 v104, v96, v96
	v_max_f32_e32 v96, 0, v101
	v_mul_f32_e32 v101, v97, v97
	v_max_f32_e32 v97, 0, v102
	v_mul_f32_e32 v102, v98, v98
	v_max_f32_e32 v98, 0, v103
	v_mul_f32_e32 v96, v96, v96
	v_mul_f32_e32 v97, v97, v97
	v_max_f32_e32 v99, 0, v99
	v_mul_f32_e32 v98, v98, v98
	v_pk_mul_f32 v[90:91], v[142:143], v[90:91] op_sel_hi:[0,1]
	v_pk_mul_f32 v[88:89], v[142:143], v[88:89] op_sel_hi:[0,1]
	v_mul_f32_e32 v99, v99, v99
	v_cvt_pk_bf16_f32 v96, v100, v96
	v_cvt_pk_bf16_f32 v97, v97, v98
	v_cvt_pk_bf16_f32 v98, v104, v101
	v_lshl_add_u64 v[100:101], v[112:113], 0, s[6:7]
	v_pk_mul_f32 v[94:95], v[142:143], v[94:95] op_sel_hi:[0,1]
	v_pk_mul_f32 v[92:93], v[142:143], v[92:93] op_sel_hi:[0,1]
	v_max_f32_e32 v88, 0, v88
	v_max_f32_e32 v89, 0, v89
	v_max_f32_e32 v90, 0, v90
	v_cvt_pk_bf16_f32 v99, v102, v99
	global_store_dwordx4 v[100:101], v[96:99], off sc0 sc1
	v_max_f32_e32 v92, 0, v92
	v_mul_f32_e32 v92, v92, v92
	v_mul_f32_e32 v98, v88, v88
	v_max_f32_e32 v88, 0, v93
	v_mul_f32_e32 v93, v89, v89
	v_max_f32_e32 v89, 0, v94
	v_mul_f32_e32 v94, v90, v90
	v_max_f32_e32 v90, 0, v95
	v_lshl_add_u64 v[96:97], v[170:171], 0, s[12:13]
	v_mul_f32_e32 v88, v88, v88
	v_mul_f32_e32 v89, v89, v89
	v_max_f32_e32 v91, 0, v91
	v_mul_f32_e32 v90, v90, v90
	v_pk_mul_f32 v[82:83], v[142:143], v[82:83] op_sel_hi:[0,1]
	v_pk_mul_f32 v[80:81], v[142:143], v[80:81] op_sel_hi:[0,1]
	v_mul_f32_e32 v91, v91, v91
; __host__ __device__ __forceinline__ int blk_off(int r, int c) { const int rr = r & 127; return (r >> 7) * 8192 + (((rr >> 4) * 2 + (c >> 5)) * 512) + (rr & 15) * 32 + (c & 31); }
; __device__ __forceinline__ unsigned cvt_pk_bf16(float lo, float hi) { unsigned r; asm volatile("v_cvt_pk_bf16_f32 %0, %1, %2" : "=v"(r) : "v"(lo), "v"(hi)); return r; }
;     __device__ __forceinline__ void operator()(const f32x4 (&acc)[2][2][4][2], const State& st, const Unit& u, int wr, int wc, int fr, int fq) const {
;     ...
;         for (int ai = 0; ai < 2; ++ai)
; #pragma unroll
;             for (int m = 0; m < 4; ++m) { const int row = row0 + ai * HALF + m * 16;
;                 const float rs = rsv[ai][m];
;                 bf16_t* rowp = O + (size_t)(row >> 8) * (ldc >> 6) * (256 * 64);
; #pragma unroll
;                 for (int bj = 0; bj < 2; ++bj) { f32x4 v0 = acc[ai][bj][m][0] * rs, v1 = acc[ai][bj][m][1] * rs;
; #pragma unroll
;                     for (int e = 0; e < 4; ++e) { const float a = fmaxf(v0[e], 0.f), b = fmaxf(v1[e], 0.f); v0[e] = a * a; v1[e] = b * b; }
;                     u32x4 w; w.x = cvt_pk_bf16(v0[0], v0[1]); w.y = cvt_pk_bf16(v0[2], v0[3]); w.z = cvt_pk_bf16(v1[0], v1[1]); w.w = cvt_pk_bf16(v1[2], v1[3]);
;                     { const int col = col0 + bj * HALF; *(u32x4*)(rowp + (size_t)(col >> 6) * (256 * 64) + blk_off(row & 255, col & 63)) = w; } } }
	v_cvt_pk_bf16_f32 v88, v92, v88
	v_cvt_pk_bf16_f32 v89, v89, v90
	v_cvt_pk_bf16_f32 v90, v98, v93
	v_lshl_add_u64 v[92:93], v[96:97], 0, s[0:1]
	v_pk_mul_f32 v[86:87], v[142:143], v[86:87] op_sel_hi:[0,1]
	v_pk_mul_f32 v[84:85], v[142:143], v[84:85] op_sel_hi:[0,1]
	v_max_f32_e32 v80, 0, v80
	v_max_f32_e32 v81, 0, v81
	v_max_f32_e32 v82, 0, v82
	v_cvt_pk_bf16_f32 v91, v94, v91
	global_store_dwordx4 v[92:93], v[88:91], off sc0 sc1
	v_max_f32_e32 v84, 0, v84
	v_mul_f32_e32 v84, v84, v84
	v_mul_f32_e32 v88, v80, v80
	v_max_f32_e32 v80, 0, v85
	v_mul_f32_e32 v85, v81, v81
	v_max_f32_e32 v81, 0, v86
	v_mul_f32_e32 v86, v82, v82
	v_max_f32_e32 v82, 0, v87
	v_mul_f32_e32 v80, v80, v80
	v_mul_f32_e32 v81, v81, v81
	v_max_f32_e32 v83, 0, v83
	v_mul_f32_e32 v82, v82, v82
	v_pk_mul_f32 v[74:75], v[160:161], v[74:75] op_sel_hi:[0,1]
	v_pk_mul_f32 v[72:73], v[160:161], v[72:73] op_sel_hi:[0,1]
	v_mul_f32_e32 v83, v83, v83
	v_cvt_pk_bf16_f32 v80, v84, v80
	v_cvt_pk_bf16_f32 v81, v81, v82
	v_cvt_pk_bf16_f32 v82, v88, v85
	v_lshl_add_u64 v[84:85], v[96:97], 0, s[6:7]
	v_pk_mul_f32 v[78:79], v[160:161], v[78:79] op_sel_hi:[0,1]
	v_pk_mul_f32 v[76:77], v[160:161], v[76:77] op_sel_hi:[0,1]
	v_max_f32_e32 v72, 0, v72
	v_max_f32_e32 v73, 0, v73
	v_max_f32_e32 v74, 0, v74
	v_cvt_pk_bf16_f32 v83, v86, v83
	global_store_dwordx4 v[84:85], v[80:83], off sc0 sc1
	v_or_b32_e32 v144, 0x1800, v114
	v_max_f32_e32 v76, 0, v76
	v_mul_f32_e32 v82, v72, v72
	v_max_f32_e32 v72, 0, v77
	v_mul_f32_e32 v77, v73, v73
	v_max_f32_e32 v73, 0, v78
	v_mul_f32_e32 v78, v74, v74
	v_max_f32_e32 v74, 0, v79
	v_lshl_add_u64 v[80:81], s[8:9], 0, v[144:145]
	v_mul_f32_e32 v76, v76, v76
	v_mul_f32_e32 v72, v72, v72
	v_mul_f32_e32 v73, v73, v73
	v_max_f32_e32 v75, 0, v75
	v_mul_f32_e32 v74, v74, v74
	v_pk_mul_f32 v[66:67], v[160:161], v[66:67] op_sel_hi:[0,1]
	v_pk_mul_f32 v[64:65], v[160:161], v[64:65] op_sel_hi:[0,1]
	v_mul_f32_e32 v75, v75, v75
	v_cvt_pk_bf16_f32 v72, v76, v72
	v_cvt_pk_bf16_f32 v73, v73, v74
	v_cvt_pk_bf16_f32 v74, v82, v77
	v_lshl_add_u64 v[76:77], v[80:81], 0, s[0:1]
	v_pk_mul_f32 v[70:71], v[160:161], v[70:71] op_sel_hi:[0,1]
	v_pk_mul_f32 v[68:69], v[160:161], v[68:69] op_sel_hi:[0,1]
	v_max_f32_e32 v64, 0, v64
	v_max_f32_e32 v65, 0, v65
	v_max_f32_e32 v66, 0, v66
	v_cvt_pk_bf16_f32 v75, v78, v75
	global_store_dwordx4 v[76:77], v[72:75], off sc0 sc1
	v_max_f32_e32 v68, 0, v68
	v_mul_f32_e32 v68, v68, v68
	v_mul_f32_e32 v72, v64, v64
	v_max_f32_e32 v64, 0, v69
	v_mul_f32_e32 v69, v65, v65
	v_max_f32_e32 v65, 0, v70
	v_mul_f32_e32 v70, v66, v66
	v_max_f32_e32 v66, 0, v71
	v_mul_f32_e32 v64, v64, v64
	v_mul_f32_e32 v65, v65, v65
	v_max_f32_e32 v67, 0, v67
	v_mul_f32_e32 v66, v66, v66
	v_mul_f32_e32 v67, v67, v67
	v_cvt_pk_bf16_f32 v64, v68, v64
	v_cvt_pk_bf16_f32 v65, v65, v66
	v_cvt_pk_bf16_f32 v66, v72, v69
	v_lshl_add_u64 v[68:69], v[80:81], 0, s[6:7]
	v_cvt_pk_bf16_f32 v67, v70, v67
	global_store_dwordx4 v[68:69], v[64:67], off sc0 sc1
	v_pk_mul_f32 v[58:59], v[162:163], v[58:59] op_sel_hi:[0,1]
	v_pk_mul_f32 v[56:57], v[162:163], v[56:57] op_sel_hi:[0,1]
	v_add_u32_e32 v66, 0x80, v165
	v_ashrrev_i32_e32 v64, 8, v66
	v_lshlrev_b32_e32 v67, 6, v66
	v_lshlrev_b32_e32 v66, 5, v66
	v_and_b32_e32 v67, 0x2000, v67
	v_and_b32_e32 v66, 0x1e0, v66
	v_ashrrev_i32_e32 v65, 31, v64
	v_or3_b32 v68, v67, v66, v131
	v_lshlrev_b64 v[64:65], 22, v[64:65]
	v_or_b32_e32 v66, s53, v68
	v_pk_mul_f32 v[62:63], v[162:163], v[62:63] op_sel_hi:[0,1]
	v_pk_mul_f32 v[60:61], v[162:163], v[60:61] op_sel_hi:[0,1]
	v_max_f32_e32 v56, 0, v56
	v_max_f32_e32 v57, 0, v57
	v_max_f32_e32 v58, 0, v58
	v_lshl_add_u64 v[64:65], s[18:19], 0, v[64:65]
	v_lshlrev_b32_e32 v144, 1, v66
	v_max_f32_e32 v60, 0, v60
	v_mul_f32_e32 v69, v56, v56
	v_max_f32_e32 v56, 0, v61
	v_mul_f32_e32 v61, v57, v57
	v_max_f32_e32 v57, 0, v62
	v_mul_f32_e32 v62, v58, v58
	v_max_f32_e32 v58, 0, v63
	v_lshl_add_u64 v[66:67], v[64:65], 0, v[144:145]
	v_mul_f32_e32 v60, v60, v60
	v_mul_f32_e32 v56, v56, v56
	v_mul_f32_e32 v57, v57, v57
	v_max_f32_e32 v59, 0, v59
	v_mul_f32_e32 v58, v58, v58
	v_pk_mul_f32 v[50:51], v[162:163], v[50:51] op_sel_hi:[0,1]
	v_pk_mul_f32 v[48:49], v[162:163], v[48:49] op_sel_hi:[0,1]
	v_mul_f32_e32 v59, v59, v59
	v_cvt_pk_bf16_f32 v56, v60, v56
	v_cvt_pk_bf16_f32 v57, v57, v58
	v_cvt_pk_bf16_f32 v58, v69, v61
	v_lshl_add_u64 v[60:61], v[66:67], 0, s[0:1]
	v_pk_mul_f32 v[54:55], v[162:163], v[54:55] op_sel_hi:[0,1]
	v_pk_mul_f32 v[52:53], v[162:163], v[52:53] op_sel_hi:[0,1]
	v_max_f32_e32 v48, 0, v48
	v_max_f32_e32 v49, 0, v49
	v_max_f32_e32 v50, 0, v50
	v_cvt_pk_bf16_f32 v59, v62, v59
	global_store_dwordx4 v[60:61], v[56:59], off sc0 sc1
	v_max_f32_e32 v52, 0, v52
	v_mul_f32_e32 v52, v52, v52
	v_mul_f32_e32 v56, v48, v48
	v_max_f32_e32 v48, 0, v53
	v_mul_f32_e32 v53, v49, v49
	v_max_f32_e32 v49, 0, v54
	v_mul_f32_e32 v54, v50, v50
	v_max_f32_e32 v50, 0, v55
	v_mul_f32_e32 v48, v48, v48
	v_mul_f32_e32 v49, v49, v49
	v_max_f32_e32 v51, 0, v51
	v_mul_f32_e32 v50, v50, v50
	v_mul_f32_e32 v51, v51, v51
	v_cvt_pk_bf16_f32 v48, v52, v48
	v_cvt_pk_bf16_f32 v49, v49, v50
	v_cvt_pk_bf16_f32 v50, v56, v53
	v_lshl_add_u64 v[52:53], v[66:67], 0, s[6:7]
	v_cvt_pk_bf16_f32 v51, v54, v51
	global_store_dwordx4 v[52:53], v[48:51], off sc0 sc1
	v_pk_mul_f32 v[42:43], v[164:165], v[42:43] op_sel_hi:[0,1]
	v_pk_mul_f32 v[40:41], v[164:165], v[40:41] op_sel_hi:[0,1]
	v_or_b32_e32 v48, s54, v68
	v_lshlrev_b32_e32 v50, 1, v48
	v_pk_mul_f32 v[46:47], v[164:165], v[46:47] op_sel_hi:[0,1]
	v_pk_mul_f32 v[44:45], v[164:165], v[44:45] op_sel_hi:[0,1]
	v_max_f32_e32 v40, 0, v40
	v_max_f32_e32 v41, 0, v41
	v_max_f32_e32 v42, 0, v42
; __host__ __device__ __forceinline__ int blk_off(int r, int c) { const int rr = r & 127; return (r >> 7) * 8192 + (((rr >> 4) * 2 + (c >> 5)) * 512) + (rr & 15) * 32 + (c & 31); }
; __device__ __forceinline__ unsigned cvt_pk_bf16(float lo, float hi) { unsigned r; asm volatile("v_cvt_pk_bf16_f32 %0, %1, %2" : "=v"(r) : "v"(lo), "v"(hi)); return r; }
;     __device__ __forceinline__ void operator()(const f32x4 (&acc)[2][2][4][2], const State& st, const Unit& u, int wr, int wc, int fr, int fq) const {
;     ...
;         for (int ai = 0; ai < 2; ++ai)
; #pragma unroll
;             for (int m = 0; m < 4; ++m) { const int row = row0 + ai * HALF + m * 16;
;                 const float rs = rsv[ai][m];
;                 bf16_t* rowp = O + (size_t)(row >> 8) * (ldc >> 6) * (256 * 64);
; #pragma unroll
;                 for (int bj = 0; bj < 2; ++bj) { f32x4 v0 = acc[ai][bj][m][0] * rs, v1 = acc[ai][bj][m][1] * rs;
; #pragma unroll
;                     for (int e = 0; e < 4; ++e) { const float a = fmaxf(v0[e], 0.f), b = fmaxf(v1[e], 0.f); v0[e] = a * a; v1[e] = b * b; }
;                     u32x4 w; w.x = cvt_pk_bf16(v0[0], v0[1]); w.y = cvt_pk_bf16(v0[2], v0[3]); w.z = cvt_pk_bf16(v1[0], v1[1]); w.w = cvt_pk_bf16(v1[2], v1[3]);
;                     { const int col = col0 + bj * HALF; *(u32x4*)(rowp + (size_t)(col >> 6) * (256 * 64) + blk_off(row & 255, col & 63)) = w; } } }
; template <class Epi, class Sched, bool ALIGN_EPI = false, bool SP2 = false>
; __device__ __forceinline__ void gemm_phase(PG8_LAS unsigned char* lds, const Gemm g, const Sched& S, const Epi& E) {
;     ...
;         if (!has_next) break;
;         E.init(acc, est, nxt, wr, wc, fr, fq);
	v_or_b32_e32 v144, 0x800, v50
	v_max_f32_e32 v44, 0, v44
	v_mul_f32_e32 v51, v40, v40
	v_max_f32_e32 v40, 0, v45
	v_mul_f32_e32 v45, v41, v41
	v_max_f32_e32 v41, 0, v46
	v_mul_f32_e32 v46, v42, v42
	v_max_f32_e32 v42, 0, v47
	v_lshl_add_u64 v[48:49], v[64:65], 0, v[144:145]
	v_mul_f32_e32 v44, v44, v44
	v_mul_f32_e32 v40, v40, v40
	v_mul_f32_e32 v41, v41, v41
	v_max_f32_e32 v43, 0, v43
	v_mul_f32_e32 v42, v42, v42
	v_pk_mul_f32 v[34:35], v[164:165], v[34:35] op_sel_hi:[0,1]
	v_pk_mul_f32 v[32:33], v[164:165], v[32:33] op_sel_hi:[0,1]
	v_mul_f32_e32 v43, v43, v43
	v_cvt_pk_bf16_f32 v40, v44, v40
	v_cvt_pk_bf16_f32 v41, v41, v42
	v_cvt_pk_bf16_f32 v42, v51, v45
	v_lshl_add_u64 v[44:45], v[48:49], 0, s[0:1]
	v_pk_mul_f32 v[38:39], v[164:165], v[38:39] op_sel_hi:[0,1]
	v_pk_mul_f32 v[36:37], v[164:165], v[36:37] op_sel_hi:[0,1]
	v_max_f32_e32 v32, 0, v32
	v_max_f32_e32 v33, 0, v33
	v_max_f32_e32 v34, 0, v34
	v_cvt_pk_bf16_f32 v43, v46, v43
	global_store_dwordx4 v[44:45], v[40:43], off sc0 sc1
	v_max_f32_e32 v36, 0, v36
	v_mul_f32_e32 v36, v36, v36
	v_mul_f32_e32 v40, v32, v32
	v_max_f32_e32 v32, 0, v37
	v_mul_f32_e32 v37, v33, v33
	v_max_f32_e32 v33, 0, v38
	v_mul_f32_e32 v38, v34, v34
	v_max_f32_e32 v34, 0, v39
	v_mul_f32_e32 v32, v32, v32
	v_mul_f32_e32 v33, v33, v33
	v_max_f32_e32 v35, 0, v35
	v_mul_f32_e32 v34, v34, v34
	v_pk_mul_f32 v[26:27], v[166:167], v[26:27] op_sel_hi:[0,1]
	v_pk_mul_f32 v[24:25], v[166:167], v[24:25] op_sel_hi:[0,1]
	v_mul_f32_e32 v35, v35, v35
	v_cvt_pk_bf16_f32 v32, v36, v32
	v_cvt_pk_bf16_f32 v33, v33, v34
	v_cvt_pk_bf16_f32 v34, v40, v37
	v_lshl_add_u64 v[36:37], v[48:49], 0, s[6:7]
	v_pk_mul_f32 v[30:31], v[166:167], v[30:31] op_sel_hi:[0,1]
	v_pk_mul_f32 v[28:29], v[166:167], v[28:29] op_sel_hi:[0,1]
	v_max_f32_e32 v24, 0, v24
	v_max_f32_e32 v25, 0, v25
	v_max_f32_e32 v26, 0, v26
	v_cvt_pk_bf16_f32 v35, v38, v35
	global_store_dwordx4 v[36:37], v[32:35], off sc0 sc1
	v_max_f32_e32 v28, 0, v28
	v_mul_f32_e32 v28, v28, v28
	v_mul_f32_e32 v34, v24, v24
	v_max_f32_e32 v24, 0, v29
	v_mul_f32_e32 v29, v25, v25
	v_max_f32_e32 v25, 0, v30
	v_mul_f32_e32 v30, v26, v26
	v_max_f32_e32 v26, 0, v31
	v_lshl_add_u64 v[32:33], v[66:67], 0, s[12:13]
	v_mul_f32_e32 v24, v24, v24
	v_mul_f32_e32 v25, v25, v25
	v_max_f32_e32 v27, 0, v27
	v_mul_f32_e32 v26, v26, v26
	v_pk_mul_f32 v[18:19], v[166:167], v[18:19] op_sel_hi:[0,1]
	v_pk_mul_f32 v[16:17], v[166:167], v[16:17] op_sel_hi:[0,1]
	v_mul_f32_e32 v27, v27, v27
	v_cvt_pk_bf16_f32 v24, v28, v24
	v_cvt_pk_bf16_f32 v25, v25, v26
	v_cvt_pk_bf16_f32 v26, v34, v29
	v_lshl_add_u64 v[28:29], v[32:33], 0, s[0:1]
	v_pk_mul_f32 v[22:23], v[166:167], v[22:23] op_sel_hi:[0,1]
	v_pk_mul_f32 v[20:21], v[166:167], v[20:21] op_sel_hi:[0,1]
	v_max_f32_e32 v16, 0, v16
	v_max_f32_e32 v17, 0, v17
	v_max_f32_e32 v18, 0, v18
	v_cvt_pk_bf16_f32 v27, v30, v27
	global_store_dwordx4 v[28:29], v[24:27], off sc0 sc1
	v_max_f32_e32 v20, 0, v20
	v_mul_f32_e32 v20, v20, v20
	v_mul_f32_e32 v24, v16, v16
	v_max_f32_e32 v16, 0, v21
	v_mul_f32_e32 v21, v17, v17
	v_max_f32_e32 v17, 0, v22
	v_mul_f32_e32 v22, v18, v18
	v_max_f32_e32 v18, 0, v23
	v_mul_f32_e32 v16, v16, v16
	v_mul_f32_e32 v17, v17, v17
	v_max_f32_e32 v19, 0, v19
	v_mul_f32_e32 v18, v18, v18
	v_pk_mul_f32 v[10:11], v[168:169], v[10:11] op_sel_hi:[0,1]
	v_pk_mul_f32 v[8:9], v[168:169], v[8:9] op_sel_hi:[0,1]
	v_mul_f32_e32 v19, v19, v19
	v_cvt_pk_bf16_f32 v16, v20, v16
	v_cvt_pk_bf16_f32 v17, v17, v18
	v_cvt_pk_bf16_f32 v18, v24, v21
	v_lshl_add_u64 v[20:21], v[32:33], 0, s[6:7]
	v_pk_mul_f32 v[14:15], v[168:169], v[14:15] op_sel_hi:[0,1]
	v_pk_mul_f32 v[12:13], v[168:169], v[12:13] op_sel_hi:[0,1]
	v_max_f32_e32 v8, 0, v8
	v_max_f32_e32 v9, 0, v9
	v_max_f32_e32 v10, 0, v10
	v_cvt_pk_bf16_f32 v19, v22, v19
	global_store_dwordx4 v[20:21], v[16:19], off sc0 sc1
	v_or_b32_e32 v144, 0x1800, v50
	v_max_f32_e32 v12, 0, v12
	v_mul_f32_e32 v18, v8, v8
	v_max_f32_e32 v8, 0, v13
	v_mul_f32_e32 v13, v9, v9
	v_max_f32_e32 v9, 0, v14
	v_mul_f32_e32 v14, v10, v10
	v_max_f32_e32 v10, 0, v15
	v_lshl_add_u64 v[16:17], v[64:65], 0, v[144:145]
	v_mul_f32_e32 v12, v12, v12
	v_mul_f32_e32 v8, v8, v8
	v_mul_f32_e32 v9, v9, v9
	v_max_f32_e32 v11, 0, v11
	v_mul_f32_e32 v10, v10, v10
	v_pk_mul_f32 v[2:3], v[168:169], v[2:3] op_sel_hi:[0,1]
	v_pk_mul_f32 v[0:1], v[168:169], v[0:1] op_sel_hi:[0,1]
	v_mul_f32_e32 v11, v11, v11
	v_cvt_pk_bf16_f32 v8, v12, v8
	v_cvt_pk_bf16_f32 v9, v9, v10
	v_cvt_pk_bf16_f32 v10, v18, v13
	v_lshl_add_u64 v[12:13], v[16:17], 0, s[0:1]
	v_pk_mul_f32 v[6:7], v[168:169], v[6:7] op_sel_hi:[0,1]
	v_pk_mul_f32 v[4:5], v[168:169], v[4:5] op_sel_hi:[0,1]
	v_max_f32_e32 v0, 0, v0
	v_max_f32_e32 v1, 0, v1
	v_max_f32_e32 v2, 0, v2
	v_cvt_pk_bf16_f32 v11, v14, v11
	global_store_dwordx4 v[12:13], v[8:11], off sc0 sc1
	v_max_f32_e32 v4, 0, v4
	v_mul_f32_e32 v4, v4, v4
	v_mul_f32_e32 v8, v0, v0
	v_max_f32_e32 v0, 0, v5
	v_mul_f32_e32 v5, v1, v1
	v_max_f32_e32 v1, 0, v6
	v_mul_f32_e32 v6, v2, v2
	v_max_f32_e32 v2, 0, v7
	v_mul_f32_e32 v0, v0, v0
	v_mul_f32_e32 v1, v1, v1
	v_max_f32_e32 v3, 0, v3
	v_mul_f32_e32 v2, v2, v2
	v_mul_f32_e32 v3, v3, v3
	v_cvt_pk_bf16_f32 v0, v4, v0
	v_cvt_pk_bf16_f32 v1, v1, v2
	v_cvt_pk_bf16_f32 v2, v8, v5
	v_lshl_add_u64 v[4:5], v[16:17], 0, s[6:7]
	s_andn2_b64 vcc, exec, s[38:39]
	s_mov_b64 s[0:1], -1
	v_cvt_pk_bf16_f32 v3, v6, v3
	global_store_dwordx4 v[4:5], v[0:3], off sc0 sc1
	s_cbranch_vccnz .LBB0_545
	s_cmp_eq_u32 s56, s40
	s_cbranch_scc1 .LBB0_559
; __device__ __forceinline__ void rows_rstd(float (&rs)[2][4], const float* ssq, int row0, int fq) {
;     f32x4 pa[2][4], pb[2][4];
; #pragma unroll
;     for (int ai = 0; ai < 2; ++ai)
; #pragma unroll
;         for (int m = 0; m < 4; ++m) { const f32x4* p = (const f32x4*)(ssq + (size_t)(row0 + ai * HALF + m * 16) * 32 + 8 * fq); pa[ai][m] = p[0]; pb[ai][m] = p[1]; }
; #pragma unroll
;     for (int ai = 0; ai < 2; ++ai)
; #pragma unroll
;         for (int m = 0; m < 4; ++m) { const f32x4 a = pa[ai][m] + pb[ai][m]; float t = (a[0] + a[1]) + (a[2] + a[3]);
;             t += __shfl_xor(t, 16); t += __shfl_xor(t, 32); rs[ai][m] = 1.0f / sqrtf(t * (1.0f / 2048.0f) + RMS_EPS); }
; }
;     __device__ __forceinline__ void init(f32x4 (&acc)[2][2][4][2], State& st, const Unit& u, int wr, int, int fr, int fq) const { zero_acc(acc);
;         if (st.pm != u.pm) { float t[2][4]; rows_rstd(t, ssq, u.pm * BM + wr * 64 + fr, fq); st.ra = (f32x4){t[0][0], t[0][1], t[0][2], t[0][3]}; st.rb = (f32x4){t[1][0], t[1][1], t[1][2], t[1][3]}; st.pm = u.pm; } }
	v_lshl_add_u32 v0, s40, 8, v143
	v_ashrrev_i32_e32 v1, 31, v0
	v_lshlrev_b64 v[2:3], 7, v[0:1]
	v_lshl_add_u64 v[2:3], v[136:137], 0, v[2:3]
	global_load_dwordx4 v[58:61], v[2:3], off
	global_load_dwordx4 v[62:65], v[2:3], off offset:16
	v_or_b32_e32 v4, 16, v0
	v_ashrrev_i32_e32 v5, 31, v4
	v_lshlrev_b64 v[4:5], 7, v[4:5]
	v_lshl_add_u64 v[4:5], v[136:137], 0, v[4:5]
	global_load_dwordx4 v[48:51], v[4:5], off
	global_load_dwordx4 v[52:55], v[4:5], off offset:16
	v_or_b32_e32 v4, 32, v0
	v_ashrrev_i32_e32 v5, 31, v4
	v_lshlrev_b64 v[4:5], 7, v[4:5]
	v_lshl_add_u64 v[4:5], v[136:137], 0, v[4:5]
	global_load_dwordx4 v[40:43], v[4:5], off
	global_load_dwordx4 v[44:47], v[4:5], off offset:16
	v_or_b32_e32 v0, 48, v0
	v_ashrrev_i32_e32 v1, 31, v0
	v_lshlrev_b64 v[0:1], 7, v[0:1]
	v_lshl_add_u64 v[0:1], v[136:137], 0, v[0:1]
	s_mov_b64 s[0:1], 0x4000
	global_load_dwordx4 v[32:35], v[0:1], off
	global_load_dwordx4 v[36:39], v[0:1], off offset:16
	v_lshl_add_u64 v[0:1], v[2:3], 0, s[0:1]
	s_movk_i32 s0, 0x4000
	v_add_co_u32_e32 v4, vcc, s0, v2
	s_movk_i32 s0, 0x5000
	s_nop 0
	v_addc_co_u32_e32 v5, vcc, 0, v3, vcc
	v_add_co_u32_e32 v6, vcc, s0, v2
	s_mov_b64 s[0:1], 0x4800
	s_nop 0
	v_addc_co_u32_e32 v7, vcc, 0, v3, vcc
	v_cmp_lt_i32_e32 vcc, v191, v192
	global_load_dwordx4 v[24:27], v[6:7], off offset:-4096
	global_load_dwordx4 v[28:31], v[0:1], off offset:16
	v_cndmask_b32_e32 v56, v190, v191, vcc
	v_lshlrev_b32_e32 v56, 2, v56
	v_cmp_lt_i32_e32 vcc, v193, v192
	v_lshl_add_u64 v[0:1], v[2:3], 0, s[0:1]
	s_mov_b64 s[0:1], 0x5000
	v_cndmask_b32_e32 v57, v190, v193, vcc
	v_lshlrev_b32_e32 v57, 2, v57
	global_load_dwordx4 v[16:19], v[4:5], off offset:2048
	global_load_dwordx4 v[20:23], v[0:1], off offset:16
	v_lshl_add_u64 v[0:1], v[2:3], 0, s[0:1]
	s_mov_b64 s[0:1], 0x5800
	v_lshl_add_u64 v[4:5], v[2:3], 0, s[0:1]
	global_load_dwordx4 v[8:11], v[6:7], off
	global_load_dwordx4 v[12:15], v[0:1], off offset:16
	s_nop 0
	global_load_dwordx4 v[0:3], v[6:7], off offset:2048
	s_nop 0
	global_load_dwordx4 v[4:7], v[4:5], off offset:16
	s_mov_b32 s56, s40
	s_waitcnt vmcnt(0)
	v_pk_add_f32 v[60:61], v[60:61], v[64:65]
	v_pk_add_f32 v[58:59], v[58:59], v[62:63]
	v_pk_add_f32 v[50:51], v[50:51], v[54:55]
	v_pk_mov_b32 v[62:63], v[58:59], v[60:61] op_sel:[1,0]
	v_mov_b32_e32 v59, v61
	v_pk_add_f32 v[58:59], v[62:63], v[58:59]
	v_pk_add_f32 v[48:49], v[48:49], v[52:53]
	v_add_f32_e32 v58, v58, v59
	ds_bpermute_b32 v59, v56, v58
	v_pk_mov_b32 v[52:53], v[48:49], v[50:51] op_sel:[1,0]
	v_mov_b32_e32 v49, v51
	v_pk_add_f32 v[48:49], v[52:53], v[48:49]
	v_pk_add_f32 v[42:43], v[42:43], v[46:47]
	s_waitcnt lgkmcnt(0)
	v_add_f32_e32 v58, v58, v59
	ds_bpermute_b32 v59, v57, v58
	v_add_f32_e32 v48, v48, v49
	ds_bpermute_b32 v49, v56, v48
	v_pk_add_f32 v[40:41], v[40:41], v[44:45]
	v_pk_add_f32 v[34:35], v[34:35], v[38:39]
	s_waitcnt lgkmcnt(1)
	v_add_f32_e32 v58, v58, v59
	v_fmamk_f32 v58, v58, 0x3a000000, v186
	v_cmp_gt_f32_e32 vcc, s65, v58
	v_mul_f32_e32 v59, 0x4f800000, v58
	s_waitcnt lgkmcnt(0)
	v_add_f32_e32 v48, v48, v49
	v_cndmask_b32_e32 v58, v58, v59, vcc
	v_sqrt_f32_e32 v59, v58
	ds_bpermute_b32 v49, v57, v48
	v_pk_mov_b32 v[44:45], v[40:41], v[42:43] op_sel:[1,0]
	v_mov_b32_e32 v41, v43
	v_add_u32_e32 v60, -1, v59
	v_fma_f32 v61, -v60, v59, v58
	v_cmp_ge_f32_e64 s[38:39], 0, v61
	v_add_u32_e32 v61, 1, v59
	s_waitcnt lgkmcnt(0)
	v_add_f32_e32 v48, v48, v49
	v_cndmask_b32_e64 v60, v59, v60, s[38:39]
	v_fma_f32 v59, -v61, v59, v58
	v_cmp_lt_f32_e64 s[38:39], 0, v59
	v_fmamk_f32 v48, v48, 0x3a000000, v186
	v_mul_f32_e32 v49, 0x4f800000, v48
	v_cndmask_b32_e64 v59, v60, v61, s[38:39]
	v_mul_f32_e32 v60, 0x37800000, v59
	v_cndmask_b32_e32 v59, v59, v60, vcc
	v_cmp_class_f32_e32 vcc, v58, v187
	v_pk_add_f32 v[40:41], v[44:45], v[40:41]
	v_pk_add_f32 v[32:33], v[32:33], v[36:37]
	v_cndmask_b32_e32 v58, v59, v58, vcc
	v_div_scale_f32 v59, s[0:1], v58, v58, 1.0
	v_rcp_f32_e32 v60, v59
	v_add_f32_e32 v40, v40, v41
	ds_bpermute_b32 v41, v56, v40
	v_pk_mov_b32 v[36:37], v[32:33], v[34:35] op_sel:[1,0]
	v_fma_f32 v61, -v59, v60, 1.0
	v_fmac_f32_e32 v60, v61, v60
	v_div_scale_f32 v61, vcc, 1.0, v58, 1.0
	v_mul_f32_e32 v62, v61, v60
	v_fma_f32 v63, -v59, v62, v61
	v_fmac_f32_e32 v62, v63, v60
	v_fma_f32 v59, -v59, v62, v61
	v_div_fmas_f32 v59, v59, v60, v62
	v_cmp_gt_f32_e32 vcc, s65, v48
	s_waitcnt lgkmcnt(0)
	v_add_f32_e32 v40, v40, v41
	ds_bpermute_b32 v41, v57, v40
	v_cndmask_b32_e32 v48, v48, v49, vcc
	v_sqrt_f32_e32 v49, v48
	v_mov_b32_e32 v33, v35
	v_pk_add_f32 v[32:33], v[36:37], v[32:33]
	s_waitcnt lgkmcnt(0)
	v_add_f32_e32 v40, v40, v41
	v_add_u32_e32 v50, -1, v49
	v_fma_f32 v51, -v50, v49, v48
	v_cmp_ge_f32_e64 s[38:39], 0, v51
	v_add_u32_e32 v51, 1, v49
	v_fmamk_f32 v40, v40, 0x3a000000, v186
	v_cndmask_b32_e64 v50, v49, v50, s[38:39]
	v_fma_f32 v49, -v51, v49, v48
	v_cmp_lt_f32_e64 s[38:39], 0, v49
	v_mul_f32_e32 v41, 0x4f800000, v40
	v_add_f32_e32 v32, v32, v33
	v_cndmask_b32_e64 v49, v50, v51, s[38:39]
	v_mul_f32_e32 v50, 0x37800000, v49
	v_cndmask_b32_e32 v49, v49, v50, vcc
	v_cmp_class_f32_e32 vcc, v48, v187
	ds_bpermute_b32 v33, v56, v32
	v_pk_add_f32 v[26:27], v[26:27], v[30:31]
	v_cndmask_b32_e32 v48, v49, v48, vcc
	v_div_scale_f32 v49, s[0:1], v48, v48, 1.0
	v_rcp_f32_e32 v50, v49
	s_waitcnt lgkmcnt(0)
	v_add_f32_e32 v32, v32, v33
	ds_bpermute_b32 v33, v57, v32
	v_pk_add_f32 v[24:25], v[24:25], v[28:29]
	v_fma_f32 v51, -v49, v50, 1.0
	v_fmac_f32_e32 v50, v51, v50
	v_div_scale_f32 v51, vcc, 1.0, v48, 1.0
	v_mul_f32_e32 v52, v51, v50
	v_fma_f32 v53, -v49, v52, v51
	v_fmac_f32_e32 v52, v53, v50
	v_fma_f32 v49, -v49, v52, v51
	v_div_fmas_f32 v49, v49, v50, v52
	v_cmp_gt_f32_e32 vcc, s65, v40
	s_waitcnt lgkmcnt(0)
; __device__ __forceinline__ void rows_rstd(float (&rs)[2][4], const float* ssq, int row0, int fq) {
;     ...
;     for (int ai = 0; ai < 2; ++ai)
; #pragma unroll
;         for (int m = 0; m < 4; ++m) { const f32x4 a = pa[ai][m] + pb[ai][m]; float t = (a[0] + a[1]) + (a[2] + a[3]);
;             t += __shfl_xor(t, 16); t += __shfl_xor(t, 32); rs[ai][m] = 1.0f / sqrtf(t * (1.0f / 2048.0f) + RMS_EPS); }
	v_add_f32_e32 v32, v32, v33
	v_fmamk_f32 v32, v32, 0x3a000000, v186
	v_cndmask_b32_e32 v40, v40, v41, vcc
	v_sqrt_f32_e32 v41, v40
	v_mul_f32_e32 v33, 0x4f800000, v32
	v_pk_mov_b32 v[28:29], v[24:25], v[26:27] op_sel:[1,0]
	v_mov_b32_e32 v25, v27
	v_add_u32_e32 v42, -1, v41
	v_fma_f32 v43, -v42, v41, v40
	v_cmp_ge_f32_e64 s[38:39], 0, v43
	v_add_u32_e32 v43, 1, v41
	v_pk_add_f32 v[24:25], v[28:29], v[24:25]
	v_cndmask_b32_e64 v42, v41, v42, s[38:39]
	v_fma_f32 v41, -v43, v41, v40
	v_cmp_lt_f32_e64 s[38:39], 0, v41
	v_add_f32_e32 v24, v24, v25
	ds_bpermute_b32 v25, v56, v24
	v_cndmask_b32_e64 v41, v42, v43, s[38:39]
	v_mul_f32_e32 v42, 0x37800000, v41
	v_cndmask_b32_e32 v41, v41, v42, vcc
	v_cmp_class_f32_e32 vcc, v40, v187
	s_waitcnt lgkmcnt(0)
	v_add_f32_e32 v24, v24, v25
	ds_bpermute_b32 v25, v57, v24
	v_cndmask_b32_e32 v40, v41, v40, vcc
	v_div_scale_f32 v41, s[0:1], v40, v40, 1.0
	v_rcp_f32_e32 v42, v41
	s_waitcnt lgkmcnt(0)
	v_add_f32_e32 v24, v24, v25
	v_fmamk_f32 v24, v24, 0x3a000000, v186
	v_mul_f32_e32 v25, 0x4f800000, v24
	v_fma_f32 v43, -v41, v42, 1.0
	v_fmac_f32_e32 v42, v43, v42
	v_div_scale_f32 v43, vcc, 1.0, v40, 1.0
	v_mul_f32_e32 v44, v43, v42
	v_fma_f32 v45, -v41, v44, v43
	v_fmac_f32_e32 v44, v45, v42
	v_fma_f32 v41, -v41, v44, v43
	v_div_fmas_f32 v41, v41, v42, v44
	v_cmp_gt_f32_e32 vcc, s65, v32
	v_pk_add_f32 v[18:19], v[18:19], v[22:23]
	v_pk_add_f32 v[16:17], v[16:17], v[20:21]
	v_cndmask_b32_e32 v32, v32, v33, vcc
	v_sqrt_f32_e32 v33, v32
	v_pk_mov_b32 v[20:21], v[16:17], v[18:19] op_sel:[1,0]
	v_mov_b32_e32 v17, v19
	v_pk_add_f32 v[16:17], v[20:21], v[16:17]
	v_add_u32_e32 v34, -1, v33
	v_fma_f32 v35, -v34, v33, v32
	v_cmp_ge_f32_e64 s[38:39], 0, v35
	v_add_u32_e32 v35, 1, v33
	v_add_f32_e32 v16, v16, v17
	v_cndmask_b32_e64 v34, v33, v34, s[38:39]
	v_fma_f32 v33, -v35, v33, v32
	v_cmp_lt_f32_e64 s[38:39], 0, v33
	ds_bpermute_b32 v17, v56, v16
	v_pk_add_f32 v[10:11], v[10:11], v[14:15]
	v_cndmask_b32_e64 v33, v34, v35, s[38:39]
	v_mul_f32_e32 v34, 0x37800000, v33
	v_cndmask_b32_e32 v33, v33, v34, vcc
	v_cmp_class_f32_e32 vcc, v32, v187
	s_waitcnt lgkmcnt(0)
	v_add_f32_e32 v16, v16, v17
	ds_bpermute_b32 v17, v57, v16
	v_cndmask_b32_e32 v32, v33, v32, vcc
	v_div_scale_f32 v33, s[0:1], v32, v32, 1.0
	v_rcp_f32_e32 v34, v33
	s_waitcnt lgkmcnt(0)
	v_add_f32_e32 v16, v16, v17
	v_fmamk_f32 v16, v16, 0x3a000000, v186
	v_mul_f32_e32 v17, 0x4f800000, v16
	v_fma_f32 v35, -v33, v34, 1.0
	v_fmac_f32_e32 v34, v35, v34
	v_div_scale_f32 v35, vcc, 1.0, v32, 1.0
	v_mul_f32_e32 v36, v35, v34
	v_fma_f32 v37, -v33, v36, v35
	v_fmac_f32_e32 v36, v37, v34
	v_fma_f32 v33, -v33, v36, v35
	v_div_fmas_f32 v33, v33, v34, v36
	v_cmp_gt_f32_e32 vcc, s65, v24
	v_pk_add_f32 v[8:9], v[8:9], v[12:13]
	v_pk_add_f32 v[2:3], v[2:3], v[6:7]
	v_cndmask_b32_e32 v24, v24, v25, vcc
	v_sqrt_f32_e32 v25, v24
	v_pk_mov_b32 v[12:13], v[8:9], v[10:11] op_sel:[1,0]
	v_mov_b32_e32 v9, v11
	v_pk_add_f32 v[8:9], v[12:13], v[8:9]
	v_add_u32_e32 v26, -1, v25
	v_fma_f32 v27, -v26, v25, v24
	v_cmp_ge_f32_e64 s[38:39], 0, v27
	v_add_u32_e32 v27, 1, v25
	v_add_f32_e32 v8, v8, v9
	v_cndmask_b32_e64 v26, v25, v26, s[38:39]
	v_fma_f32 v25, -v27, v25, v24
	v_cmp_lt_f32_e64 s[38:39], 0, v25
	ds_bpermute_b32 v9, v56, v8
	v_pk_add_f32 v[0:1], v[0:1], v[4:5]
	v_cndmask_b32_e64 v25, v26, v27, s[38:39]
	v_mul_f32_e32 v26, 0x37800000, v25
	v_cndmask_b32_e32 v25, v25, v26, vcc
	v_cmp_class_f32_e32 vcc, v24, v187
	s_waitcnt lgkmcnt(0)
	v_add_f32_e32 v8, v8, v9
	ds_bpermute_b32 v9, v57, v8
	v_cndmask_b32_e32 v24, v25, v24, vcc
	v_div_scale_f32 v25, s[0:1], v24, v24, 1.0
	v_rcp_f32_e32 v26, v25
	s_waitcnt lgkmcnt(0)
; __device__ __forceinline__ void rows_rstd(float (&rs)[2][4], const float* ssq, int row0, int fq) {
;     ...
;     for (int ai = 0; ai < 2; ++ai)
; #pragma unroll
;         for (int m = 0; m < 4; ++m) { const f32x4 a = pa[ai][m] + pb[ai][m]; float t = (a[0] + a[1]) + (a[2] + a[3]);
;             t += __shfl_xor(t, 16); t += __shfl_xor(t, 32); rs[ai][m] = 1.0f / sqrtf(t * (1.0f / 2048.0f) + RMS_EPS); }
	v_add_f32_e32 v8, v8, v9
	v_fmamk_f32 v8, v8, 0x3a000000, v186
	v_mul_f32_e32 v9, 0x4f800000, v8
	v_fma_f32 v27, -v25, v26, 1.0
	v_fmac_f32_e32 v26, v27, v26
	v_div_scale_f32 v27, vcc, 1.0, v24, 1.0
	v_mul_f32_e32 v28, v27, v26
	v_fma_f32 v29, -v25, v28, v27
	v_fmac_f32_e32 v28, v29, v26
	v_fma_f32 v25, -v25, v28, v27
	v_div_fmas_f32 v25, v25, v26, v28
	v_cmp_gt_f32_e32 vcc, s65, v16
	v_pk_mov_b32 v[4:5], v[0:1], v[2:3] op_sel:[1,0]
	v_mov_b32_e32 v1, v3
	v_cndmask_b32_e32 v16, v16, v17, vcc
	v_sqrt_f32_e32 v17, v16
	v_pk_add_f32 v[0:1], v[4:5], v[0:1]
	v_div_fixup_f32 v128, v59, v58, 1.0
	v_add_f32_e32 v0, v0, v1
	v_add_u32_e32 v18, -1, v17
	v_fma_f32 v19, -v18, v17, v16
	v_cmp_ge_f32_e64 s[38:39], 0, v19
	v_add_u32_e32 v19, 1, v17
	ds_bpermute_b32 v1, v56, v0
	v_cndmask_b32_e64 v18, v17, v18, s[38:39]
	v_fma_f32 v17, -v19, v17, v16
	v_cmp_lt_f32_e64 s[38:39], 0, v17
	v_div_fixup_f32 v130, v49, v48, 1.0
	s_waitcnt lgkmcnt(0)
	v_add_f32_e32 v0, v0, v1
	v_cndmask_b32_e64 v17, v18, v19, s[38:39]
	v_mul_f32_e32 v18, 0x37800000, v17
	v_cndmask_b32_e32 v17, v17, v18, vcc
	v_cmp_class_f32_e32 vcc, v16, v187
	ds_bpermute_b32 v1, v57, v0
	v_div_fixup_f32 v142, v41, v40, 1.0
	v_cndmask_b32_e32 v16, v17, v16, vcc
	v_div_scale_f32 v17, s[0:1], v16, v16, 1.0
	v_rcp_f32_e32 v18, v17
	s_waitcnt lgkmcnt(0)
	v_add_f32_e32 v0, v0, v1
	v_fmamk_f32 v0, v0, 0x3a000000, v186
	v_mul_f32_e32 v1, 0x4f800000, v0
	v_fma_f32 v19, -v17, v18, 1.0
	v_fmac_f32_e32 v18, v19, v18
	v_div_scale_f32 v19, vcc, 1.0, v16, 1.0
	v_mul_f32_e32 v20, v19, v18
	v_fma_f32 v21, -v17, v20, v19
	v_fmac_f32_e32 v20, v21, v18
	v_fma_f32 v17, -v17, v20, v19
	v_div_fmas_f32 v17, v17, v18, v20
	v_cmp_gt_f32_e32 vcc, s65, v8
	v_div_fixup_f32 v160, v33, v32, 1.0
	v_div_fixup_f32 v162, v25, v24, 1.0
	v_cndmask_b32_e32 v8, v8, v9, vcc
	v_sqrt_f32_e32 v9, v8
	v_div_fixup_f32 v164, v17, v16, 1.0
	v_add_u32_e32 v10, -1, v9
	v_fma_f32 v11, -v10, v9, v8
	v_cmp_ge_f32_e64 s[38:39], 0, v11
	v_add_u32_e32 v11, 1, v9
	s_nop 0
	v_cndmask_b32_e64 v10, v9, v10, s[38:39]
	v_fma_f32 v9, -v11, v9, v8
	v_cmp_lt_f32_e64 s[38:39], 0, v9
	s_nop 1
	v_cndmask_b32_e64 v9, v10, v11, s[38:39]
	v_mul_f32_e32 v10, 0x37800000, v9
	v_cndmask_b32_e32 v9, v9, v10, vcc
	v_cmp_class_f32_e32 vcc, v8, v187
	s_nop 1
	v_cndmask_b32_e32 v8, v9, v8, vcc
	v_div_scale_f32 v9, s[0:1], v8, v8, 1.0
	v_rcp_f32_e32 v10, v9
	s_nop 0
	v_fma_f32 v11, -v9, v10, 1.0
	v_fmac_f32_e32 v10, v11, v10
	v_div_scale_f32 v11, vcc, 1.0, v8, 1.0
	v_mul_f32_e32 v12, v11, v10
	v_fma_f32 v13, -v9, v12, v11
	v_fmac_f32_e32 v12, v13, v10
	v_fma_f32 v9, -v9, v12, v11
	v_div_fmas_f32 v9, v9, v10, v12
	v_cmp_gt_f32_e32 vcc, s65, v0
	v_div_fixup_f32 v166, v9, v8, 1.0
	s_nop 0
	v_cndmask_b32_e32 v0, v0, v1, vcc
	v_sqrt_f32_e32 v1, v0
	s_nop 0
	v_add_u32_e32 v2, -1, v1
	v_fma_f32 v3, -v2, v1, v0
	v_cmp_ge_f32_e64 s[38:39], 0, v3
	v_add_u32_e32 v3, 1, v1
	s_nop 0
	v_cndmask_b32_e64 v2, v1, v2, s[38:39]
	v_fma_f32 v1, -v3, v1, v0
	v_cmp_lt_f32_e64 s[38:39], 0, v1
	s_nop 1
	v_cndmask_b32_e64 v1, v2, v3, s[38:39]
	v_mul_f32_e32 v2, 0x37800000, v1
	v_cndmask_b32_e32 v1, v1, v2, vcc
	v_cmp_class_f32_e32 vcc, v0, v187
	s_nop 1
	v_cndmask_b32_e32 v0, v1, v0, vcc
	v_div_scale_f32 v1, s[0:1], v0, v0, 1.0
	v_rcp_f32_e32 v2, v1
	s_nop 0
	v_fma_f32 v3, -v1, v2, 1.0
	v_fmac_f32_e32 v2, v3, v2
	v_div_scale_f32 v3, vcc, 1.0, v0, 1.0
	v_mul_f32_e32 v4, v3, v2
	v_fma_f32 v5, -v1, v4, v3
	v_fmac_f32_e32 v4, v5, v2
	v_fma_f32 v1, -v1, v4, v3
	v_div_fmas_f32 v1, v1, v2, v4
	v_div_fixup_f32 v168, v1, v0, 1.0

; #define PG8_STAGE(bufoff, gbase, voff) do { _Pragma("unroll") for (int _i = 0; _i < 2; ++_i) \
;         __builtin_amdgcn_global_load_lds((const unsigned*)((const char*)(gbase) + (voff)[_i]), (PG8_LAS unsigned*)(lds + (bufoff) + ldsw + _i * 8192), 16, 0, 0); } while (0)
; #define PG8_LDA(dst, b, h) do { _Pragma("unroll") for (int m = 0; m < 4; ++m) _Pragma("unroll") for (int k = 0; k < 2; ++k) dst[m][k] = *(const PG8_LAS bf16x8*)(lds + PG8_SA(b, h) + aoff + m * 2048 + k * 1024); } while (0)
; #define PG8_LDB(dst, b, h) do { _Pragma("unroll") for (int n = 0; n < 2; ++n) _Pragma("unroll") for (int k = 0; k < 2; ++k) dst[n][k] = *(const PG8_LAS bf16x8*)(lds + PG8_SB(b, h) + boff + n * 2048 + k * 1024); } while (0)
; #define PG8_MMA(ai, bj, At, Bt) do { __builtin_amdgcn_s_setprio(1); _Pragma("unroll") for (int m = 0; m < 4; ++m) _Pragma("unroll") for (int n = 0; n < 2; ++n) _Pragma("unroll") for (int k = 0; k < 2; ++k) \
;         acc[ai][bj][m][n] = __builtin_amdgcn_mfma_f32_16x16x32_bf16(Bt[n][k], At[m][k], acc[ai][bj][m][n], 0, 0, 0); __builtin_amdgcn_s_setprio(0); } while (0)
; #define PG8_WAIT_V(n) asm volatile("s_waitcnt vmcnt(" #n ")" ::: "memory")
; #define PG8_WAIT_L(n) asm volatile("s_waitcnt lgkmcnt(" #n ")" ::: "memory")
; #define PG8_BAR __builtin_amdgcn_s_barrier()
; #define PG8_SCHED __builtin_amdgcn_sched_barrier(0)
; template <class Epi, class Sched, bool ALIGN_EPI = false, bool SP2 = false>
; __device__ __forceinline__ void gemm_phase(PG8_LAS unsigned char* lds, const Gemm g, const Sched& S, const Epi& E) {
;     ...
;             PG8_LDB(B0, 0, 0); PG8_LDB(B1, 0, 1); PG8_SCHED; PG8_LDA(At, 0, 0); PG8_STAGE(PG8_SA(1, 1), a1 + hstepA, voffA);
;             PG8_WAIT_V(8); PG8_WAIT_L(0); PG8_BAR; PG8_MMA(0, 0, At, B0); PG8_MMA(0, 1, At, B1); PG8_BAR; PG8_SCHED;
;             PG8_LDA(At, 0, 1); PG8_STAGE(PG8_SB(0, 0), b2, voffB); PG8_STAGE(PG8_SB(0, 1), b2 + hstepB, voffB); PG8_STAGE(PG8_SA(0, 0), a2, voffA);
;             PG8_WAIT_V(8); PG8_WAIT_L(0); PG8_BAR; PG8_MMA(1, 0, At, B0); PG8_MMA(1, 1, At, B1); PG8_BAR; PG8_SCHED;
.LBB0_629:
	s_add_u32 s6, s0, 0x10000
	s_addc_u32 s7, s1, 0
	s_cmpk_eq_i32 s61, 0x7c
	s_cselect_b32 s24, s43, s6
	s_cselect_b32 s25, s27, s7
	s_cselect_b32 s22, s56, s59
	s_cselect_b32 s23, s31, s60
	s_add_u32 s8, s24, 0x8000
	s_addc_u32 s9, s25, 0
	s_add_i32 s73, 0, 0x10000
	v_add_u32_e32 v144, s73, v166
	s_add_i32 s76, 0, 0x14000
	ds_read_b128 v[140:143], v144
	ds_read_b128 v[160:163], v144 offset:1024
	ds_read_b128 v[170:173], v144 offset:2048
	ds_read_b128 v[178:181], v144 offset:3072
	v_add_u32_e32 v144, s76, v166
	ds_read_b128 v[198:201], v144
	ds_read_b128 v[202:205], v144 offset:1024
	ds_read_b128 v[206:209], v144 offset:2048
	ds_read_b128 v[210:213], v144 offset:3072
	v_lshl_add_u64 v[174:175], s[0:1], 0, v[128:129]
	s_add_i32 m0, s54, 0xc000
	ds_read_b128 v[214:217], v168
	ds_read_b128 v[218:221], v168 offset:1024
	ds_read_b128 v[222:225], v168 offset:2048
	ds_read_b128 v[226:229], v168 offset:3072
	ds_read_b128 v[230:233], v168 offset:4096
	ds_read_b128 v[234:237], v168 offset:5120
	ds_read_b128 v[238:241], v168 offset:6144
	ds_read_b128 v[242:245], v168 offset:7168
	global_load_lds_dwordx4 v[174:175], off
	v_lshl_add_u64 v[174:175], s[0:1], 0, v[130:131]
	s_add_i32 m0, s54, 0xe000
	s_nop 0
	global_load_lds_dwordx4 v[174:175], off
	s_waitcnt vmcnt(8)
	s_waitcnt lgkmcnt(0)
	s_barrier
	s_setprio 1
	s_waitcnt lgkmcnt(0)
	v_mfma_f32_16x16x32_bf16 v[112:115], v[140:143], v[214:217], v[112:115]
	v_mfma_f32_16x16x32_bf16 v[120:123], v[170:173], v[214:217], v[120:123]
	v_mfma_f32_16x16x32_bf16 v[80:83], v[140:143], v[222:225], v[80:83]
	v_mfma_f32_16x16x32_bf16 v[56:59], v[170:173], v[222:225], v[56:59]
	v_mfma_f32_16x16x32_bf16 v[60:63], v[140:143], v[230:233], v[60:63]
	v_mfma_f32_16x16x32_bf16 v[100:103], v[170:173], v[230:233], v[100:103]
	v_mfma_f32_16x16x32_bf16 v[68:71], v[140:143], v[238:241], v[68:71]
	v_mfma_f32_16x16x32_bf16 v[48:51], v[170:173], v[238:241], v[48:51]
	v_mfma_f32_16x16x32_bf16 v[112:115], v[160:163], v[218:221], v[112:115]
	v_mfma_f32_16x16x32_bf16 v[120:123], v[178:181], v[218:221], v[120:123]
	v_mfma_f32_16x16x32_bf16 v[80:83], v[160:163], v[226:229], v[80:83]
	v_mfma_f32_16x16x32_bf16 v[56:59], v[178:181], v[226:229], v[56:59]
	v_mfma_f32_16x16x32_bf16 v[60:63], v[160:163], v[234:237], v[60:63]
	v_mfma_f32_16x16x32_bf16 v[100:103], v[178:181], v[234:237], v[100:103]
	v_mfma_f32_16x16x32_bf16 v[68:71], v[160:163], v[242:245], v[68:71]
	v_mfma_f32_16x16x32_bf16 v[48:51], v[178:181], v[242:245], v[48:51]
	s_setprio 0
	s_setprio 1
	v_mfma_f32_16x16x32_bf16 v[116:119], v[198:201], v[214:217], v[116:119]
	v_mfma_f32_16x16x32_bf16 v[124:127], v[206:209], v[214:217], v[124:127]
	v_mfma_f32_16x16x32_bf16 v[72:75], v[198:201], v[222:225], v[72:75]
	v_mfma_f32_16x16x32_bf16 v[92:95], v[206:209], v[222:225], v[92:95]
	v_mfma_f32_16x16x32_bf16 v[104:107], v[198:201], v[230:233], v[104:107]
	v_mfma_f32_16x16x32_bf16 v[108:111], v[206:209], v[230:233], v[108:111]
	v_mfma_f32_16x16x32_bf16 v[64:67], v[198:201], v[238:241], v[64:67]
	v_mfma_f32_16x16x32_bf16 v[76:79], v[206:209], v[238:241], v[76:79]
	v_mfma_f32_16x16x32_bf16 v[116:119], v[202:205], v[218:221], v[116:119]
	v_mfma_f32_16x16x32_bf16 v[124:127], v[210:213], v[218:221], v[124:127]
	v_mfma_f32_16x16x32_bf16 v[72:75], v[202:205], v[226:229], v[72:75]
	v_mfma_f32_16x16x32_bf16 v[92:95], v[210:213], v[226:229], v[92:95]
	v_mfma_f32_16x16x32_bf16 v[104:107], v[202:205], v[234:237], v[104:107]
	v_mfma_f32_16x16x32_bf16 v[108:111], v[210:213], v[234:237], v[108:111]
	v_mfma_f32_16x16x32_bf16 v[64:67], v[202:205], v[242:245], v[64:67]
	v_mfma_f32_16x16x32_bf16 v[76:79], v[210:213], v[242:245], v[76:79]
	s_setprio 0
	s_barrier
	s_add_i32 s0, s73, s50
	v_lshl_add_u64 v[174:175], s[22:23], 0, v[136:137]
	s_mov_b32 m0, s0
	ds_read_b128 v[214:217], v168 offset:16384
	ds_read_b128 v[218:221], v168 offset:17408
	ds_read_b128 v[222:225], v168 offset:18432
	ds_read_b128 v[226:229], v168 offset:19456
	ds_read_b128 v[230:233], v168 offset:20480
	ds_read_b128 v[234:237], v168 offset:21504
	ds_read_b128 v[238:241], v168 offset:22528
	ds_read_b128 v[242:245], v168 offset:23552
	global_load_lds_dwordx4 v[174:175], off
	s_add_i32 m0, s0, 0x2000
	s_add_u32 s0, s22, 0x4000
	v_lshl_add_u64 v[174:175], s[22:23], 0, v[132:133]
	s_addc_u32 s1, s23, 0
	s_add_i32 s73, s76, s50
	global_load_lds_dwordx4 v[174:175], off
	v_lshl_add_u64 v[174:175], s[0:1], 0, v[136:137]
	s_mov_b32 m0, s73
	s_nop 0
	global_load_lds_dwordx4 v[174:175], off
	v_lshl_add_u64 v[174:175], s[0:1], 0, v[132:133]
	s_add_i32 m0, s73, 0x2000
	s_nop 0
	global_load_lds_dwordx4 v[174:175], off
	v_lshl_add_u64 v[174:175], s[24:25], 0, v[138:139]
	s_mov_b32 m0, s54
	s_nop 0
	global_load_lds_dwordx4 v[174:175], off
	v_lshl_add_u64 v[174:175], s[24:25], 0, v[134:135]
	s_mov_b32 m0, s55
	s_nop 0
	global_load_lds_dwordx4 v[174:175], off
	s_waitcnt vmcnt(8)
	s_waitcnt lgkmcnt(0)
	s_barrier
; #define PG8_STAGE(bufoff, gbase, voff) do { _Pragma("unroll") for (int _i = 0; _i < 2; ++_i) \
;         __builtin_amdgcn_global_load_lds((const unsigned*)((const char*)(gbase) + (voff)[_i]), (PG8_LAS unsigned*)(lds + (bufoff) + ldsw + _i * 8192), 16, 0, 0); } while (0)
; #define PG8_LDA(dst, b, h) do { _Pragma("unroll") for (int m = 0; m < 4; ++m) _Pragma("unroll") for (int k = 0; k < 2; ++k) dst[m][k] = *(const PG8_LAS bf16x8*)(lds + PG8_SA(b, h) + aoff + m * 2048 + k * 1024); } while (0)
; #define PG8_LDB(dst, b, h) do { _Pragma("unroll") for (int n = 0; n < 2; ++n) _Pragma("unroll") for (int k = 0; k < 2; ++k) dst[n][k] = *(const PG8_LAS bf16x8*)(lds + PG8_SB(b, h) + boff + n * 2048 + k * 1024); } while (0)
; #define PG8_MMA(ai, bj, At, Bt) do { __builtin_amdgcn_s_setprio(1); _Pragma("unroll") for (int m = 0; m < 4; ++m) _Pragma("unroll") for (int n = 0; n < 2; ++n) _Pragma("unroll") for (int k = 0; k < 2; ++k) \
;         acc[ai][bj][m][n] = __builtin_amdgcn_mfma_f32_16x16x32_bf16(Bt[n][k], At[m][k], acc[ai][bj][m][n], 0, 0, 0); __builtin_amdgcn_s_setprio(0); } while (0)
; #define PG8_WAIT_V(n) asm volatile("s_waitcnt vmcnt(" #n ")" ::: "memory")
; #define PG8_WAIT_L(n) asm volatile("s_waitcnt lgkmcnt(" #n ")" ::: "memory")
; #define PG8_BAR __builtin_amdgcn_s_barrier()
; #define PG8_SCHED __builtin_amdgcn_sched_barrier(0)
; template <class Epi, class Sched, bool ALIGN_EPI = false, bool SP2 = false>
; __device__ __forceinline__ void gemm_phase(PG8_LAS unsigned char* lds, const Gemm g, const Sched& S, const Epi& E) {
;     ...
;             PG8_WAIT_V(8); PG8_WAIT_L(0); PG8_BAR; PG8_MMA(1, 0, At, B0); PG8_MMA(1, 1, At, B1); PG8_BAR; PG8_SCHED;
;             PG8_LDB(B0, 1, 0); PG8_LDB(B1, 1, 1); PG8_SCHED; PG8_LDA(At, 1, 0); PG8_STAGE(PG8_SA(0, 1), a2 + hstepA, voffA);
;             PG8_WAIT_V(8); PG8_WAIT_L(0); PG8_BAR; PG8_MMA(0, 0, At, B0); PG8_MMA(0, 1, At, B1); PG8_BAR; PG8_SCHED;
;             PG8_LDA(At, 1, 1); PG8_STAGE(PG8_SB(1, 0), b3, voffB); PG8_STAGE(PG8_SB(1, 1), b3 + hstepB, voffB); PG8_STAGE(PG8_SA(1, 0), a3, voffA);
	s_setprio 1
	s_waitcnt lgkmcnt(0)
	v_mfma_f32_16x16x32_bf16 v[40:43], v[140:143], v[214:217], v[40:43]
	v_mfma_f32_16x16x32_bf16 v[44:47], v[170:173], v[214:217], v[44:47]
	v_mfma_f32_16x16x32_bf16 v[16:19], v[140:143], v[222:225], v[16:19]
	v_mfma_f32_16x16x32_bf16 v[88:91], v[170:173], v[222:225], v[88:91]
	v_mfma_f32_16x16x32_bf16 v[24:27], v[140:143], v[230:233], v[24:27]
	v_mfma_f32_16x16x32_bf16 v[28:31], v[170:173], v[230:233], v[28:31]
	v_mfma_f32_16x16x32_bf16 v[4:7], v[140:143], v[238:241], v[4:7]
	v_mfma_f32_16x16x32_bf16 v[8:11], v[170:173], v[238:241], v[8:11]
	v_mfma_f32_16x16x32_bf16 v[40:43], v[160:163], v[218:221], v[40:43]
	v_mfma_f32_16x16x32_bf16 v[44:47], v[178:181], v[218:221], v[44:47]
	v_mfma_f32_16x16x32_bf16 v[16:19], v[160:163], v[226:229], v[16:19]
	v_mfma_f32_16x16x32_bf16 v[88:91], v[178:181], v[226:229], v[88:91]
	v_mfma_f32_16x16x32_bf16 v[24:27], v[160:163], v[234:237], v[24:27]
	v_mfma_f32_16x16x32_bf16 v[28:31], v[178:181], v[234:237], v[28:31]
	v_mfma_f32_16x16x32_bf16 v[4:7], v[160:163], v[242:245], v[4:7]
	v_mfma_f32_16x16x32_bf16 v[8:11], v[178:181], v[242:245], v[8:11]
	s_setprio 0
	s_setprio 1
	v_mfma_f32_16x16x32_bf16 v[36:39], v[198:201], v[214:217], v[36:39]
	v_mfma_f32_16x16x32_bf16 v[52:55], v[206:209], v[214:217], v[52:55]
	v_mfma_f32_16x16x32_bf16 v[84:87], v[198:201], v[222:225], v[84:87]
	v_mfma_f32_16x16x32_bf16 v[96:99], v[206:209], v[222:225], v[96:99]
	v_mfma_f32_16x16x32_bf16 v[20:23], v[198:201], v[230:233], v[20:23]
	v_mfma_f32_16x16x32_bf16 v[32:35], v[206:209], v[230:233], v[32:35]
	v_mfma_f32_16x16x32_bf16 v[0:3], v[198:201], v[238:241], v[0:3]
	v_mfma_f32_16x16x32_bf16 v[12:15], v[206:209], v[238:241], v[12:15]
	v_mfma_f32_16x16x32_bf16 v[36:39], v[202:205], v[218:221], v[36:39]
	v_mfma_f32_16x16x32_bf16 v[52:55], v[210:213], v[218:221], v[52:55]
	v_mfma_f32_16x16x32_bf16 v[84:87], v[202:205], v[226:229], v[84:87]
	v_mfma_f32_16x16x32_bf16 v[96:99], v[210:213], v[226:229], v[96:99]
	v_mfma_f32_16x16x32_bf16 v[20:23], v[202:205], v[234:237], v[20:23]
	v_mfma_f32_16x16x32_bf16 v[32:35], v[210:213], v[234:237], v[32:35]
	v_mfma_f32_16x16x32_bf16 v[0:3], v[202:205], v[242:245], v[0:3]
	v_mfma_f32_16x16x32_bf16 v[12:15], v[210:213], v[242:245], v[12:15]
	s_setprio 0
	s_barrier
	s_add_i32 s73, 0, 0x18000
	v_add_u32_e32 v144, s73, v166
	s_add_i32 s76, 0, 0x1c000
	ds_read_b128 v[140:143], v144
	ds_read_b128 v[160:163], v144 offset:1024
	ds_read_b128 v[170:173], v144 offset:2048
	ds_read_b128 v[178:181], v144 offset:3072
	v_add_u32_e32 v144, s76, v166
	ds_read_b128 v[198:201], v144
	ds_read_b128 v[202:205], v144 offset:1024
	ds_read_b128 v[206:209], v144 offset:2048
	ds_read_b128 v[210:213], v144 offset:3072
	s_add_u32 s0, s24, 0x4000
	s_addc_u32 s1, s25, 0
	s_mov_b32 m0, s66
	v_lshl_add_u64 v[174:175], s[0:1], 0, v[138:139]
	ds_read_b128 v[214:217], v168 offset:32768
	ds_read_b128 v[218:221], v168 offset:33792
	ds_read_b128 v[222:225], v168 offset:34816
	ds_read_b128 v[226:229], v168 offset:35840
	ds_read_b128 v[230:233], v168 offset:36864
	ds_read_b128 v[234:237], v168 offset:37888
	ds_read_b128 v[238:241], v168 offset:38912
	ds_read_b128 v[242:245], v168 offset:39936
	global_load_lds_dwordx4 v[174:175], off
	v_lshl_add_u64 v[174:175], s[0:1], 0, v[134:135]
	s_mov_b32 m0, s67
	s_nop 0
	global_load_lds_dwordx4 v[174:175], off
	s_waitcnt vmcnt(8)
	s_waitcnt lgkmcnt(0)
	s_barrier
	s_setprio 1
	s_waitcnt lgkmcnt(0)
	v_mfma_f32_16x16x32_bf16 v[112:115], v[140:143], v[214:217], v[112:115]
	v_mfma_f32_16x16x32_bf16 v[120:123], v[170:173], v[214:217], v[120:123]
	v_mfma_f32_16x16x32_bf16 v[80:83], v[140:143], v[222:225], v[80:83]
	v_mfma_f32_16x16x32_bf16 v[56:59], v[170:173], v[222:225], v[56:59]
	v_mfma_f32_16x16x32_bf16 v[60:63], v[140:143], v[230:233], v[60:63]
	v_mfma_f32_16x16x32_bf16 v[100:103], v[170:173], v[230:233], v[100:103]
	v_mfma_f32_16x16x32_bf16 v[68:71], v[140:143], v[238:241], v[68:71]
	v_mfma_f32_16x16x32_bf16 v[48:51], v[170:173], v[238:241], v[48:51]
	v_mfma_f32_16x16x32_bf16 v[112:115], v[160:163], v[218:221], v[112:115]
	v_mfma_f32_16x16x32_bf16 v[120:123], v[178:181], v[218:221], v[120:123]
	v_mfma_f32_16x16x32_bf16 v[80:83], v[160:163], v[226:229], v[80:83]
	v_mfma_f32_16x16x32_bf16 v[56:59], v[178:181], v[226:229], v[56:59]
	v_mfma_f32_16x16x32_bf16 v[60:63], v[160:163], v[234:237], v[60:63]
	v_mfma_f32_16x16x32_bf16 v[100:103], v[178:181], v[234:237], v[100:103]
	v_mfma_f32_16x16x32_bf16 v[68:71], v[160:163], v[242:245], v[68:71]
	v_mfma_f32_16x16x32_bf16 v[48:51], v[178:181], v[242:245], v[48:51]
	s_setprio 0
	s_setprio 1
	v_mfma_f32_16x16x32_bf16 v[116:119], v[198:201], v[214:217], v[116:119]
	v_mfma_f32_16x16x32_bf16 v[124:127], v[206:209], v[214:217], v[124:127]
	v_mfma_f32_16x16x32_bf16 v[72:75], v[198:201], v[222:225], v[72:75]
	v_mfma_f32_16x16x32_bf16 v[92:95], v[206:209], v[222:225], v[92:95]
	v_mfma_f32_16x16x32_bf16 v[104:107], v[198:201], v[230:233], v[104:107]
	v_mfma_f32_16x16x32_bf16 v[108:111], v[206:209], v[230:233], v[108:111]
	v_mfma_f32_16x16x32_bf16 v[64:67], v[198:201], v[238:241], v[64:67]
	v_mfma_f32_16x16x32_bf16 v[76:79], v[206:209], v[238:241], v[76:79]
	v_mfma_f32_16x16x32_bf16 v[116:119], v[202:205], v[218:221], v[116:119]
	v_mfma_f32_16x16x32_bf16 v[124:127], v[210:213], v[218:221], v[124:127]
	v_mfma_f32_16x16x32_bf16 v[72:75], v[202:205], v[226:229], v[72:75]
	v_mfma_f32_16x16x32_bf16 v[92:95], v[210:213], v[226:229], v[92:95]
	v_mfma_f32_16x16x32_bf16 v[104:107], v[202:205], v[234:237], v[104:107]
	v_mfma_f32_16x16x32_bf16 v[108:111], v[210:213], v[234:237], v[108:111]
	v_mfma_f32_16x16x32_bf16 v[64:67], v[202:205], v[242:245], v[64:67]
	v_mfma_f32_16x16x32_bf16 v[76:79], v[210:213], v[242:245], v[76:79]
	s_setprio 0
	s_barrier
; #define PG8_STAGE(bufoff, gbase, voff) do { _Pragma("unroll") for (int _i = 0; _i < 2; ++_i) \
;         __builtin_amdgcn_global_load_lds((const unsigned*)((const char*)(gbase) + (voff)[_i]), (PG8_LAS unsigned*)(lds + (bufoff) + ldsw + _i * 8192), 16, 0, 0); } while (0)
; #define PG8_LDA(dst, b, h) do { _Pragma("unroll") for (int m = 0; m < 4; ++m) _Pragma("unroll") for (int k = 0; k < 2; ++k) dst[m][k] = *(const PG8_LAS bf16x8*)(lds + PG8_SA(b, h) + aoff + m * 2048 + k * 1024); } while (0)
; #define PG8_MMA(ai, bj, At, Bt) do { __builtin_amdgcn_s_setprio(1); _Pragma("unroll") for (int m = 0; m < 4; ++m) _Pragma("unroll") for (int n = 0; n < 2; ++n) _Pragma("unroll") for (int k = 0; k < 2; ++k) \
;         acc[ai][bj][m][n] = __builtin_amdgcn_mfma_f32_16x16x32_bf16(Bt[n][k], At[m][k], acc[ai][bj][m][n], 0, 0, 0); __builtin_amdgcn_s_setprio(0); } while (0)
; #define PG8_WAIT_V(n) asm volatile("s_waitcnt vmcnt(" #n ")" ::: "memory")
; #define PG8_WAIT_L(n) asm volatile("s_waitcnt lgkmcnt(" #n ")" ::: "memory")
; #define PG8_BAR __builtin_amdgcn_s_barrier()
; #define PG8_SCHED __builtin_amdgcn_sched_barrier(0)
;     __device__ __forceinline__ void operator()(const f32x4 (&acc)[2][2][4][2], const State&, const Unit& u, int wr, int wc, int fr, int fq) const {
;     ...
;         if (xout_f) {
; #pragma unroll
;             for (int ai = 0; ai < 2; ++ai)
; #pragma unroll
;                 for (int m = 0; m < 4; ++m) { const size_t off = (size_t)(row0 + ai * HALF + m * 16) * ldc + col0;
; #pragma unroll
;                     for (int bj = 0; bj < 2; ++bj)
; #pragma unroll
;                         for (int n = 0; n < 2; ++n) *(f32x4*)(xout_f + off + bj * HALF + n * 4) = acc[ai][bj][m][n]; }
; template <class Epi, class Sched, bool ALIGN_EPI = false, bool SP2 = false>
; __device__ __forceinline__ void gemm_phase(PG8_LAS unsigned char* lds, const Gemm g, const Sched& S, const Epi& E) {
;     ...
;             PG8_LDA(At, 1, 1); PG8_STAGE(PG8_SB(1, 0), b3, voffB); PG8_STAGE(PG8_SB(1, 1), b3 + hstepB, voffB); PG8_STAGE(PG8_SA(1, 0), a3, voffA);
;             PG8_WAIT_V(8); PG8_WAIT_L(0); PG8_BAR; PG8_MMA(1, 0, At, B0); PG8_MMA(1, 1, At, B1); PG8_BAR; PG8_SCHED;
	s_add_u32 s0, s22, 0x8000
	s_addc_u32 s1, s23, 0
	s_add_i32 s24, s73, s50
	v_lshl_add_u64 v[174:175], s[0:1], 0, v[136:137]
	s_mov_b32 m0, s24
	ds_read_b128 v[214:217], v168 offset:49152
	ds_read_b128 v[218:221], v168 offset:50176
	ds_read_b128 v[222:225], v168 offset:51200
	ds_read_b128 v[226:229], v168 offset:52224
	ds_read_b128 v[230:233], v168 offset:53248
	ds_read_b128 v[234:237], v168 offset:54272
	ds_read_b128 v[238:241], v168 offset:55296
	ds_read_b128 v[242:245], v168 offset:56320
	global_load_lds_dwordx4 v[174:175], off
	s_add_i32 m0, s24, 0x2000
	v_lshl_add_u64 v[174:175], s[0:1], 0, v[132:133]
	s_add_u32 s0, s22, 0xc000
	s_addc_u32 s1, s23, 0
	s_add_i32 s22, s76, s50
	global_load_lds_dwordx4 v[174:175], off
	v_lshl_add_u64 v[174:175], s[0:1], 0, v[136:137]
	s_mov_b32 m0, s22
	s_nop 0
	global_load_lds_dwordx4 v[174:175], off
	v_lshl_add_u64 v[174:175], s[0:1], 0, v[132:133]
	s_add_i32 m0, s22, 0x2000
	s_nop 0
	global_load_lds_dwordx4 v[174:175], off
	v_lshl_add_u64 v[174:175], s[8:9], 0, v[138:139]
	s_mov_b32 m0, s68
	s_nop 0
	global_load_lds_dwordx4 v[174:175], off
	v_lshl_add_u64 v[174:175], s[8:9], 0, v[134:135]
	s_mov_b32 m0, s69
	s_nop 0
	global_load_lds_dwordx4 v[174:175], off
	s_waitcnt vmcnt(8)
	s_waitcnt lgkmcnt(0)
	s_barrier
	s_setprio 1
	s_waitcnt lgkmcnt(0)
	v_mfma_f32_16x16x32_bf16 v[40:43], v[140:143], v[214:217], v[40:43]
	v_mfma_f32_16x16x32_bf16 v[44:47], v[170:173], v[214:217], v[44:47]
	v_mfma_f32_16x16x32_bf16 v[16:19], v[140:143], v[222:225], v[16:19]
	v_mfma_f32_16x16x32_bf16 v[88:91], v[170:173], v[222:225], v[88:91]
	v_mfma_f32_16x16x32_bf16 v[24:27], v[140:143], v[230:233], v[24:27]
	v_mfma_f32_16x16x32_bf16 v[28:31], v[170:173], v[230:233], v[28:31]
	v_mfma_f32_16x16x32_bf16 v[4:7], v[140:143], v[238:241], v[4:7]
	v_mfma_f32_16x16x32_bf16 v[8:11], v[170:173], v[238:241], v[8:11]
	v_mfma_f32_16x16x32_bf16 v[40:43], v[160:163], v[218:221], v[40:43]
	v_mfma_f32_16x16x32_bf16 v[44:47], v[178:181], v[218:221], v[44:47]
	v_mfma_f32_16x16x32_bf16 v[16:19], v[160:163], v[226:229], v[16:19]
	v_mfma_f32_16x16x32_bf16 v[88:91], v[178:181], v[226:229], v[88:91]
	v_mfma_f32_16x16x32_bf16 v[24:27], v[160:163], v[234:237], v[24:27]
	v_mfma_f32_16x16x32_bf16 v[28:31], v[178:181], v[234:237], v[28:31]
	v_mfma_f32_16x16x32_bf16 v[4:7], v[160:163], v[242:245], v[4:7]
	v_mfma_f32_16x16x32_bf16 v[8:11], v[178:181], v[242:245], v[8:11]
	s_setprio 0
	s_setprio 1
	v_mfma_f32_16x16x32_bf16 v[36:39], v[198:201], v[214:217], v[36:39]
	v_mfma_f32_16x16x32_bf16 v[52:55], v[206:209], v[214:217], v[52:55]
	v_mfma_f32_16x16x32_bf16 v[84:87], v[198:201], v[222:225], v[84:87]
	v_mfma_f32_16x16x32_bf16 v[96:99], v[206:209], v[222:225], v[96:99]
	v_mfma_f32_16x16x32_bf16 v[20:23], v[198:201], v[230:233], v[20:23]
	v_mfma_f32_16x16x32_bf16 v[32:35], v[206:209], v[230:233], v[32:35]
	v_mfma_f32_16x16x32_bf16 v[0:3], v[198:201], v[238:241], v[0:3]
	v_mfma_f32_16x16x32_bf16 v[12:15], v[206:209], v[238:241], v[12:15]
	v_mfma_f32_16x16x32_bf16 v[36:39], v[202:205], v[218:221], v[36:39]
	v_mfma_f32_16x16x32_bf16 v[52:55], v[210:213], v[218:221], v[52:55]
	v_mfma_f32_16x16x32_bf16 v[84:87], v[202:205], v[226:229], v[84:87]
	v_mfma_f32_16x16x32_bf16 v[96:99], v[210:213], v[226:229], v[96:99]
	v_mfma_f32_16x16x32_bf16 v[20:23], v[202:205], v[234:237], v[20:23]
	v_mfma_f32_16x16x32_bf16 v[32:35], v[210:213], v[234:237], v[32:35]
	v_mfma_f32_16x16x32_bf16 v[0:3], v[202:205], v[242:245], v[0:3]
	v_mfma_f32_16x16x32_bf16 v[12:15], v[210:213], v[242:245], v[12:15]
	s_setprio 0
	s_barrier
	s_add_i32 s61, s61, 2
	s_add_u32 s59, s59, 0x10000
	s_addc_u32 s60, s60, 0
	s_cmpk_gt_u32 s61, 0x7d
	s_mov_b64 s[0:1], s[6:7]
	s_cbranch_scc0 .LBB0_629
	s_lshl_b32 s7, s26, 8
	s_add_i32 s7, s7, s51
	v_or_b32_e32 v140, s7, v164
	s_lshl_b32 s0, s14, 8
	s_or_b32 s6, s0, s52
	s_andn2_b64 vcc, exec, s[20:21]
	v_or_b32_e32 v162, 16, v140
	v_or_b32_e32 v160, 32, v140
	v_or_b32_e32 v142, 48, v140
	s_cbranch_vccnz .LBB0_633
	v_or_b32_e32 v170, s6, v165
	v_ashrrev_i32_e32 v141, 31, v140
	v_ashrrev_i32_e32 v163, 31, v162
	v_ashrrev_i32_e32 v171, 31, v170
	v_lshlrev_b64 v[172:173], 13, v[140:141]
	v_lshlrev_b64 v[174:175], 13, v[162:163]
	v_lshl_add_u64 v[172:173], s[16:17], 0, v[172:173]
	v_lshlrev_b64 v[170:171], 2, v[170:171]
	v_lshl_add_u64 v[174:175], s[16:17], 0, v[174:175]
	v_lshl_add_u64 v[172:173], v[172:173], 0, v[170:171]
	v_lshl_add_u64 v[174:175], v[174:175], 0, v[170:171]
	v_ashrrev_i32_e32 v161, 31, v160
	global_store_dwordx4 v[172:173], v[112:115], off sc0 sc1
	global_store_dwordx4 v[172:173], v[120:123], off offset:16 sc0 sc1
	global_store_dwordx4 v[172:173], v[116:119], off offset:512 sc0 sc1
	global_store_dwordx4 v[172:173], v[124:127], off offset:528 sc0 sc1
	global_store_dwordx4 v[174:175], v[80:83], off sc0 sc1
	global_store_dwordx4 v[174:175], v[56:59], off offset:16 sc0 sc1
	global_store_dwordx4 v[174:175], v[72:75], off offset:512 sc0 sc1
	global_store_dwordx4 v[174:175], v[92:95], off offset:528 sc0 sc1
	v_lshlrev_b64 v[174:175], 13, v[160:161]
	v_lshl_add_u64 v[174:175], s[16:17], 0, v[174:175]
	v_lshl_add_u64 v[174:175], v[174:175], 0, v[170:171]
	v_ashrrev_i32_e32 v143, 31, v142
	global_store_dwordx4 v[174:175], v[60:63], off sc0 sc1
	global_store_dwordx4 v[174:175], v[100:103], off offset:16 sc0 sc1
	global_store_dwordx4 v[174:175], v[104:107], off offset:512 sc0 sc1
	global_store_dwordx4 v[174:175], v[108:111], off offset:528 sc0 sc1
	v_lshlrev_b64 v[174:175], 13, v[142:143]
	v_lshl_add_u64 v[174:175], s[16:17], 0, v[174:175]
	v_lshl_add_u64 v[170:171], v[174:175], 0, v[170:171]
	s_mov_b64 s[0:1], 0x100000
	global_store_dwordx4 v[170:171], v[68:71], off sc0 sc1
; __device__ __forceinline__ unsigned cvt_pk_bf16(float lo, float hi) { unsigned r; asm volatile("v_cvt_pk_bf16_f32 %0, %1, %2" : "=v"(r) : "v"(lo), "v"(hi)); return r; }
;     __device__ __forceinline__ size_t xb_off(int row, int col) const { return ((size_t)(row >> 8) * (ldc >> 6) + (col >> 6)) * (256 * 64) + blk_off(row & 255, col & 63); }
;     __device__ __forceinline__ void operator()(const f32x4 (&acc)[2][2][4][2], const State&, const Unit& u, int wr, int wc, int fr, int fq) const {
;     ...
;         if (xout_f) {
; #pragma unroll
;             for (int ai = 0; ai < 2; ++ai)
; #pragma unroll
;                 for (int m = 0; m < 4; ++m) { const size_t off = (size_t)(row0 + ai * HALF + m * 16) * ldc + col0;
; #pragma unroll
;                     for (int bj = 0; bj < 2; ++bj)
; #pragma unroll
;                         for (int n = 0; n < 2; ++n) *(f32x4*)(xout_f + off + bj * HALF + n * 4) = acc[ai][bj][m][n]; }
;         } else {
; #pragma unroll
;             for (int ai = 0; ai < 2; ++ai)
; #pragma unroll
;                 for (int m = 0; m < 4; ++m) { const int row = row0 + ai * HALF + m * 16; const size_t off = (size_t)row * ldc + col0; float ss = 0.f;
; #pragma unroll
;                     for (int bj = 0; bj < 2; ++bj) { const f32x4 v0 = acc[ai][bj][m][0], v1 = acc[ai][bj][m][1];
;                         u32x4 w; w.x = cvt_pk_bf16(v0[0], v0[1]); w.y = cvt_pk_bf16(v0[2], v0[3]); w.z = cvt_pk_bf16(v1[0], v1[1]); w.w = cvt_pk_bf16(v1[2], v1[3]);
;                         *(u32x4*)(xb + xb_off(row, col0 + bj * HALF)) = w;
;                         ss += ((v0[0] * v0[0] + v0[1] * v0[1]) + (v0[2] * v0[2] + v0[3] * v0[3])) + ((v1[0] * v1[0] + v1[1] * v1[1]) + (v1[2] * v1[2] + v1[3] * v1[3])); }
;                     ss += __shfl_xor(ss, 16); ss += __shfl_xor(ss, 32);
;                     if (fq == 0) ssq[(size_t)row * 32 + u.pn * 4 + wc] = ss; }
	global_store_dwordx4 v[170:171], v[48:51], off offset:16 sc0 sc1
	global_store_dwordx4 v[170:171], v[64:67], off offset:512 sc0 sc1
	global_store_dwordx4 v[170:171], v[76:79], off offset:528 sc0 sc1
	v_lshl_add_u64 v[170:171], v[172:173], 0, s[0:1]
	s_mov_b32 s0, 0x100000
	v_add_co_u32_e32 v174, vcc, s0, v172
	s_mov_b64 s[0:1], 0x120000
	s_nop 0
	v_addc_co_u32_e32 v175, vcc, 0, v173, vcc
	global_store_dwordx4 v[174:175], v[40:43], off sc0 sc1
	global_store_dwordx4 v[170:171], v[44:47], off offset:16 sc0 sc1
	global_store_dwordx4 v[170:171], v[36:39], off offset:512 sc0 sc1
	global_store_dwordx4 v[170:171], v[52:55], off offset:528 sc0 sc1
	v_lshl_add_u64 v[170:171], v[172:173], 0, s[0:1]
	s_mov_b32 s0, 0x120000
	v_add_co_u32_e32 v174, vcc, s0, v172
	s_mov_b64 s[0:1], 0x140000
	s_nop 0
	v_addc_co_u32_e32 v175, vcc, 0, v173, vcc
	global_store_dwordx4 v[174:175], v[16:19], off sc0 sc1
	global_store_dwordx4 v[170:171], v[88:91], off offset:16 sc0 sc1
	global_store_dwordx4 v[170:171], v[84:87], off offset:512 sc0 sc1
	global_store_dwordx4 v[170:171], v[96:99], off offset:528 sc0 sc1
	v_add_co_u32_e32 v174, vcc, 0x140000, v172
	v_lshl_add_u64 v[170:171], v[172:173], 0, s[0:1]
	s_nop 0
	v_addc_co_u32_e32 v175, vcc, 0, v173, vcc
	s_mov_b64 s[0:1], 0x160000
	global_store_dwordx4 v[174:175], v[24:27], off sc0 sc1
	global_store_dwordx4 v[170:171], v[28:31], off offset:16 sc0 sc1
	global_store_dwordx4 v[170:171], v[20:23], off offset:512 sc0 sc1
	global_store_dwordx4 v[170:171], v[32:35], off offset:528 sc0 sc1
	v_lshl_add_u64 v[170:171], v[172:173], 0, s[0:1]
	v_add_co_u32_e32 v172, vcc, 0x160000, v172
	s_nop 1
	v_addc_co_u32_e32 v173, vcc, 0, v173, vcc
	global_store_dwordx4 v[172:173], v[4:7], off sc0 sc1
	global_store_dwordx4 v[170:171], v[8:11], off offset:16 sc0 sc1
	global_store_dwordx4 v[170:171], v[0:3], off offset:512 sc0 sc1
	global_store_dwordx4 v[170:171], v[12:15], off offset:528 sc0 sc1
	s_cbranch_execz .LBB0_634
	s_mov_b64 s[0:1], -1
	s_and_b64 vcc, s[40:41], exec
	s_cbranch_vccz .LBB0_621
	s_branch .LBB0_651
.LBB0_633:
.LBB0_634:
	v_cvt_pk_bf16_f32 v170, v112, v113
	v_mul_f32_e32 v113, v113, v113
	v_fmac_f32_e32 v113, v112, v112
	v_mul_f32_e32 v112, v115, v115
	v_fmac_f32_e32 v112, v114, v114
	v_cvt_pk_bf16_f32 v171, v114, v115
	v_add_f32_e32 v112, v113, v112
	v_mul_f32_e32 v113, v121, v121
	v_mul_f32_e32 v114, v123, v123
	v_fmac_f32_e32 v113, v120, v120
	v_fmac_f32_e32 v114, v122, v122
	v_add_f32_e32 v113, v113, v114
	v_add_f32_e32 v112, v112, v113
	v_mul_f32_e32 v113, v117, v117
	v_mul_f32_e32 v114, v119, v119
	v_fmac_f32_e32 v113, v116, v116
	v_fmac_f32_e32 v114, v118, v118
	v_add_f32_e32 v113, v113, v114
	v_mul_f32_e32 v114, v125, v125
	v_mul_f32_e32 v115, v127, v127
	v_fmac_f32_e32 v114, v124, v124
	v_fmac_f32_e32 v115, v126, v126
	v_add_f32_e32 v114, v114, v115
	v_add_f32_e32 v113, v113, v114
	v_cmp_lt_i32_e32 vcc, v191, v192
	s_ashr_i32 s8, s7, 8
	v_add_f32_e32 v113, v112, v113
	v_cndmask_b32_e32 v112, v190, v191, vcc
	s_lshl_b32 s0, s14, 2
	s_ashr_i32 s9, s8, 31
	s_ashr_i32 s6, s6, 6
	v_lshlrev_b32_e32 v112, 2, v112
	s_ashr_i32 s1, s0, 31
	s_lshl_b64 s[24:25], s[8:9], 5
	s_ashr_i32 s7, s6, 31
	ds_bpermute_b32 v114, v112, v113
	s_add_u32 s8, s24, s6
	s_addc_u32 s9, s25, s7
	s_lshl_b64 s[8:9], s[8:9], 15
	s_add_u32 s22, s10, s8
	v_cmp_lt_i32_e32 vcc, v193, v192
	s_addc_u32 s23, s11, s9
	s_or_b32 s8, s6, 2
	s_waitcnt lgkmcnt(0)
	v_add_f32_e32 v114, v113, v114
	v_cndmask_b32_e32 v113, v190, v193, vcc
	s_ashr_i32 s9, s8, 31
	v_lshlrev_b32_e32 v113, 2, v113
	v_lshlrev_b32_e32 v141, 6, v140
	s_add_u32 s24, s24, s8
	ds_bpermute_b32 v115, v113, v114
	v_and_b32_e32 v143, 0x2000, v141
	v_lshlrev_b32_e32 v141, 5, v140
	s_addc_u32 s25, s25, s9
	v_and_b32_e32 v144, 0x1e0, v141
	s_lshl_b64 s[24:25], s[24:25], 15
	v_or3_b32 v141, v143, v144, v167
	s_add_u32 s24, s10, s24
	v_lshlrev_b32_e32 v141, 1, v141
	s_addc_u32 s25, s11, s25
	v_cvt_pk_bf16_f32 v172, v120, v121
	v_cvt_pk_bf16_f32 v173, v122, v123
	global_store_dwordx4 v141, v[170:173], s[22:23] sc0 sc1
	v_cvt_pk_bf16_f32 v120, v116, v117
	v_cvt_pk_bf16_f32 v121, v118, v119
	v_cvt_pk_bf16_f32 v122, v124, v125
	v_cvt_pk_bf16_f32 v123, v126, v127
	global_store_dwordx4 v141, v[120:123], s[24:25] sc0 sc1
	s_and_saveexec_b64 s[26:27], s[38:39]
	s_cbranch_execz .LBB0_636
	v_ashrrev_i32_e32 v141, 31, v140
	v_lshlrev_b64 v[116:117], 7, v[140:141]
	v_lshl_add_u64 v[116:117], s[18:19], 0, v[116:117]
	v_lshl_add_u64 v[116:117], s[0:1], 2, v[116:117]
	s_lshl_b32 s14, s49, 2
	v_lshl_add_u64 v[116:117], v[116:117], 0, s[14:15]
	s_waitcnt lgkmcnt(0)
	v_add_f32_e32 v114, v114, v115
	global_store_dword v[116:117], v114, off
.LBB0_636:
	s_or_b64 exec, exec, s[26:27]
	v_lshrrev_b32_e32 v114, 3, v162
	v_and_or_b32 v114, v114, 10, s53
	v_lshl_or_b32 v114, v114, 9, v143
	v_or3_b32 v118, v114, v144, v165
	v_cvt_pk_bf16_f32 v114, v80, v81
	s_waitcnt lgkmcnt(0)
	v_cvt_pk_bf16_f32 v115, v82, v83
	v_cvt_pk_bf16_f32 v116, v56, v57
	v_mul_f32_e32 v81, v81, v81
	v_mul_f32_e32 v57, v57, v57
	v_fmac_f32_e32 v81, v80, v80
	v_mul_f32_e32 v80, v83, v83
	v_fmac_f32_e32 v57, v56, v56
	v_mul_f32_e32 v56, v59, v59
	v_fmac_f32_e32 v80, v82, v82
	v_fmac_f32_e32 v56, v58, v58
	v_add_f32_e32 v80, v81, v80
	v_add_f32_e32 v56, v57, v56
	v_add_f32_e32 v56, v80, v56
	v_mul_f32_e32 v57, v73, v73
	v_mul_f32_e32 v80, v75, v75
	v_fmac_f32_e32 v57, v72, v72
	v_fmac_f32_e32 v80, v74, v74
	v_add_f32_e32 v57, v57, v80
	v_mul_f32_e32 v80, v93, v93
	v_mul_f32_e32 v81, v95, v95
	v_fmac_f32_e32 v80, v92, v92
	v_fmac_f32_e32 v81, v94, v94
	v_add_f32_e32 v80, v80, v81
	v_add_f32_e32 v57, v57, v80
	v_add_f32_e32 v56, v56, v57
	ds_bpermute_b32 v57, v112, v56
	v_cvt_pk_bf16_f32 v117, v58, v59
	v_lshlrev_b32_e32 v58, 1, v118
	global_store_dwordx4 v58, v[114:117], s[22:23] sc0 sc1
	v_cvt_pk_bf16_f32 v72, v72, v73
	s_waitcnt lgkmcnt(0)
	v_add_f32_e32 v56, v56, v57
	ds_bpermute_b32 v57, v113, v56
	v_cvt_pk_bf16_f32 v73, v74, v75
	v_cvt_pk_bf16_f32 v74, v92, v93
	v_cvt_pk_bf16_f32 v75, v94, v95
	global_store_dwordx4 v58, v[72:75], s[24:25] sc0 sc1
	s_and_saveexec_b64 s[26:27], s[38:39]
	s_cbranch_execz .LBB0_638
	v_ashrrev_i32_e32 v163, 31, v162
	v_lshlrev_b64 v[58:59], 7, v[162:163]
	v_lshl_add_u64 v[58:59], s[18:19], 0, v[58:59]
	v_lshl_add_u64 v[58:59], s[0:1], 2, v[58:59]
	s_lshl_b32 s14, s49, 2
	v_lshl_add_u64 v[58:59], v[58:59], 0, s[14:15]
	s_waitcnt lgkmcnt(0)
	v_add_f32_e32 v56, v56, v57
	global_store_dword v[58:59], v56, off
; __device__ __forceinline__ unsigned cvt_pk_bf16(float lo, float hi) { unsigned r; asm volatile("v_cvt_pk_bf16_f32 %0, %1, %2" : "=v"(r) : "v"(lo), "v"(hi)); return r; }
;     __device__ __forceinline__ size_t xb_off(int row, int col) const { return ((size_t)(row >> 8) * (ldc >> 6) + (col >> 6)) * (256 * 64) + blk_off(row & 255, col & 63); }
;     __device__ __forceinline__ void operator()(const f32x4 (&acc)[2][2][4][2], const State&, const Unit& u, int wr, int wc, int fr, int fq) const {
;     ...
;             for (int ai = 0; ai < 2; ++ai)
; #pragma unroll
;                 for (int m = 0; m < 4; ++m) { const int row = row0 + ai * HALF + m * 16; const size_t off = (size_t)row * ldc + col0; float ss = 0.f;
; #pragma unroll
;                     for (int bj = 0; bj < 2; ++bj) { const f32x4 v0 = acc[ai][bj][m][0], v1 = acc[ai][bj][m][1];
;                         u32x4 w; w.x = cvt_pk_bf16(v0[0], v0[1]); w.y = cvt_pk_bf16(v0[2], v0[3]); w.z = cvt_pk_bf16(v1[0], v1[1]); w.w = cvt_pk_bf16(v1[2], v1[3]);
;                         *(u32x4*)(xb + xb_off(row, col0 + bj * HALF)) = w;
;                         ss += ((v0[0] * v0[0] + v0[1] * v0[1]) + (v0[2] * v0[2] + v0[3] * v0[3])) + ((v1[0] * v1[0] + v1[1] * v1[1]) + (v1[2] * v1[2] + v1[3] * v1[3])); }
;                     ss += __shfl_xor(ss, 16); ss += __shfl_xor(ss, 32);
;                     if (fq == 0) ssq[(size_t)row * 32 + u.pn * 4 + wc] = ss; }
.LBB0_638:
	s_or_b64 exec, exec, s[26:27]
	v_lshrrev_b32_e32 v56, 3, v160
	v_and_or_b32 v56, v56, 12, s53
	v_lshl_or_b32 v56, v56, 9, v143
	v_mul_f32_e32 v59, v61, v61
	v_or3_b32 v72, v56, v144, v165
	v_cvt_pk_bf16_f32 v56, v60, v61
	v_fmac_f32_e32 v59, v60, v60
	v_mul_f32_e32 v60, v63, v63
	v_fmac_f32_e32 v60, v62, v62
	v_add_f32_e32 v59, v59, v60
	v_mul_f32_e32 v60, v101, v101
	v_mul_f32_e32 v61, v103, v103
	v_fmac_f32_e32 v60, v100, v100
	v_fmac_f32_e32 v61, v102, v102
	v_add_f32_e32 v60, v60, v61
	v_add_f32_e32 v59, v59, v60
	v_mul_f32_e32 v60, v105, v105
	v_mul_f32_e32 v61, v107, v107
	v_fmac_f32_e32 v60, v104, v104
	v_fmac_f32_e32 v61, v106, v106
	s_waitcnt lgkmcnt(0)
	v_cvt_pk_bf16_f32 v57, v62, v63
	v_add_f32_e32 v60, v60, v61
	v_mul_f32_e32 v61, v109, v109
	v_mul_f32_e32 v62, v111, v111
	v_fmac_f32_e32 v61, v108, v108
	v_fmac_f32_e32 v62, v110, v110
	v_add_f32_e32 v61, v61, v62
	v_add_f32_e32 v60, v60, v61
	v_add_f32_e32 v60, v59, v60
	ds_bpermute_b32 v61, v112, v60
	v_lshlrev_b32_e32 v62, 1, v72
	v_cvt_pk_bf16_f32 v58, v100, v101
	v_cvt_pk_bf16_f32 v59, v102, v103
	global_store_dwordx4 v62, v[56:59], s[22:23] sc0 sc1
	s_waitcnt lgkmcnt(0)
	s_nop 0
	v_add_f32_e32 v56, v60, v61
	ds_bpermute_b32 v57, v113, v56
	v_cvt_pk_bf16_f32 v58, v104, v105
	v_cvt_pk_bf16_f32 v59, v106, v107
	v_cvt_pk_bf16_f32 v60, v108, v109
	v_cvt_pk_bf16_f32 v61, v110, v111
	global_store_dwordx4 v62, v[58:61], s[24:25] sc0 sc1
	s_and_saveexec_b64 s[26:27], s[38:39]
	s_cbranch_execz .LBB0_640
	v_ashrrev_i32_e32 v161, 31, v160
	v_lshlrev_b64 v[58:59], 7, v[160:161]
	v_lshl_add_u64 v[58:59], s[18:19], 0, v[58:59]
	v_lshl_add_u64 v[58:59], s[0:1], 2, v[58:59]
	s_lshl_b32 s14, s49, 2
	v_lshl_add_u64 v[58:59], v[58:59], 0, s[14:15]
	s_waitcnt lgkmcnt(0)
	v_add_f32_e32 v56, v56, v57
	global_store_dword v[58:59], v56, off
.LBB0_640:
	s_or_b64 exec, exec, s[26:27]
	v_lshrrev_b32_e32 v56, 3, v142
	v_and_or_b32 v56, v56, 14, s53
	v_lshl_or_b32 v56, v56, 9, v143
	v_or3_b32 v60, v56, v144, v165
	v_cvt_pk_bf16_f32 v56, v68, v69
	s_waitcnt lgkmcnt(0)
	v_cvt_pk_bf16_f32 v57, v70, v71
	v_cvt_pk_bf16_f32 v58, v48, v49
	v_mul_f32_e32 v49, v49, v49
	v_mul_f32_e32 v59, v69, v69
	v_mul_f32_e32 v61, v71, v71
	v_fmac_f32_e32 v49, v48, v48
	v_mul_f32_e32 v48, v51, v51
	v_fmac_f32_e32 v59, v68, v68
	v_fmac_f32_e32 v61, v70, v70
	v_fmac_f32_e32 v48, v50, v50
	v_add_f32_e32 v59, v59, v61
	v_add_f32_e32 v48, v49, v48
	v_add_f32_e32 v48, v59, v48
	v_mul_f32_e32 v49, v65, v65
	v_mul_f32_e32 v59, v67, v67
	v_fmac_f32_e32 v49, v64, v64
	v_fmac_f32_e32 v59, v66, v66
	v_add_f32_e32 v49, v49, v59
	v_mul_f32_e32 v59, v77, v77
	v_mul_f32_e32 v61, v79, v79
	v_fmac_f32_e32 v59, v76, v76
	v_fmac_f32_e32 v61, v78, v78
	v_add_f32_e32 v59, v59, v61
	v_add_f32_e32 v49, v49, v59
	v_add_f32_e32 v48, v48, v49
	ds_bpermute_b32 v49, v112, v48
	v_cvt_pk_bf16_f32 v59, v50, v51
	v_lshlrev_b32_e32 v50, 1, v60
	global_store_dwordx4 v50, v[56:59], s[22:23] sc0 sc1
	s_waitcnt lgkmcnt(0)
	v_add_f32_e32 v48, v48, v49
	ds_bpermute_b32 v49, v113, v48
	v_cvt_pk_bf16_f32 v56, v64, v65
	v_cvt_pk_bf16_f32 v57, v66, v67
	v_cvt_pk_bf16_f32 v58, v76, v77
	v_cvt_pk_bf16_f32 v59, v78, v79
	global_store_dwordx4 v50, v[56:59], s[24:25] sc0 sc1
	s_and_saveexec_b64 s[22:23], s[38:39]
	s_cbranch_execz .LBB0_642
	v_ashrrev_i32_e32 v143, 31, v142
	v_lshlrev_b64 v[50:51], 7, v[142:143]
	v_lshl_add_u64 v[50:51], s[18:19], 0, v[50:51]
	v_lshl_add_u64 v[50:51], s[0:1], 2, v[50:51]
	s_lshl_b32 s14, s49, 2
	v_lshl_add_u64 v[50:51], v[50:51], 0, s[14:15]
	s_waitcnt lgkmcnt(0)
	v_add_f32_e32 v48, v48, v49
	global_store_dword v[50:51], v48, off
.LBB0_642:
	s_or_b64 exec, exec, s[22:23]
	v_add_u32_e32 v50, 0x80, v140
	v_lshlrev_b32_e32 v51, 6, v50
	v_lshlrev_b32_e32 v56, 5, v50
	v_ashrrev_i32_e32 v48, 8, v50
	v_and_b32_e32 v51, 0x2000, v51
	v_and_b32_e32 v56, 0x1e0, v56
	s_waitcnt lgkmcnt(0)
	v_ashrrev_i32_e32 v49, 31, v48
	v_or3_b32 v51, v51, v56, v167
	v_cvt_pk_bf16_f32 v56, v40, v41
	v_mul_f32_e32 v41, v41, v41
	v_lshlrev_b64 v[60:61], 5, v[48:49]
	v_fmac_f32_e32 v41, v40, v40
	v_mul_f32_e32 v40, v43, v43
	v_lshl_add_u64 v[48:49], v[60:61], 0, s[6:7]
	v_fmac_f32_e32 v40, v42, v42
	v_cvt_pk_bf16_f32 v57, v42, v43
	v_lshlrev_b64 v[48:49], 15, v[48:49]
	v_add_f32_e32 v40, v41, v40
	v_mul_f32_e32 v41, v45, v45
	v_mul_f32_e32 v42, v47, v47
	v_lshl_add_u64 v[48:49], s[10:11], 0, v[48:49]
	v_lshlrev_b32_e32 v144, 1, v51
	v_fmac_f32_e32 v41, v44, v44
	v_fmac_f32_e32 v42, v46, v46
	v_lshl_add_u64 v[62:63], v[48:49], 0, v[144:145]
	v_add_f32_e32 v41, v41, v42
	v_cvt_pk_bf16_f32 v58, v44, v45
	v_cvt_pk_bf16_f32 v59, v46, v47
	global_store_dwordx4 v[62:63], v[56:59], off sc0 sc1
	v_add_f32_e32 v41, v40, v41
	v_cvt_pk_bf16_f32 v40, v36, v37
	v_mul_f32_e32 v37, v37, v37
	v_fmac_f32_e32 v37, v36, v36
	v_mul_f32_e32 v36, v39, v39
	v_fmac_f32_e32 v36, v38, v38
	v_add_f32_e32 v36, v37, v36
	v_mul_f32_e32 v37, v53, v53
	v_mul_f32_e32 v42, v55, v55
	v_fmac_f32_e32 v37, v52, v52
	v_fmac_f32_e32 v42, v54, v54
	v_add_f32_e32 v37, v37, v42
	v_add_f32_e32 v36, v36, v37
	v_add_f32_e32 v44, v41, v36
	ds_bpermute_b32 v45, v112, v44
	v_cvt_pk_bf16_f32 v41, v38, v39
	v_lshl_add_u64 v[36:37], v[60:61], 0, s[8:9]
	v_lshlrev_b64 v[36:37], 15, v[36:37]
	v_lshl_add_u64 v[36:37], s[10:11], 0, v[36:37]
	s_waitcnt lgkmcnt(0)
	v_add_f32_e32 v38, v44, v45
	ds_bpermute_b32 v39, v113, v38
	v_lshl_add_u64 v[44:45], v[36:37], 0, v[144:145]
	v_cvt_pk_bf16_f32 v42, v52, v53
	v_cvt_pk_bf16_f32 v43, v54, v55
	global_store_dwordx4 v[44:45], v[40:43], off sc0 sc1
	s_and_saveexec_b64 s[6:7], s[38:39]
	s_cbranch_execz .LBB0_644
	v_ashrrev_i32_e32 v51, 31, v50
	v_lshlrev_b64 v[40:41], 7, v[50:51]
	v_lshl_add_u64 v[40:41], s[18:19], 0, v[40:41]
	v_lshl_add_u64 v[40:41], s[0:1], 2, v[40:41]
	s_lshl_b32 s14, s49, 2
	v_lshl_add_u64 v[40:41], v[40:41], 0, s[14:15]
	s_waitcnt lgkmcnt(0)
	v_add_f32_e32 v38, v38, v39
	global_store_dword v[40:41], v38, off
; __device__ __forceinline__ unsigned cvt_pk_bf16(float lo, float hi) { unsigned r; asm volatile("v_cvt_pk_bf16_f32 %0, %1, %2" : "=v"(r) : "v"(lo), "v"(hi)); return r; }
;     __device__ __forceinline__ size_t xb_off(int row, int col) const { return ((size_t)(row >> 8) * (ldc >> 6) + (col >> 6)) * (256 * 64) + blk_off(row & 255, col & 63); }
;     __device__ __forceinline__ void operator()(const f32x4 (&acc)[2][2][4][2], const State&, const Unit& u, int wr, int wc, int fr, int fq) const {
;     ...
;             for (int ai = 0; ai < 2; ++ai)
; #pragma unroll
;                 for (int m = 0; m < 4; ++m) { const int row = row0 + ai * HALF + m * 16; const size_t off = (size_t)row * ldc + col0; float ss = 0.f;
; #pragma unroll
;                     for (int bj = 0; bj < 2; ++bj) { const f32x4 v0 = acc[ai][bj][m][0], v1 = acc[ai][bj][m][1];
;                         u32x4 w; w.x = cvt_pk_bf16(v0[0], v0[1]); w.y = cvt_pk_bf16(v0[2], v0[3]); w.z = cvt_pk_bf16(v1[0], v1[1]); w.w = cvt_pk_bf16(v1[2], v1[3]);
;                         *(u32x4*)(xb + xb_off(row, col0 + bj * HALF)) = w;
;                         ss += ((v0[0] * v0[0] + v0[1] * v0[1]) + (v0[2] * v0[2] + v0[3] * v0[3])) + ((v1[0] * v1[0] + v1[1] * v1[1]) + (v1[2] * v1[2] + v1[3] * v1[3])); }
;                     ss += __shfl_xor(ss, 16); ss += __shfl_xor(ss, 32);
;                     if (fq == 0) ssq[(size_t)row * 32 + u.pn * 4 + wc] = ss; }
.LBB0_644:
	s_or_b64 exec, exec, s[6:7]
	v_add_u32_e32 v38, 0x90, v140
	s_waitcnt lgkmcnt(0)
	v_lshlrev_b32_e32 v39, 6, v38
	v_lshrrev_b32_e32 v40, 3, v38
	v_and_b32_e32 v39, 0x2000, v39
	v_and_or_b32 v40, v40, 10, s53
	v_lshl_or_b32 v39, v40, 9, v39
	v_lshlrev_b32_e32 v40, 5, v38
	v_and_b32_e32 v40, 0x1e0, v40
	v_or3_b32 v39, v39, v40, v165
	v_cvt_pk_bf16_f32 v40, v16, v17
	v_mul_f32_e32 v17, v17, v17
	v_fmac_f32_e32 v17, v16, v16
	v_mul_f32_e32 v16, v19, v19
	v_fmac_f32_e32 v16, v18, v18
	v_cvt_pk_bf16_f32 v41, v18, v19
	v_add_f32_e32 v16, v17, v16
	v_mul_f32_e32 v17, v89, v89
	v_mul_f32_e32 v18, v91, v91
	v_fmac_f32_e32 v17, v88, v88
	v_fmac_f32_e32 v18, v90, v90
	v_add_f32_e32 v17, v17, v18
	v_add_f32_e32 v16, v16, v17
	v_mul_f32_e32 v17, v85, v85
	v_mul_f32_e32 v18, v87, v87
	v_fmac_f32_e32 v17, v84, v84
	v_fmac_f32_e32 v18, v86, v86
	v_add_f32_e32 v17, v17, v18
	v_mul_f32_e32 v18, v97, v97
	v_mul_f32_e32 v19, v99, v99
	v_fmac_f32_e32 v18, v96, v96
	v_fmac_f32_e32 v19, v98, v98
	v_add_f32_e32 v18, v18, v19
	v_add_f32_e32 v17, v17, v18
	v_add_f32_e32 v18, v16, v17
	ds_bpermute_b32 v19, v112, v18
	v_lshlrev_b32_e32 v144, 1, v39
	v_lshl_add_u64 v[16:17], v[48:49], 0, v[144:145]
	v_cvt_pk_bf16_f32 v42, v88, v89
	v_cvt_pk_bf16_f32 v43, v90, v91
	global_store_dwordx4 v[16:17], v[40:43], off sc0 sc1
	s_waitcnt lgkmcnt(0)
	v_add_f32_e32 v16, v18, v19
	ds_bpermute_b32 v17, v113, v16
	v_lshl_add_u64 v[18:19], v[36:37], 0, v[144:145]
	v_cvt_pk_bf16_f32 v40, v84, v85
	v_cvt_pk_bf16_f32 v41, v86, v87
	v_cvt_pk_bf16_f32 v42, v96, v97
	v_cvt_pk_bf16_f32 v43, v98, v99
	global_store_dwordx4 v[18:19], v[40:43], off sc0 sc1
	s_and_saveexec_b64 s[6:7], s[38:39]
	s_cbranch_execz .LBB0_646
	v_ashrrev_i32_e32 v39, 31, v38
	v_lshlrev_b64 v[18:19], 7, v[38:39]
	v_lshl_add_u64 v[18:19], s[18:19], 0, v[18:19]
	v_lshl_add_u64 v[18:19], s[0:1], 2, v[18:19]
	s_lshl_b32 s14, s49, 2
	v_lshl_add_u64 v[18:19], v[18:19], 0, s[14:15]
	s_waitcnt lgkmcnt(0)
	v_add_f32_e32 v16, v16, v17
	global_store_dword v[18:19], v16, off
.LBB0_646:
	s_or_b64 exec, exec, s[6:7]
	v_add_u32_e32 v16, 0xa0, v140
	s_waitcnt lgkmcnt(0)
	v_lshlrev_b32_e32 v17, 6, v16
	v_lshrrev_b32_e32 v18, 3, v16
	v_and_b32_e32 v17, 0x2000, v17
	v_and_or_b32 v18, v18, 12, s53
	v_lshl_or_b32 v17, v18, 9, v17
	v_lshlrev_b32_e32 v18, 5, v16
	v_and_b32_e32 v18, 0x1e0, v18
	v_or3_b32 v17, v17, v18, v165
	v_lshlrev_b32_e32 v144, 1, v17
	v_mul_f32_e32 v17, v25, v25
	v_mul_f32_e32 v18, v27, v27
	v_fmac_f32_e32 v17, v24, v24
	v_fmac_f32_e32 v18, v26, v26
	v_add_f32_e32 v17, v17, v18
	v_mul_f32_e32 v18, v29, v29
	v_mul_f32_e32 v19, v31, v31
	v_fmac_f32_e32 v18, v28, v28
	v_fmac_f32_e32 v19, v30, v30
	v_add_f32_e32 v18, v18, v19
	v_add_f32_e32 v17, v17, v18
	v_mul_f32_e32 v18, v21, v21
	v_mul_f32_e32 v19, v23, v23
	v_fmac_f32_e32 v18, v20, v20
	v_fmac_f32_e32 v19, v22, v22
	v_cvt_pk_bf16_f32 v38, v24, v25
	v_add_f32_e32 v18, v18, v19
	v_mul_f32_e32 v19, v33, v33
	v_mul_f32_e32 v24, v35, v35
	v_fmac_f32_e32 v19, v32, v32
	v_fmac_f32_e32 v24, v34, v34
	v_add_f32_e32 v19, v19, v24
	v_add_f32_e32 v18, v18, v19
	v_add_f32_e32 v17, v17, v18
	ds_bpermute_b32 v24, v112, v17
	v_lshl_add_u64 v[18:19], v[48:49], 0, v[144:145]
	v_cvt_pk_bf16_f32 v39, v26, v27
	v_cvt_pk_bf16_f32 v40, v28, v29
	v_cvt_pk_bf16_f32 v41, v30, v31
	global_store_dwordx4 v[18:19], v[38:41], off sc0 sc1
	s_waitcnt lgkmcnt(0)
	v_add_f32_e32 v18, v17, v24
	ds_bpermute_b32 v19, v113, v18
	v_lshl_add_u64 v[24:25], v[36:37], 0, v[144:145]
	v_cvt_pk_bf16_f32 v20, v20, v21
	v_cvt_pk_bf16_f32 v21, v22, v23
	v_cvt_pk_bf16_f32 v22, v32, v33
	v_cvt_pk_bf16_f32 v23, v34, v35
	global_store_dwordx4 v[24:25], v[20:23], off sc0 sc1
	s_and_saveexec_b64 s[6:7], s[38:39]
	s_cbranch_execz .LBB0_648
	v_ashrrev_i32_e32 v17, 31, v16
	v_lshlrev_b64 v[16:17], 7, v[16:17]
	v_lshl_add_u64 v[16:17], s[18:19], 0, v[16:17]
	v_lshl_add_u64 v[16:17], s[0:1], 2, v[16:17]
	s_lshl_b32 s14, s49, 2
	v_lshl_add_u64 v[16:17], v[16:17], 0, s[14:15]
	s_waitcnt lgkmcnt(0)
	v_add_f32_e32 v18, v18, v19
	global_store_dword v[16:17], v18, off
.LBB0_648:
	s_or_b64 exec, exec, s[6:7]
	v_add_u32_e32 v16, 0xb0, v140
	v_lshlrev_b32_e32 v17, 6, v16
	v_lshrrev_b32_e32 v18, 3, v16
	v_and_b32_e32 v17, 0x2000, v17
	v_and_or_b32 v18, v18, 14, s53
	v_lshl_or_b32 v17, v18, 9, v17
	v_lshlrev_b32_e32 v18, 5, v16
	v_and_b32_e32 v18, 0x1e0, v18
	v_or3_b32 v17, v17, v18, v165
	v_cvt_pk_bf16_f32 v18, v4, v5
	v_mul_f32_e32 v5, v5, v5
	v_fmac_f32_e32 v5, v4, v4
	v_mul_f32_e32 v4, v7, v7
	v_fmac_f32_e32 v4, v6, v6
	s_waitcnt lgkmcnt(0)
	v_cvt_pk_bf16_f32 v19, v6, v7
	v_add_f32_e32 v4, v5, v4
	v_mul_f32_e32 v5, v9, v9
	v_mul_f32_e32 v6, v11, v11
	v_fmac_f32_e32 v5, v8, v8
	v_fmac_f32_e32 v6, v10, v10
	v_add_f32_e32 v5, v5, v6
	v_add_f32_e32 v4, v4, v5
	v_mul_f32_e32 v5, v1, v1
	v_mul_f32_e32 v6, v3, v3
	v_fmac_f32_e32 v5, v0, v0
	v_fmac_f32_e32 v6, v2, v2
	v_add_f32_e32 v5, v5, v6
	v_mul_f32_e32 v6, v13, v13
	v_mul_f32_e32 v7, v15, v15
	v_fmac_f32_e32 v6, v12, v12
	v_fmac_f32_e32 v7, v14, v14
	v_add_f32_e32 v6, v6, v7
	v_add_f32_e32 v5, v5, v6
	v_add_f32_e32 v6, v4, v5
	ds_bpermute_b32 v7, v112, v6
	v_lshlrev_b32_e32 v144, 1, v17
	v_lshl_add_u64 v[4:5], v[48:49], 0, v[144:145]
	v_cvt_pk_bf16_f32 v20, v8, v9
	v_cvt_pk_bf16_f32 v21, v10, v11
	global_store_dwordx4 v[4:5], v[18:21], off sc0 sc1
	v_cvt_pk_bf16_f32 v4, v0, v1
	s_waitcnt lgkmcnt(0)
	v_add_f32_e32 v0, v6, v7
	ds_bpermute_b32 v1, v113, v0
	v_cvt_pk_bf16_f32 v5, v2, v3
	v_lshl_add_u64 v[2:3], v[36:37], 0, v[144:145]
	v_cvt_pk_bf16_f32 v6, v12, v13
	v_cvt_pk_bf16_f32 v7, v14, v15
	global_store_dwordx4 v[2:3], v[4:7], off sc0 sc1
	s_and_saveexec_b64 s[6:7], s[38:39]
	s_cbranch_execz .LBB0_650
	v_ashrrev_i32_e32 v17, 31, v16
	v_lshlrev_b64 v[2:3], 7, v[16:17]
	v_lshl_add_u64 v[2:3], s[18:19], 0, v[2:3]
	v_lshl_add_u64 v[2:3], s[0:1], 2, v[2:3]
	s_lshl_b32 s14, s49, 2
	v_lshl_add_u64 v[2:3], v[2:3], 0, s[14:15]
	s_waitcnt lgkmcnt(0)
	v_add_f32_e32 v0, v0, v1
	global_store_dword v[2:3], v0, off
